# v12 with the s_setprio flips of the bf16 K-loops removed (A/B of the priority flips on the chained order)
# speedup vs baseline: 1.0046x; 1.0046x over previous
.LBB0_642:
	ds_read_b128 v[148:151], v139
	ds_read_b128 v[152:155], v139 offset:1024
	ds_read_b128 v[156:159], v139 offset:2048
	ds_read_b128 v[160:163], v139 offset:3072
	ds_read_b128 v[164:167], v140
	ds_read_b128 v[168:171], v140 offset:1024
	ds_read_b128 v[172:175], v140 offset:2048
	ds_read_b128 v[176:179], v140 offset:3072
	s_add_i32 s18, s71, 0xffe80080
	s_cmp_eq_u32 s58, s73
	s_cselect_b32 s74, s69, s18
	s_cselect_b32 s76, s70, s72
	s_or_b32 s75, s74, 0x80
	s_add_i32 s18, s71, 0xfff80000
	s_mov_b32 m0, s59
	ds_read_b128 v[180:183], v141
	ds_read_b128 v[184:187], v141 offset:1024
	ds_read_b128 v[188:191], v141 offset:2048
	ds_read_b128 v[192:195], v141 offset:3072
	ds_read_b128 v[196:199], v141 offset:4096
	ds_read_b128 v[200:203], v141 offset:5120
	ds_read_b128 v[204:207], v141 offset:6144
	ds_read_b128 v[208:211], v141 offset:7168
	buffer_load_dwordx4 v137, s[12:15], s18 offen lds
	s_mov_b32 m0, s60
	s_nop 0
	buffer_load_dwordx4 v137, s[12:15], s71 offen lds
	s_waitcnt vmcnt(8)
	s_waitcnt lgkmcnt(0)
	v_mfma_f32_16x16x32_bf16 v[118:121], v[148:151], v[180:183], v[118:121]
	s_barrier
	v_mfma_f32_16x16x32_bf16 v[118:121], v[152:155], v[184:187], v[118:121]
	v_mfma_f32_16x16x32_bf16 v[114:117], v[156:159], v[180:183], v[114:117]
	v_mfma_f32_16x16x32_bf16 v[114:117], v[160:163], v[184:187], v[114:117]
	v_mfma_f32_16x16x32_bf16 v[126:129], v[164:167], v[180:183], v[126:129]
	v_mfma_f32_16x16x32_bf16 v[126:129], v[168:171], v[184:187], v[126:129]
	v_mfma_f32_16x16x32_bf16 v[122:125], v[172:175], v[180:183], v[122:125]
	v_mfma_f32_16x16x32_bf16 v[122:125], v[176:179], v[184:187], v[122:125]
	v_mfma_f32_16x16x32_bf16 v[98:101], v[172:175], v[188:191], v[98:101]
	v_mfma_f32_16x16x32_bf16 v[98:101], v[176:179], v[192:195], v[98:101]
	v_mfma_f32_16x16x32_bf16 v[106:109], v[164:167], v[188:191], v[106:109]
	v_mfma_f32_16x16x32_bf16 v[106:109], v[168:171], v[192:195], v[106:109]
	v_mfma_f32_16x16x32_bf16 v[102:105], v[156:159], v[188:191], v[102:105]
	v_mfma_f32_16x16x32_bf16 v[102:105], v[160:163], v[192:195], v[102:105]
	v_mfma_f32_16x16x32_bf16 v[110:113], v[148:151], v[188:191], v[110:113]
	v_mfma_f32_16x16x32_bf16 v[110:113], v[152:155], v[192:195], v[110:113]
	v_mfma_f32_16x16x32_bf16 v[94:97], v[148:151], v[196:199], v[94:97]
	v_mfma_f32_16x16x32_bf16 v[94:97], v[152:155], v[200:203], v[94:97]
	v_mfma_f32_16x16x32_bf16 v[86:89], v[156:159], v[196:199], v[86:89]
	v_mfma_f32_16x16x32_bf16 v[86:89], v[160:163], v[200:203], v[86:89]
	v_mfma_f32_16x16x32_bf16 v[90:93], v[164:167], v[196:199], v[90:93]
	v_mfma_f32_16x16x32_bf16 v[90:93], v[168:171], v[200:203], v[90:93]
	v_mfma_f32_16x16x32_bf16 v[82:85], v[172:175], v[196:199], v[82:85]
	v_mfma_f32_16x16x32_bf16 v[82:85], v[176:179], v[200:203], v[82:85]
	v_mfma_f32_16x16x32_bf16 v[70:73], v[172:175], v[204:207], v[70:73]
	v_mfma_f32_16x16x32_bf16 v[70:73], v[176:179], v[208:211], v[70:73]
	v_mfma_f32_16x16x32_bf16 v[74:77], v[164:167], v[204:207], v[74:77]
	v_mfma_f32_16x16x32_bf16 v[74:77], v[168:171], v[208:211], v[74:77]
	v_mfma_f32_16x16x32_bf16 v[66:69], v[156:159], v[204:207], v[66:69]
	v_mfma_f32_16x16x32_bf16 v[66:69], v[160:163], v[208:211], v[66:69]
	v_mfma_f32_16x16x32_bf16 v[78:81], v[148:151], v[204:207], v[78:81]
	v_mfma_f32_16x16x32_bf16 v[78:81], v[152:155], v[208:211], v[78:81]
	s_barrier
	s_mov_b32 m0, s30
	s_mov_b32 s18, s14
	s_mov_b32 s19, s15
	ds_read_b128 v[180:183], v141 offset:16384
	ds_read_b128 v[184:187], v141 offset:17408
	ds_read_b128 v[188:191], v141 offset:18432
	ds_read_b128 v[192:195], v141 offset:19456
	ds_read_b128 v[196:199], v141 offset:20480
	ds_read_b128 v[200:203], v141 offset:21504
	ds_read_b128 v[204:207], v141 offset:22528
	ds_read_b128 v[208:211], v141 offset:23552
	buffer_load_dwordx4 v138, s[16:19], s76 offen lds
	s_add_i32 s77, s76, 0x80000
	s_mov_b32 m0, s31
	s_nop 0
	buffer_load_dwordx4 v138, s[16:19], s77 offen lds
	s_add_i32 s77, s76, 0x100000
	s_mov_b32 m0, s44
	s_nop 0
	buffer_load_dwordx4 v138, s[16:19], s77 offen lds
	s_add_i32 s77, s76, 0x180000
	s_mov_b32 m0, s45
	s_nop 0
	buffer_load_dwordx4 v138, s[16:19], s77 offen lds
	s_mov_b32 m0, s27
	s_add_i32 s77, s74, 0x80000
	buffer_load_dwordx4 v137, s[12:15], s74 offen lds
	s_mov_b32 m0, s46
	s_nop 0
	buffer_load_dwordx4 v137, s[12:15], s77 offen lds
	s_waitcnt vmcnt(8)
	s_waitcnt lgkmcnt(0)
	v_mfma_f32_16x16x32_bf16 v[62:65], v[148:151], v[180:183], v[62:65]
	s_barrier
	v_mfma_f32_16x16x32_bf16 v[62:65], v[152:155], v[184:187], v[62:65]
	v_mfma_f32_16x16x32_bf16 v[54:57], v[156:159], v[180:183], v[54:57]
	v_mfma_f32_16x16x32_bf16 v[54:57], v[160:163], v[184:187], v[54:57]
	v_mfma_f32_16x16x32_bf16 v[58:61], v[164:167], v[180:183], v[58:61]
	v_mfma_f32_16x16x32_bf16 v[58:61], v[168:171], v[184:187], v[58:61]
	v_mfma_f32_16x16x32_bf16 v[50:53], v[172:175], v[180:183], v[50:53]
	v_mfma_f32_16x16x32_bf16 v[50:53], v[176:179], v[184:187], v[50:53]
	v_mfma_f32_16x16x32_bf16 v[34:37], v[172:175], v[188:191], v[34:37]
	v_mfma_f32_16x16x32_bf16 v[34:37], v[176:179], v[192:195], v[34:37]
	v_mfma_f32_16x16x32_bf16 v[42:45], v[164:167], v[188:191], v[42:45]
	v_mfma_f32_16x16x32_bf16 v[42:45], v[168:171], v[192:195], v[42:45]
	v_mfma_f32_16x16x32_bf16 v[38:41], v[156:159], v[188:191], v[38:41]
	v_mfma_f32_16x16x32_bf16 v[38:41], v[160:163], v[192:195], v[38:41]
	v_mfma_f32_16x16x32_bf16 v[46:49], v[148:151], v[188:191], v[46:49]
	v_mfma_f32_16x16x32_bf16 v[46:49], v[152:155], v[192:195], v[46:49]
	v_mfma_f32_16x16x32_bf16 v[30:33], v[148:151], v[196:199], v[30:33]
	v_mfma_f32_16x16x32_bf16 v[30:33], v[152:155], v[200:203], v[30:33]
	v_mfma_f32_16x16x32_bf16 v[22:25], v[156:159], v[196:199], v[22:25]
	v_mfma_f32_16x16x32_bf16 v[22:25], v[160:163], v[200:203], v[22:25]
	v_mfma_f32_16x16x32_bf16 v[26:29], v[164:167], v[196:199], v[26:29]
	v_mfma_f32_16x16x32_bf16 v[26:29], v[168:171], v[200:203], v[26:29]
	v_mfma_f32_16x16x32_bf16 v[18:21], v[172:175], v[196:199], v[18:21]
	v_mfma_f32_16x16x32_bf16 v[18:21], v[176:179], v[200:203], v[18:21]
	v_mfma_f32_16x16x32_bf16 v[2:5], v[172:175], v[204:207], v[2:5]
	v_mfma_f32_16x16x32_bf16 v[2:5], v[176:179], v[208:211], v[2:5]
	v_mfma_f32_16x16x32_bf16 v[10:13], v[164:167], v[204:207], v[10:13]
	v_mfma_f32_16x16x32_bf16 v[10:13], v[168:171], v[208:211], v[10:13]
	v_mfma_f32_16x16x32_bf16 v[6:9], v[156:159], v[204:207], v[6:9]
	v_mfma_f32_16x16x32_bf16 v[6:9], v[160:163], v[208:211], v[6:9]
	v_mfma_f32_16x16x32_bf16 v[14:17], v[148:151], v[204:207], v[14:17]
	v_mfma_f32_16x16x32_bf16 v[14:17], v[152:155], v[208:211], v[14:17]
	s_barrier
	ds_read_b128 v[148:151], v142
	ds_read_b128 v[152:155], v142 offset:1024
	ds_read_b128 v[156:159], v142 offset:2048
	ds_read_b128 v[160:163], v142 offset:3072
	ds_read_b128 v[164:167], v143
	ds_read_b128 v[168:171], v143 offset:1024
	ds_read_b128 v[172:175], v143 offset:2048
	ds_read_b128 v[176:179], v143 offset:3072
	s_mov_b32 m0, s47
	s_add_i32 s77, s74, 0x100000
	ds_read_b128 v[180:183], v141 offset:32768
	ds_read_b128 v[184:187], v141 offset:33792
	ds_read_b128 v[188:191], v141 offset:34816
	ds_read_b128 v[192:195], v141 offset:35840
	ds_read_b128 v[196:199], v141 offset:36864
	ds_read_b128 v[200:203], v141 offset:37888
	ds_read_b128 v[204:207], v141 offset:38912
	ds_read_b128 v[208:211], v141 offset:39936
	buffer_load_dwordx4 v137, s[12:15], s77 offen lds
	s_add_i32 s77, s74, 0x180000
	s_mov_b32 m0, s48
	s_nop 0
	buffer_load_dwordx4 v137, s[12:15], s77 offen lds
	s_waitcnt vmcnt(8)
	s_waitcnt lgkmcnt(0)
	v_mfma_f32_16x16x32_bf16 v[118:121], v[148:151], v[180:183], v[118:121]
	s_barrier
	v_mfma_f32_16x16x32_bf16 v[118:121], v[152:155], v[184:187], v[118:121]
	v_mfma_f32_16x16x32_bf16 v[114:117], v[156:159], v[180:183], v[114:117]
	v_mfma_f32_16x16x32_bf16 v[114:117], v[160:163], v[184:187], v[114:117]
	v_mfma_f32_16x16x32_bf16 v[126:129], v[164:167], v[180:183], v[126:129]
	v_mfma_f32_16x16x32_bf16 v[126:129], v[168:171], v[184:187], v[126:129]
	v_mfma_f32_16x16x32_bf16 v[122:125], v[172:175], v[180:183], v[122:125]
	v_mfma_f32_16x16x32_bf16 v[122:125], v[176:179], v[184:187], v[122:125]
	v_mfma_f32_16x16x32_bf16 v[98:101], v[172:175], v[188:191], v[98:101]
	v_mfma_f32_16x16x32_bf16 v[98:101], v[176:179], v[192:195], v[98:101]
	v_mfma_f32_16x16x32_bf16 v[106:109], v[164:167], v[188:191], v[106:109]
	v_mfma_f32_16x16x32_bf16 v[106:109], v[168:171], v[192:195], v[106:109]
	v_mfma_f32_16x16x32_bf16 v[102:105], v[156:159], v[188:191], v[102:105]
	v_mfma_f32_16x16x32_bf16 v[102:105], v[160:163], v[192:195], v[102:105]
	v_mfma_f32_16x16x32_bf16 v[110:113], v[148:151], v[188:191], v[110:113]
	v_mfma_f32_16x16x32_bf16 v[110:113], v[152:155], v[192:195], v[110:113]
	v_mfma_f32_16x16x32_bf16 v[94:97], v[148:151], v[196:199], v[94:97]
	v_mfma_f32_16x16x32_bf16 v[94:97], v[152:155], v[200:203], v[94:97]
	v_mfma_f32_16x16x32_bf16 v[86:89], v[156:159], v[196:199], v[86:89]
	v_mfma_f32_16x16x32_bf16 v[86:89], v[160:163], v[200:203], v[86:89]
	v_mfma_f32_16x16x32_bf16 v[90:93], v[164:167], v[196:199], v[90:93]
	v_mfma_f32_16x16x32_bf16 v[90:93], v[168:171], v[200:203], v[90:93]
	v_mfma_f32_16x16x32_bf16 v[82:85], v[172:175], v[196:199], v[82:85]
	v_mfma_f32_16x16x32_bf16 v[82:85], v[176:179], v[200:203], v[82:85]
	v_mfma_f32_16x16x32_bf16 v[70:73], v[172:175], v[204:207], v[70:73]
	v_mfma_f32_16x16x32_bf16 v[70:73], v[176:179], v[208:211], v[70:73]
	v_mfma_f32_16x16x32_bf16 v[74:77], v[164:167], v[204:207], v[74:77]
	v_mfma_f32_16x16x32_bf16 v[74:77], v[168:171], v[208:211], v[74:77]
	v_mfma_f32_16x16x32_bf16 v[66:69], v[156:159], v[204:207], v[66:69]
	v_mfma_f32_16x16x32_bf16 v[66:69], v[160:163], v[208:211], v[66:69]
	v_mfma_f32_16x16x32_bf16 v[78:81], v[148:151], v[204:207], v[78:81]
	v_mfma_f32_16x16x32_bf16 v[78:81], v[152:155], v[208:211], v[78:81]
	s_barrier
	s_mov_b32 m0, s50
	s_or_b32 s77, s76, 0x80
	ds_read_b128 v[180:183], v141 offset:49152
	ds_read_b128 v[184:187], v141 offset:50176
	ds_read_b128 v[188:191], v141 offset:51200
	ds_read_b128 v[192:195], v141 offset:52224
	ds_read_b128 v[196:199], v141 offset:53248
	ds_read_b128 v[200:203], v141 offset:54272
	ds_read_b128 v[204:207], v141 offset:55296
	ds_read_b128 v[208:211], v141 offset:56320
	buffer_load_dwordx4 v138, s[16:19], s77 offen lds
	s_add_i32 s77, s76, 0x80080
	s_mov_b32 m0, s51
	s_add_i32 s74, s74, 0x80080
	buffer_load_dwordx4 v138, s[16:19], s77 offen lds
	s_add_i32 s77, s76, 0x100080
	s_mov_b32 m0, s54
	s_add_i32 s76, s76, 0x180080
	buffer_load_dwordx4 v138, s[16:19], s77 offen lds
	s_mov_b32 m0, s55
	s_nop 0
	buffer_load_dwordx4 v138, s[16:19], s76 offen lds
	s_mov_b32 m0, s52
	s_nop 0
	buffer_load_dwordx4 v137, s[12:15], s75 offen lds
	s_mov_b32 m0, s53
	s_nop 0
	buffer_load_dwordx4 v137, s[12:15], s74 offen lds
	s_waitcnt vmcnt(8)
	s_waitcnt lgkmcnt(0)
	v_mfma_f32_16x16x32_bf16 v[62:65], v[148:151], v[180:183], v[62:65]
	s_barrier
	v_mfma_f32_16x16x32_bf16 v[62:65], v[152:155], v[184:187], v[62:65]
	v_mfma_f32_16x16x32_bf16 v[54:57], v[156:159], v[180:183], v[54:57]
	v_mfma_f32_16x16x32_bf16 v[54:57], v[160:163], v[184:187], v[54:57]
	v_mfma_f32_16x16x32_bf16 v[58:61], v[164:167], v[180:183], v[58:61]
	v_mfma_f32_16x16x32_bf16 v[58:61], v[168:171], v[184:187], v[58:61]
	v_mfma_f32_16x16x32_bf16 v[50:53], v[172:175], v[180:183], v[50:53]
	v_mfma_f32_16x16x32_bf16 v[50:53], v[176:179], v[184:187], v[50:53]
	v_mfma_f32_16x16x32_bf16 v[34:37], v[172:175], v[188:191], v[34:37]
	v_mfma_f32_16x16x32_bf16 v[34:37], v[176:179], v[192:195], v[34:37]
	v_mfma_f32_16x16x32_bf16 v[42:45], v[164:167], v[188:191], v[42:45]
	v_mfma_f32_16x16x32_bf16 v[42:45], v[168:171], v[192:195], v[42:45]
	v_mfma_f32_16x16x32_bf16 v[38:41], v[156:159], v[188:191], v[38:41]
	v_mfma_f32_16x16x32_bf16 v[38:41], v[160:163], v[192:195], v[38:41]
	v_mfma_f32_16x16x32_bf16 v[46:49], v[148:151], v[188:191], v[46:49]
	v_mfma_f32_16x16x32_bf16 v[46:49], v[152:155], v[192:195], v[46:49]
	v_mfma_f32_16x16x32_bf16 v[30:33], v[148:151], v[196:199], v[30:33]
	v_mfma_f32_16x16x32_bf16 v[30:33], v[152:155], v[200:203], v[30:33]
	v_mfma_f32_16x16x32_bf16 v[22:25], v[156:159], v[196:199], v[22:25]
	v_mfma_f32_16x16x32_bf16 v[22:25], v[160:163], v[200:203], v[22:25]
	v_mfma_f32_16x16x32_bf16 v[26:29], v[164:167], v[196:199], v[26:29]
	v_mfma_f32_16x16x32_bf16 v[26:29], v[168:171], v[200:203], v[26:29]
	v_mfma_f32_16x16x32_bf16 v[18:21], v[172:175], v[196:199], v[18:21]
	v_mfma_f32_16x16x32_bf16 v[18:21], v[176:179], v[200:203], v[18:21]
	v_mfma_f32_16x16x32_bf16 v[2:5], v[172:175], v[204:207], v[2:5]
	v_mfma_f32_16x16x32_bf16 v[2:5], v[176:179], v[208:211], v[2:5]
	v_mfma_f32_16x16x32_bf16 v[10:13], v[164:167], v[204:207], v[10:13]
	v_mfma_f32_16x16x32_bf16 v[10:13], v[168:171], v[208:211], v[10:13]
	v_mfma_f32_16x16x32_bf16 v[6:9], v[156:159], v[204:207], v[6:9]
	v_mfma_f32_16x16x32_bf16 v[6:9], v[160:163], v[208:211], v[6:9]
	v_mfma_f32_16x16x32_bf16 v[14:17], v[148:151], v[204:207], v[14:17]
	v_mfma_f32_16x16x32_bf16 v[14:17], v[152:155], v[208:211], v[14:17]
	s_barrier
	s_add_i32 s73, s73, 2
	s_addk_i32 s71, 0x100
	s_addk_i32 s72, 0x100
	s_cmp_ge_i32 s73, s3
	s_cbranch_scc0 .LBB0_642
	s_and_b64 vcc, exec, s[42:43]
	s_cbranch_vccz .LBB0_645

.LBB0_799:
	ds_read_b128 v[134:137], v210
	ds_read_b128 v[138:141], v210 offset:1024
	ds_read_b128 v[142:145], v210 offset:2048
	ds_read_b128 v[148:151], v210 offset:3072
	ds_read_b128 v[152:155], v211
	ds_read_b128 v[156:159], v211 offset:1024
	ds_read_b128 v[160:163], v211 offset:2048
	ds_read_b128 v[164:167], v211 offset:3072
	s_add_i32 s18, s77, 0xffbf8080
	s_cmp_eq_u32 s62, s79
	s_cselect_b32 s80, s6, s18
	s_cselect_b32 s82, s7, s78
	s_or_b32 s81, s80, 0x80
	s_add_i32 s18, s77, 0xffea8000
	s_mov_b32 m0, s63
	ds_read_b128 v[168:171], v212
	ds_read_b128 v[172:175], v212 offset:1024
	ds_read_b128 v[176:179], v212 offset:2048
	ds_read_b128 v[180:183], v212 offset:3072
	ds_read_b128 v[184:187], v212 offset:4096
	ds_read_b128 v[188:191], v212 offset:5120
	ds_read_b128 v[192:195], v212 offset:6144
	ds_read_b128 v[196:199], v212 offset:7168
	buffer_load_dwordx4 v208, s[12:15], s18 offen lds
	s_mov_b32 m0, s66
	s_nop 0
	buffer_load_dwordx4 v208, s[12:15], s77 offen lds
	s_waitcnt vmcnt(8)
	s_waitcnt lgkmcnt(0)
	v_mfma_f32_16x16x32_bf16 v[126:129], v[134:137], v[168:171], v[126:129]
	s_barrier
	v_mfma_f32_16x16x32_bf16 v[126:129], v[138:141], v[172:175], v[126:129]
	v_mfma_f32_16x16x32_bf16 v[122:125], v[142:145], v[168:171], v[122:125]
	v_mfma_f32_16x16x32_bf16 v[122:125], v[148:151], v[172:175], v[122:125]
	v_mfma_f32_16x16x32_bf16 v[110:113], v[152:155], v[168:171], v[110:113]
	v_mfma_f32_16x16x32_bf16 v[110:113], v[156:159], v[172:175], v[110:113]
	v_mfma_f32_16x16x32_bf16 v[102:105], v[160:163], v[168:171], v[102:105]
	v_mfma_f32_16x16x32_bf16 v[102:105], v[164:167], v[172:175], v[102:105]
	v_mfma_f32_16x16x32_bf16 v[86:89], v[160:163], v[176:179], v[86:89]
	v_mfma_f32_16x16x32_bf16 v[86:89], v[164:167], v[180:183], v[86:89]
	v_mfma_f32_16x16x32_bf16 v[94:97], v[152:155], v[176:179], v[94:97]
	v_mfma_f32_16x16x32_bf16 v[94:97], v[156:159], v[180:183], v[94:97]
	v_mfma_f32_16x16x32_bf16 v[114:117], v[142:145], v[176:179], v[114:117]
	v_mfma_f32_16x16x32_bf16 v[114:117], v[148:151], v[180:183], v[114:117]
	v_mfma_f32_16x16x32_bf16 v[118:121], v[134:137], v[176:179], v[118:121]
	v_mfma_f32_16x16x32_bf16 v[118:121], v[138:141], v[180:183], v[118:121]
	v_mfma_f32_16x16x32_bf16 v[106:109], v[134:137], v[184:187], v[106:109]
	v_mfma_f32_16x16x32_bf16 v[106:109], v[138:141], v[188:191], v[106:109]
	v_mfma_f32_16x16x32_bf16 v[98:101], v[142:145], v[184:187], v[98:101]
	v_mfma_f32_16x16x32_bf16 v[98:101], v[148:151], v[188:191], v[98:101]
	v_mfma_f32_16x16x32_bf16 v[78:81], v[152:155], v[184:187], v[78:81]
	v_mfma_f32_16x16x32_bf16 v[78:81], v[156:159], v[188:191], v[78:81]
	v_mfma_f32_16x16x32_bf16 v[74:77], v[160:163], v[184:187], v[74:77]
	v_mfma_f32_16x16x32_bf16 v[74:77], v[164:167], v[188:191], v[74:77]
	v_mfma_f32_16x16x32_bf16 v[66:69], v[160:163], v[192:195], v[66:69]
	v_mfma_f32_16x16x32_bf16 v[66:69], v[164:167], v[196:199], v[66:69]
	v_mfma_f32_16x16x32_bf16 v[70:73], v[152:155], v[192:195], v[70:73]
	v_mfma_f32_16x16x32_bf16 v[70:73], v[156:159], v[196:199], v[70:73]
	v_mfma_f32_16x16x32_bf16 v[82:85], v[142:145], v[192:195], v[82:85]
	v_mfma_f32_16x16x32_bf16 v[82:85], v[148:151], v[196:199], v[82:85]
	v_mfma_f32_16x16x32_bf16 v[90:93], v[134:137], v[192:195], v[90:93]
	v_mfma_f32_16x16x32_bf16 v[90:93], v[138:141], v[196:199], v[90:93]
	s_barrier
	s_mov_b32 m0, s25
	s_mov_b32 s18, s14
	s_mov_b32 s19, s15
	ds_read_b128 v[168:171], v212 offset:16384
	ds_read_b128 v[172:175], v212 offset:17408
	ds_read_b128 v[176:179], v212 offset:18432
	ds_read_b128 v[180:183], v212 offset:19456
	ds_read_b128 v[184:187], v212 offset:20480
	ds_read_b128 v[188:191], v212 offset:21504
	ds_read_b128 v[192:195], v212 offset:22528
	ds_read_b128 v[196:199], v212 offset:23552
	buffer_load_dwordx4 v209, s[16:19], s82 offen lds
	s_add_i32 s83, s82, 0x158000
	s_mov_b32 m0, s27
	s_nop 0
	buffer_load_dwordx4 v209, s[16:19], s83 offen lds
	s_add_i32 s83, s82, 0x2b0000
	s_mov_b32 m0, s30
	s_nop 0
	buffer_load_dwordx4 v209, s[16:19], s83 offen lds
	s_add_i32 s83, s82, 0x408000
	s_mov_b32 m0, s31
	s_nop 0
	buffer_load_dwordx4 v209, s[16:19], s83 offen lds
	s_mov_b32 m0, s21
	s_add_i32 s83, s80, 0x158000
	buffer_load_dwordx4 v208, s[12:15], s80 offen lds
	s_mov_b32 m0, s48
	s_nop 0
	buffer_load_dwordx4 v208, s[12:15], s83 offen lds
	s_waitcnt vmcnt(8)
	s_waitcnt lgkmcnt(0)
	v_mfma_f32_16x16x32_bf16 v[62:65], v[134:137], v[168:171], v[62:65]
	s_barrier
	v_mfma_f32_16x16x32_bf16 v[62:65], v[138:141], v[172:175], v[62:65]
	v_mfma_f32_16x16x32_bf16 v[58:61], v[142:145], v[168:171], v[58:61]
	v_mfma_f32_16x16x32_bf16 v[58:61], v[148:151], v[172:175], v[58:61]
	v_mfma_f32_16x16x32_bf16 v[46:49], v[152:155], v[168:171], v[46:49]
	v_mfma_f32_16x16x32_bf16 v[46:49], v[156:159], v[172:175], v[46:49]
	v_mfma_f32_16x16x32_bf16 v[38:41], v[160:163], v[168:171], v[38:41]
	v_mfma_f32_16x16x32_bf16 v[38:41], v[164:167], v[172:175], v[38:41]
	v_mfma_f32_16x16x32_bf16 v[22:25], v[160:163], v[176:179], v[22:25]
	v_mfma_f32_16x16x32_bf16 v[22:25], v[164:167], v[180:183], v[22:25]
	v_mfma_f32_16x16x32_bf16 v[30:33], v[152:155], v[176:179], v[30:33]
	v_mfma_f32_16x16x32_bf16 v[30:33], v[156:159], v[180:183], v[30:33]
	v_mfma_f32_16x16x32_bf16 v[50:53], v[142:145], v[176:179], v[50:53]
	v_mfma_f32_16x16x32_bf16 v[50:53], v[148:151], v[180:183], v[50:53]
	v_mfma_f32_16x16x32_bf16 v[54:57], v[134:137], v[176:179], v[54:57]
	v_mfma_f32_16x16x32_bf16 v[54:57], v[138:141], v[180:183], v[54:57]
	v_mfma_f32_16x16x32_bf16 v[42:45], v[134:137], v[184:187], v[42:45]
	v_mfma_f32_16x16x32_bf16 v[42:45], v[138:141], v[188:191], v[42:45]
	v_mfma_f32_16x16x32_bf16 v[34:37], v[142:145], v[184:187], v[34:37]
	v_mfma_f32_16x16x32_bf16 v[34:37], v[148:151], v[188:191], v[34:37]
	v_mfma_f32_16x16x32_bf16 v[14:17], v[152:155], v[184:187], v[14:17]
	v_mfma_f32_16x16x32_bf16 v[14:17], v[156:159], v[188:191], v[14:17]
	v_mfma_f32_16x16x32_bf16 v[10:13], v[160:163], v[184:187], v[10:13]
	v_mfma_f32_16x16x32_bf16 v[10:13], v[164:167], v[188:191], v[10:13]
	v_mfma_f32_16x16x32_bf16 v[2:5], v[160:163], v[192:195], v[2:5]
	v_mfma_f32_16x16x32_bf16 v[2:5], v[164:167], v[196:199], v[2:5]
	v_mfma_f32_16x16x32_bf16 v[6:9], v[152:155], v[192:195], v[6:9]
	v_mfma_f32_16x16x32_bf16 v[6:9], v[156:159], v[196:199], v[6:9]
	v_mfma_f32_16x16x32_bf16 v[18:21], v[142:145], v[192:195], v[18:21]
	v_mfma_f32_16x16x32_bf16 v[18:21], v[148:151], v[196:199], v[18:21]
	v_mfma_f32_16x16x32_bf16 v[26:29], v[134:137], v[192:195], v[26:29]
	v_mfma_f32_16x16x32_bf16 v[26:29], v[138:141], v[196:199], v[26:29]
	s_barrier
	ds_read_b128 v[134:137], v213
	ds_read_b128 v[138:141], v213 offset:1024
	ds_read_b128 v[142:145], v213 offset:2048
	ds_read_b128 v[148:151], v213 offset:3072
	ds_read_b128 v[152:155], v214
	ds_read_b128 v[156:159], v214 offset:1024
	ds_read_b128 v[160:163], v214 offset:2048
	ds_read_b128 v[164:167], v214 offset:3072
	s_mov_b32 m0, s49
	s_add_i32 s83, s80, 0x2b0000
	ds_read_b128 v[168:171], v212 offset:32768
	ds_read_b128 v[172:175], v212 offset:33792
	ds_read_b128 v[176:179], v212 offset:34816
	ds_read_b128 v[180:183], v212 offset:35840
	ds_read_b128 v[184:187], v212 offset:36864
	ds_read_b128 v[188:191], v212 offset:37888
	ds_read_b128 v[192:195], v212 offset:38912
	ds_read_b128 v[196:199], v212 offset:39936
	buffer_load_dwordx4 v208, s[12:15], s83 offen lds
	s_add_i32 s83, s80, 0x408000
	s_mov_b32 m0, s50
	s_nop 0
	buffer_load_dwordx4 v208, s[12:15], s83 offen lds
	s_waitcnt vmcnt(8)
	s_waitcnt lgkmcnt(0)
	v_mfma_f32_16x16x32_bf16 v[126:129], v[134:137], v[168:171], v[126:129]
	s_barrier
	v_mfma_f32_16x16x32_bf16 v[126:129], v[138:141], v[172:175], v[126:129]
	v_mfma_f32_16x16x32_bf16 v[122:125], v[142:145], v[168:171], v[122:125]
	v_mfma_f32_16x16x32_bf16 v[122:125], v[148:151], v[172:175], v[122:125]
	v_mfma_f32_16x16x32_bf16 v[110:113], v[152:155], v[168:171], v[110:113]
	v_mfma_f32_16x16x32_bf16 v[110:113], v[156:159], v[172:175], v[110:113]
	v_mfma_f32_16x16x32_bf16 v[102:105], v[160:163], v[168:171], v[102:105]
	v_mfma_f32_16x16x32_bf16 v[102:105], v[164:167], v[172:175], v[102:105]
	v_mfma_f32_16x16x32_bf16 v[86:89], v[160:163], v[176:179], v[86:89]
	v_mfma_f32_16x16x32_bf16 v[86:89], v[164:167], v[180:183], v[86:89]
	v_mfma_f32_16x16x32_bf16 v[94:97], v[152:155], v[176:179], v[94:97]
	v_mfma_f32_16x16x32_bf16 v[94:97], v[156:159], v[180:183], v[94:97]
	v_mfma_f32_16x16x32_bf16 v[114:117], v[142:145], v[176:179], v[114:117]
	v_mfma_f32_16x16x32_bf16 v[114:117], v[148:151], v[180:183], v[114:117]
	v_mfma_f32_16x16x32_bf16 v[118:121], v[134:137], v[176:179], v[118:121]
	v_mfma_f32_16x16x32_bf16 v[118:121], v[138:141], v[180:183], v[118:121]
	v_mfma_f32_16x16x32_bf16 v[106:109], v[134:137], v[184:187], v[106:109]
	v_mfma_f32_16x16x32_bf16 v[106:109], v[138:141], v[188:191], v[106:109]
	v_mfma_f32_16x16x32_bf16 v[98:101], v[142:145], v[184:187], v[98:101]
	v_mfma_f32_16x16x32_bf16 v[98:101], v[148:151], v[188:191], v[98:101]
	v_mfma_f32_16x16x32_bf16 v[78:81], v[152:155], v[184:187], v[78:81]
	v_mfma_f32_16x16x32_bf16 v[78:81], v[156:159], v[188:191], v[78:81]
	v_mfma_f32_16x16x32_bf16 v[74:77], v[160:163], v[184:187], v[74:77]
	v_mfma_f32_16x16x32_bf16 v[74:77], v[164:167], v[188:191], v[74:77]
	v_mfma_f32_16x16x32_bf16 v[66:69], v[160:163], v[192:195], v[66:69]
	v_mfma_f32_16x16x32_bf16 v[66:69], v[164:167], v[196:199], v[66:69]
	v_mfma_f32_16x16x32_bf16 v[70:73], v[152:155], v[192:195], v[70:73]
	v_mfma_f32_16x16x32_bf16 v[70:73], v[156:159], v[196:199], v[70:73]
	v_mfma_f32_16x16x32_bf16 v[82:85], v[142:145], v[192:195], v[82:85]
	v_mfma_f32_16x16x32_bf16 v[82:85], v[148:151], v[196:199], v[82:85]
	v_mfma_f32_16x16x32_bf16 v[90:93], v[134:137], v[192:195], v[90:93]
	v_mfma_f32_16x16x32_bf16 v[90:93], v[138:141], v[196:199], v[90:93]
	s_barrier
	s_mov_b32 m0, s54
	s_or_b32 s83, s82, 0x80
	ds_read_b128 v[168:171], v212 offset:49152
	ds_read_b128 v[172:175], v212 offset:50176
	ds_read_b128 v[176:179], v212 offset:51200
	ds_read_b128 v[180:183], v212 offset:52224
	ds_read_b128 v[184:187], v212 offset:53248
	ds_read_b128 v[188:191], v212 offset:54272
	ds_read_b128 v[192:195], v212 offset:55296
	ds_read_b128 v[196:199], v212 offset:56320
	buffer_load_dwordx4 v209, s[16:19], s83 offen lds
	s_add_i32 s83, s82, 0x158080
	s_mov_b32 m0, s55
	s_add_i32 s80, s80, 0x158080
	buffer_load_dwordx4 v209, s[16:19], s83 offen lds
	s_add_i32 s83, s82, 0x2b0080
	s_mov_b32 m0, s58
	s_add_i32 s82, s82, 0x408080
	buffer_load_dwordx4 v209, s[16:19], s83 offen lds
	s_mov_b32 m0, s59
	s_nop 0
	buffer_load_dwordx4 v209, s[16:19], s82 offen lds
	s_mov_b32 m0, s56
	s_nop 0
	buffer_load_dwordx4 v208, s[12:15], s81 offen lds
	s_mov_b32 m0, s57
	s_nop 0
	buffer_load_dwordx4 v208, s[12:15], s80 offen lds
	s_waitcnt vmcnt(8)
	s_waitcnt lgkmcnt(0)
	v_mfma_f32_16x16x32_bf16 v[62:65], v[134:137], v[168:171], v[62:65]
	s_barrier
	v_mfma_f32_16x16x32_bf16 v[62:65], v[138:141], v[172:175], v[62:65]
	v_mfma_f32_16x16x32_bf16 v[58:61], v[142:145], v[168:171], v[58:61]
	v_mfma_f32_16x16x32_bf16 v[58:61], v[148:151], v[172:175], v[58:61]
	v_mfma_f32_16x16x32_bf16 v[46:49], v[152:155], v[168:171], v[46:49]
	v_mfma_f32_16x16x32_bf16 v[46:49], v[156:159], v[172:175], v[46:49]
	v_mfma_f32_16x16x32_bf16 v[38:41], v[160:163], v[168:171], v[38:41]
	v_mfma_f32_16x16x32_bf16 v[38:41], v[164:167], v[172:175], v[38:41]
	v_mfma_f32_16x16x32_bf16 v[22:25], v[160:163], v[176:179], v[22:25]
	v_mfma_f32_16x16x32_bf16 v[22:25], v[164:167], v[180:183], v[22:25]
	v_mfma_f32_16x16x32_bf16 v[30:33], v[152:155], v[176:179], v[30:33]
	v_mfma_f32_16x16x32_bf16 v[30:33], v[156:159], v[180:183], v[30:33]
	v_mfma_f32_16x16x32_bf16 v[50:53], v[142:145], v[176:179], v[50:53]
	v_mfma_f32_16x16x32_bf16 v[50:53], v[148:151], v[180:183], v[50:53]
	v_mfma_f32_16x16x32_bf16 v[54:57], v[134:137], v[176:179], v[54:57]
	v_mfma_f32_16x16x32_bf16 v[54:57], v[138:141], v[180:183], v[54:57]
	v_mfma_f32_16x16x32_bf16 v[42:45], v[134:137], v[184:187], v[42:45]
	v_mfma_f32_16x16x32_bf16 v[42:45], v[138:141], v[188:191], v[42:45]
	v_mfma_f32_16x16x32_bf16 v[34:37], v[142:145], v[184:187], v[34:37]
	v_mfma_f32_16x16x32_bf16 v[34:37], v[148:151], v[188:191], v[34:37]
	v_mfma_f32_16x16x32_bf16 v[14:17], v[152:155], v[184:187], v[14:17]
	v_mfma_f32_16x16x32_bf16 v[14:17], v[156:159], v[188:191], v[14:17]
	v_mfma_f32_16x16x32_bf16 v[10:13], v[160:163], v[184:187], v[10:13]
	v_mfma_f32_16x16x32_bf16 v[10:13], v[164:167], v[188:191], v[10:13]
	v_mfma_f32_16x16x32_bf16 v[2:5], v[160:163], v[192:195], v[2:5]
	v_mfma_f32_16x16x32_bf16 v[2:5], v[164:167], v[196:199], v[2:5]
	v_mfma_f32_16x16x32_bf16 v[6:9], v[152:155], v[192:195], v[6:9]
	v_mfma_f32_16x16x32_bf16 v[6:9], v[156:159], v[196:199], v[6:9]
	v_mfma_f32_16x16x32_bf16 v[18:21], v[142:145], v[192:195], v[18:21]
	v_mfma_f32_16x16x32_bf16 v[18:21], v[148:151], v[196:199], v[18:21]
	v_mfma_f32_16x16x32_bf16 v[26:29], v[134:137], v[192:195], v[26:29]
	v_mfma_f32_16x16x32_bf16 v[26:29], v[138:141], v[196:199], v[26:29]
	s_barrier
	s_add_i32 s79, s79, 2
	s_addk_i32 s77, 0x100
	s_addk_i32 s78, 0x100
	s_cmp_ge_i32 s79, s3
	s_cbranch_scc0 .LBB0_799
	v_pk_mul_f32 v[184:185], v[128:129], 0.5 op_sel_hi:[1,0]
	v_pk_mul_f32 v[186:187], v[126:127], 0.5 op_sel_hi:[1,0]
	v_pk_mul_f32 v[188:189], v[124:125], 0.5 op_sel_hi:[1,0]
	v_pk_mul_f32 v[190:191], v[122:123], 0.5 op_sel_hi:[1,0]
	v_pk_mul_f32 v[198:199], v[112:113], 0.5 op_sel_hi:[1,0]
	v_pk_mul_f32 v[196:197], v[110:111], 0.5 op_sel_hi:[1,0]
	v_pk_mul_f32 v[194:195], v[104:105], 0.5 op_sel_hi:[1,0]
	v_pk_mul_f32 v[192:193], v[102:103], 0.5 op_sel_hi:[1,0]
	v_pk_mul_f32 v[182:183], v[120:121], 0.5 op_sel_hi:[1,0]
	v_pk_mul_f32 v[180:181], v[118:119], 0.5 op_sel_hi:[1,0]
	v_pk_mul_f32 v[178:179], v[116:117], 0.5 op_sel_hi:[1,0]
	v_pk_mul_f32 v[176:177], v[114:115], 0.5 op_sel_hi:[1,0]
	v_pk_mul_f32 v[172:173], v[96:97], 0.5 op_sel_hi:[1,0]
	v_pk_mul_f32 v[170:171], v[94:95], 0.5 op_sel_hi:[1,0]
	v_pk_mul_f32 v[168:169], v[88:89], 0.5 op_sel_hi:[1,0]
	v_pk_mul_f32 v[166:167], v[86:87], 0.5 op_sel_hi:[1,0]
	v_pk_mul_f32 v[164:165], v[108:109], 0.5 op_sel_hi:[1,0]
	v_pk_mul_f32 v[162:163], v[106:107], 0.5 op_sel_hi:[1,0]
	v_pk_mul_f32 v[160:161], v[100:101], 0.5 op_sel_hi:[1,0]
	v_pk_mul_f32 v[158:159], v[98:99], 0.5 op_sel_hi:[1,0]
	v_pk_mul_f32 v[156:157], v[80:81], 0.5 op_sel_hi:[1,0]
	v_pk_mul_f32 v[154:155], v[78:79], 0.5 op_sel_hi:[1,0]
	v_pk_mul_f32 v[152:153], v[76:77], 0.5 op_sel_hi:[1,0]
	v_pk_mul_f32 v[150:151], v[74:75], 0.5 op_sel_hi:[1,0]
	v_pk_mul_f32 v[144:145], v[92:93], 0.5 op_sel_hi:[1,0]
	v_pk_mul_f32 v[142:143], v[90:91], 0.5 op_sel_hi:[1,0]
	v_pk_mul_f32 v[140:141], v[84:85], 0.5 op_sel_hi:[1,0]
	v_pk_mul_f32 v[138:139], v[82:83], 0.5 op_sel_hi:[1,0]
	v_pk_mul_f32 v[136:137], v[72:73], 0.5 op_sel_hi:[1,0]
	v_pk_mul_f32 v[134:135], v[70:71], 0.5 op_sel_hi:[1,0]
	v_pk_mul_f32 v[128:129], v[68:69], 0.5 op_sel_hi:[1,0]
	v_pk_mul_f32 v[126:127], v[66:67], 0.5 op_sel_hi:[1,0]
	v_pk_mul_f32 v[122:123], v[64:65], 0.5 op_sel_hi:[1,0]
	v_pk_mul_f32 v[120:121], v[62:63], 0.5 op_sel_hi:[1,0]
	v_pk_mul_f32 v[118:119], v[60:61], 0.5 op_sel_hi:[1,0]
	v_pk_mul_f32 v[116:117], v[58:59], 0.5 op_sel_hi:[1,0]
	v_pk_mul_f32 v[112:113], v[48:49], 0.5 op_sel_hi:[1,0]
	v_pk_mul_f32 v[110:111], v[46:47], 0.5 op_sel_hi:[1,0]
	v_pk_mul_f32 v[108:109], v[40:41], 0.5 op_sel_hi:[1,0]
	v_pk_mul_f32 v[106:107], v[38:39], 0.5 op_sel_hi:[1,0]
	v_pk_mul_f32 v[104:105], v[56:57], 0.5 op_sel_hi:[1,0]
	v_pk_mul_f32 v[102:103], v[54:55], 0.5 op_sel_hi:[1,0]
	v_pk_mul_f32 v[100:101], v[52:53], 0.5 op_sel_hi:[1,0]
	v_pk_mul_f32 v[98:99], v[50:51], 0.5 op_sel_hi:[1,0]
	v_pk_mul_f32 v[96:97], v[32:33], 0.5 op_sel_hi:[1,0]
	v_pk_mul_f32 v[94:95], v[30:31], 0.5 op_sel_hi:[1,0]
	v_pk_mul_f32 v[92:93], v[24:25], 0.5 op_sel_hi:[1,0]
	v_pk_mul_f32 v[90:91], v[22:23], 0.5 op_sel_hi:[1,0]
	v_pk_mul_f32 v[88:89], v[44:45], 0.5 op_sel_hi:[1,0]
	v_pk_mul_f32 v[86:87], v[42:43], 0.5 op_sel_hi:[1,0]
	v_pk_mul_f32 v[84:85], v[36:37], 0.5 op_sel_hi:[1,0]
	v_pk_mul_f32 v[82:83], v[34:35], 0.5 op_sel_hi:[1,0]
	v_pk_mul_f32 v[80:81], v[16:17], 0.5 op_sel_hi:[1,0]
	v_pk_mul_f32 v[78:79], v[14:15], 0.5 op_sel_hi:[1,0]
	v_pk_mul_f32 v[76:77], v[12:13], 0.5 op_sel_hi:[1,0]
	v_pk_mul_f32 v[74:75], v[10:11], 0.5 op_sel_hi:[1,0]
	v_pk_mul_f32 v[72:73], v[28:29], 0.5 op_sel_hi:[1,0]
	v_pk_mul_f32 v[70:71], v[26:27], 0.5 op_sel_hi:[1,0]
	v_pk_mul_f32 v[68:69], v[20:21], 0.5 op_sel_hi:[1,0]
	v_pk_mul_f32 v[66:67], v[18:19], 0.5 op_sel_hi:[1,0]
	v_pk_mul_f32 v[64:65], v[8:9], 0.5 op_sel_hi:[1,0]
	v_pk_mul_f32 v[62:63], v[6:7], 0.5 op_sel_hi:[1,0]
	v_pk_mul_f32 v[60:61], v[4:5], 0.5 op_sel_hi:[1,0]
	v_pk_mul_f32 v[58:59], v[2:3], 0.5 op_sel_hi:[1,0]
	s_and_b64 vcc, exec, s[38:39]
	s_cbranch_vccz .LBB0_802

.LBB0_892:
	ds_read_b128 v[130:133], v172
	ds_read_b128 v[134:137], v172 offset:1024
	ds_read_b128 v[148:151], v172 offset:2048
	ds_read_b128 v[152:155], v172 offset:3072
	ds_read_b128 v[156:159], v173
	ds_read_b128 v[160:163], v173 offset:1024
	ds_read_b128 v[164:167], v173 offset:2048
	ds_read_b128 v[180:183], v173 offset:3072
	s_add_i32 s18, s8, 0xffe80080
	s_cmp_eq_u32 s77, s52
	s_cselect_b32 s53, s6, s18
	s_cselect_b32 s58, s7, s9
	s_or_b32 s57, s53, 0x80
	s_add_i32 s18, s8, 0xfff80000
	s_mov_b32 m0, s78
	ds_read_b128 v[184:187], v174
	ds_read_b128 v[188:191], v174 offset:1024
	ds_read_b128 v[192:195], v174 offset:2048
	ds_read_b128 v[196:199], v174 offset:3072
	ds_read_b128 v[200:203], v174 offset:4096
	ds_read_b128 v[204:207], v174 offset:5120
	ds_read_b128 v[208:211], v174 offset:6144
	ds_read_b128 v[212:215], v174 offset:7168
	buffer_load_dwordx4 v170, s[12:15], s18 offen lds
	s_mov_b32 m0, s79
	s_nop 0
	buffer_load_dwordx4 v170, s[12:15], s8 offen lds
	s_waitcnt vmcnt(8)
	s_waitcnt lgkmcnt(0)
	v_mfma_f32_16x16x32_bf16 v[126:129], v[130:133], v[184:187], v[126:129]
	s_barrier
	v_mfma_f32_16x16x32_bf16 v[126:129], v[134:137], v[188:191], v[126:129]
	v_mfma_f32_16x16x32_bf16 v[118:121], v[148:151], v[184:187], v[118:121]
	v_mfma_f32_16x16x32_bf16 v[118:121], v[152:155], v[188:191], v[118:121]
	v_mfma_f32_16x16x32_bf16 v[122:125], v[156:159], v[184:187], v[122:125]
	v_mfma_f32_16x16x32_bf16 v[122:125], v[160:163], v[188:191], v[122:125]
	v_mfma_f32_16x16x32_bf16 v[114:117], v[164:167], v[184:187], v[114:117]
	v_mfma_f32_16x16x32_bf16 v[114:117], v[180:183], v[188:191], v[114:117]
	v_mfma_f32_16x16x32_bf16 v[98:101], v[164:167], v[192:195], v[98:101]
	v_mfma_f32_16x16x32_bf16 v[98:101], v[180:183], v[196:199], v[98:101]
	v_mfma_f32_16x16x32_bf16 v[106:109], v[156:159], v[192:195], v[106:109]
	v_mfma_f32_16x16x32_bf16 v[106:109], v[160:163], v[196:199], v[106:109]
	v_mfma_f32_16x16x32_bf16 v[102:105], v[148:151], v[192:195], v[102:105]
	v_mfma_f32_16x16x32_bf16 v[102:105], v[152:155], v[196:199], v[102:105]
	v_mfma_f32_16x16x32_bf16 v[110:113], v[130:133], v[192:195], v[110:113]
	v_mfma_f32_16x16x32_bf16 v[110:113], v[134:137], v[196:199], v[110:113]
	v_mfma_f32_16x16x32_bf16 v[94:97], v[130:133], v[200:203], v[94:97]
	v_mfma_f32_16x16x32_bf16 v[94:97], v[134:137], v[204:207], v[94:97]
	v_mfma_f32_16x16x32_bf16 v[90:93], v[148:151], v[200:203], v[90:93]
	v_mfma_f32_16x16x32_bf16 v[90:93], v[152:155], v[204:207], v[90:93]
	v_mfma_f32_16x16x32_bf16 v[86:89], v[156:159], v[200:203], v[86:89]
	v_mfma_f32_16x16x32_bf16 v[86:89], v[160:163], v[204:207], v[86:89]
	v_mfma_f32_16x16x32_bf16 v[82:85], v[164:167], v[200:203], v[82:85]
	v_mfma_f32_16x16x32_bf16 v[82:85], v[180:183], v[204:207], v[82:85]
	v_mfma_f32_16x16x32_bf16 v[66:69], v[164:167], v[208:211], v[66:69]
	v_mfma_f32_16x16x32_bf16 v[66:69], v[180:183], v[212:215], v[66:69]
	v_mfma_f32_16x16x32_bf16 v[74:77], v[156:159], v[208:211], v[74:77]
	v_mfma_f32_16x16x32_bf16 v[74:77], v[160:163], v[212:215], v[74:77]
	v_mfma_f32_16x16x32_bf16 v[70:73], v[148:151], v[208:211], v[70:73]
	v_mfma_f32_16x16x32_bf16 v[70:73], v[152:155], v[212:215], v[70:73]
	v_mfma_f32_16x16x32_bf16 v[78:81], v[130:133], v[208:211], v[78:81]
	v_mfma_f32_16x16x32_bf16 v[78:81], v[134:137], v[212:215], v[78:81]
	s_barrier
	s_mov_b32 m0, s27
	s_mov_b32 s18, s14
	s_mov_b32 s19, s15
	ds_read_b128 v[184:187], v174 offset:16384
	ds_read_b128 v[188:191], v174 offset:17408
	ds_read_b128 v[192:195], v174 offset:18432
	ds_read_b128 v[196:199], v174 offset:19456
	ds_read_b128 v[200:203], v174 offset:20480
	ds_read_b128 v[204:207], v174 offset:21504
	ds_read_b128 v[208:211], v174 offset:22528
	ds_read_b128 v[212:215], v174 offset:23552
	buffer_load_dwordx4 v171, s[16:19], s58 offen lds
	s_add_i32 s59, s58, 0x80000
	s_mov_b32 m0, s60
	s_nop 0
	buffer_load_dwordx4 v171, s[16:19], s59 offen lds
	s_add_i32 s59, s58, 0x100000
	s_mov_b32 m0, s61
	s_nop 0
	buffer_load_dwordx4 v171, s[16:19], s59 offen lds
	s_add_i32 s59, s58, 0x180000
	s_mov_b32 m0, s62
	s_nop 0
	buffer_load_dwordx4 v171, s[16:19], s59 offen lds
	s_mov_b32 m0, s25
	s_add_i32 s59, s53, 0x80000
	buffer_load_dwordx4 v170, s[12:15], s53 offen lds
	s_mov_b32 m0, s63
	s_nop 0
	buffer_load_dwordx4 v170, s[12:15], s59 offen lds
	s_waitcnt vmcnt(8)
	s_waitcnt lgkmcnt(0)
	v_mfma_f32_16x16x32_bf16 v[62:65], v[130:133], v[184:187], v[62:65]
	s_barrier
	v_mfma_f32_16x16x32_bf16 v[62:65], v[134:137], v[188:191], v[62:65]
	v_mfma_f32_16x16x32_bf16 v[54:57], v[148:151], v[184:187], v[54:57]
	v_mfma_f32_16x16x32_bf16 v[54:57], v[152:155], v[188:191], v[54:57]
	v_mfma_f32_16x16x32_bf16 v[58:61], v[156:159], v[184:187], v[58:61]
	v_mfma_f32_16x16x32_bf16 v[58:61], v[160:163], v[188:191], v[58:61]
	v_mfma_f32_16x16x32_bf16 v[50:53], v[164:167], v[184:187], v[50:53]
	v_mfma_f32_16x16x32_bf16 v[50:53], v[180:183], v[188:191], v[50:53]
	v_mfma_f32_16x16x32_bf16 v[34:37], v[164:167], v[192:195], v[34:37]
	v_mfma_f32_16x16x32_bf16 v[34:37], v[180:183], v[196:199], v[34:37]
	v_mfma_f32_16x16x32_bf16 v[42:45], v[156:159], v[192:195], v[42:45]
	v_mfma_f32_16x16x32_bf16 v[42:45], v[160:163], v[196:199], v[42:45]
	v_mfma_f32_16x16x32_bf16 v[38:41], v[148:151], v[192:195], v[38:41]
	v_mfma_f32_16x16x32_bf16 v[38:41], v[152:155], v[196:199], v[38:41]
	v_mfma_f32_16x16x32_bf16 v[46:49], v[130:133], v[192:195], v[46:49]
	v_mfma_f32_16x16x32_bf16 v[46:49], v[134:137], v[196:199], v[46:49]
	v_mfma_f32_16x16x32_bf16 v[30:33], v[130:133], v[200:203], v[30:33]
	v_mfma_f32_16x16x32_bf16 v[30:33], v[134:137], v[204:207], v[30:33]
	v_mfma_f32_16x16x32_bf16 v[22:25], v[148:151], v[200:203], v[22:25]
	v_mfma_f32_16x16x32_bf16 v[22:25], v[152:155], v[204:207], v[22:25]
	v_mfma_f32_16x16x32_bf16 v[26:29], v[156:159], v[200:203], v[26:29]
	v_mfma_f32_16x16x32_bf16 v[26:29], v[160:163], v[204:207], v[26:29]
	v_mfma_f32_16x16x32_bf16 v[18:21], v[164:167], v[200:203], v[18:21]
	v_mfma_f32_16x16x32_bf16 v[18:21], v[180:183], v[204:207], v[18:21]
	v_mfma_f32_16x16x32_bf16 v[2:5], v[164:167], v[208:211], v[2:5]
	v_mfma_f32_16x16x32_bf16 v[2:5], v[180:183], v[212:215], v[2:5]
	v_mfma_f32_16x16x32_bf16 v[10:13], v[156:159], v[208:211], v[10:13]
	v_mfma_f32_16x16x32_bf16 v[10:13], v[160:163], v[212:215], v[10:13]
	v_mfma_f32_16x16x32_bf16 v[6:9], v[148:151], v[208:211], v[6:9]
	v_mfma_f32_16x16x32_bf16 v[6:9], v[152:155], v[212:215], v[6:9]
	v_mfma_f32_16x16x32_bf16 v[14:17], v[130:133], v[208:211], v[14:17]
	v_mfma_f32_16x16x32_bf16 v[14:17], v[134:137], v[212:215], v[14:17]
	s_barrier
	ds_read_b128 v[130:133], v175
	ds_read_b128 v[134:137], v175 offset:1024
	ds_read_b128 v[148:151], v175 offset:2048
	ds_read_b128 v[152:155], v175 offset:3072
	ds_read_b128 v[156:159], v176
	ds_read_b128 v[160:163], v176 offset:1024
	ds_read_b128 v[164:167], v176 offset:2048
	ds_read_b128 v[180:183], v176 offset:3072
	s_mov_b32 m0, s64
	s_add_i32 s59, s53, 0x100000
	ds_read_b128 v[184:187], v174 offset:32768
	ds_read_b128 v[188:191], v174 offset:33792
	ds_read_b128 v[192:195], v174 offset:34816
	ds_read_b128 v[196:199], v174 offset:35840
	ds_read_b128 v[200:203], v174 offset:36864
	ds_read_b128 v[204:207], v174 offset:37888
	ds_read_b128 v[208:211], v174 offset:38912
	ds_read_b128 v[212:215], v174 offset:39936
	buffer_load_dwordx4 v170, s[12:15], s59 offen lds
	s_add_i32 s59, s53, 0x180000
	s_mov_b32 m0, s65
	s_nop 0
	buffer_load_dwordx4 v170, s[12:15], s59 offen lds
	s_waitcnt vmcnt(8)
	s_waitcnt lgkmcnt(0)
	v_mfma_f32_16x16x32_bf16 v[126:129], v[130:133], v[184:187], v[126:129]
	s_barrier
	v_mfma_f32_16x16x32_bf16 v[126:129], v[134:137], v[188:191], v[126:129]
	v_mfma_f32_16x16x32_bf16 v[118:121], v[148:151], v[184:187], v[118:121]
	v_mfma_f32_16x16x32_bf16 v[118:121], v[152:155], v[188:191], v[118:121]
	v_mfma_f32_16x16x32_bf16 v[122:125], v[156:159], v[184:187], v[122:125]
	v_mfma_f32_16x16x32_bf16 v[122:125], v[160:163], v[188:191], v[122:125]
	v_mfma_f32_16x16x32_bf16 v[114:117], v[164:167], v[184:187], v[114:117]
	v_mfma_f32_16x16x32_bf16 v[114:117], v[180:183], v[188:191], v[114:117]
	v_mfma_f32_16x16x32_bf16 v[98:101], v[164:167], v[192:195], v[98:101]
	v_mfma_f32_16x16x32_bf16 v[98:101], v[180:183], v[196:199], v[98:101]
	v_mfma_f32_16x16x32_bf16 v[106:109], v[156:159], v[192:195], v[106:109]
	v_mfma_f32_16x16x32_bf16 v[106:109], v[160:163], v[196:199], v[106:109]
	v_mfma_f32_16x16x32_bf16 v[102:105], v[148:151], v[192:195], v[102:105]
	v_mfma_f32_16x16x32_bf16 v[102:105], v[152:155], v[196:199], v[102:105]
	v_mfma_f32_16x16x32_bf16 v[110:113], v[130:133], v[192:195], v[110:113]
	v_mfma_f32_16x16x32_bf16 v[110:113], v[134:137], v[196:199], v[110:113]
	v_mfma_f32_16x16x32_bf16 v[94:97], v[130:133], v[200:203], v[94:97]
	v_mfma_f32_16x16x32_bf16 v[94:97], v[134:137], v[204:207], v[94:97]
	v_mfma_f32_16x16x32_bf16 v[90:93], v[148:151], v[200:203], v[90:93]
	v_mfma_f32_16x16x32_bf16 v[90:93], v[152:155], v[204:207], v[90:93]
	v_mfma_f32_16x16x32_bf16 v[86:89], v[156:159], v[200:203], v[86:89]
	v_mfma_f32_16x16x32_bf16 v[86:89], v[160:163], v[204:207], v[86:89]
	v_mfma_f32_16x16x32_bf16 v[82:85], v[164:167], v[200:203], v[82:85]
	v_mfma_f32_16x16x32_bf16 v[82:85], v[180:183], v[204:207], v[82:85]
	v_mfma_f32_16x16x32_bf16 v[66:69], v[164:167], v[208:211], v[66:69]
	v_mfma_f32_16x16x32_bf16 v[66:69], v[180:183], v[212:215], v[66:69]
	v_mfma_f32_16x16x32_bf16 v[74:77], v[156:159], v[208:211], v[74:77]
	v_mfma_f32_16x16x32_bf16 v[74:77], v[160:163], v[212:215], v[74:77]
	v_mfma_f32_16x16x32_bf16 v[70:73], v[148:151], v[208:211], v[70:73]
	v_mfma_f32_16x16x32_bf16 v[70:73], v[152:155], v[212:215], v[70:73]
	v_mfma_f32_16x16x32_bf16 v[78:81], v[130:133], v[208:211], v[78:81]
	v_mfma_f32_16x16x32_bf16 v[78:81], v[134:137], v[212:215], v[78:81]
	s_barrier
	s_mov_b32 m0, s70
	s_or_b32 s59, s58, 0x80
	ds_read_b128 v[184:187], v174 offset:49152
	ds_read_b128 v[188:191], v174 offset:50176
	ds_read_b128 v[192:195], v174 offset:51200
	ds_read_b128 v[196:199], v174 offset:52224
	ds_read_b128 v[200:203], v174 offset:53248
	ds_read_b128 v[204:207], v174 offset:54272
	ds_read_b128 v[208:211], v174 offset:55296
	ds_read_b128 v[212:215], v174 offset:56320
	buffer_load_dwordx4 v171, s[16:19], s59 offen lds
	s_add_i32 s59, s58, 0x80080
	s_mov_b32 m0, s71
	s_add_i32 s53, s53, 0x80080
	buffer_load_dwordx4 v171, s[16:19], s59 offen lds
	s_add_i32 s59, s58, 0x100080
	s_mov_b32 m0, s74
	s_add_i32 s58, s58, 0x180080
	buffer_load_dwordx4 v171, s[16:19], s59 offen lds
	s_mov_b32 m0, s75
	s_nop 0
	buffer_load_dwordx4 v171, s[16:19], s58 offen lds
	s_mov_b32 m0, s72
	s_nop 0
	buffer_load_dwordx4 v170, s[12:15], s57 offen lds
	s_mov_b32 m0, s73
	s_nop 0
	buffer_load_dwordx4 v170, s[12:15], s53 offen lds
	s_waitcnt vmcnt(8)
	s_waitcnt lgkmcnt(0)
	v_mfma_f32_16x16x32_bf16 v[62:65], v[130:133], v[184:187], v[62:65]
	s_barrier
	v_mfma_f32_16x16x32_bf16 v[62:65], v[134:137], v[188:191], v[62:65]
	v_mfma_f32_16x16x32_bf16 v[54:57], v[148:151], v[184:187], v[54:57]
	v_mfma_f32_16x16x32_bf16 v[54:57], v[152:155], v[188:191], v[54:57]
	v_mfma_f32_16x16x32_bf16 v[58:61], v[156:159], v[184:187], v[58:61]
	v_mfma_f32_16x16x32_bf16 v[58:61], v[160:163], v[188:191], v[58:61]
	v_mfma_f32_16x16x32_bf16 v[50:53], v[164:167], v[184:187], v[50:53]
	v_mfma_f32_16x16x32_bf16 v[50:53], v[180:183], v[188:191], v[50:53]
	v_mfma_f32_16x16x32_bf16 v[34:37], v[164:167], v[192:195], v[34:37]
	v_mfma_f32_16x16x32_bf16 v[34:37], v[180:183], v[196:199], v[34:37]
	v_mfma_f32_16x16x32_bf16 v[42:45], v[156:159], v[192:195], v[42:45]
	v_mfma_f32_16x16x32_bf16 v[42:45], v[160:163], v[196:199], v[42:45]
	v_mfma_f32_16x16x32_bf16 v[38:41], v[148:151], v[192:195], v[38:41]
	v_mfma_f32_16x16x32_bf16 v[38:41], v[152:155], v[196:199], v[38:41]
	v_mfma_f32_16x16x32_bf16 v[46:49], v[130:133], v[192:195], v[46:49]
	v_mfma_f32_16x16x32_bf16 v[46:49], v[134:137], v[196:199], v[46:49]
	v_mfma_f32_16x16x32_bf16 v[30:33], v[130:133], v[200:203], v[30:33]
	v_mfma_f32_16x16x32_bf16 v[30:33], v[134:137], v[204:207], v[30:33]
	v_mfma_f32_16x16x32_bf16 v[22:25], v[148:151], v[200:203], v[22:25]
	v_mfma_f32_16x16x32_bf16 v[22:25], v[152:155], v[204:207], v[22:25]
	v_mfma_f32_16x16x32_bf16 v[26:29], v[156:159], v[200:203], v[26:29]
	v_mfma_f32_16x16x32_bf16 v[26:29], v[160:163], v[204:207], v[26:29]
	v_mfma_f32_16x16x32_bf16 v[18:21], v[164:167], v[200:203], v[18:21]
	v_mfma_f32_16x16x32_bf16 v[18:21], v[180:183], v[204:207], v[18:21]
	v_mfma_f32_16x16x32_bf16 v[2:5], v[164:167], v[208:211], v[2:5]
	v_mfma_f32_16x16x32_bf16 v[2:5], v[180:183], v[212:215], v[2:5]
	v_mfma_f32_16x16x32_bf16 v[10:13], v[156:159], v[208:211], v[10:13]
	v_mfma_f32_16x16x32_bf16 v[10:13], v[160:163], v[212:215], v[10:13]
	v_mfma_f32_16x16x32_bf16 v[6:9], v[148:151], v[208:211], v[6:9]
	v_mfma_f32_16x16x32_bf16 v[6:9], v[152:155], v[212:215], v[6:9]
	v_mfma_f32_16x16x32_bf16 v[14:17], v[130:133], v[208:211], v[14:17]
	v_mfma_f32_16x16x32_bf16 v[14:17], v[134:137], v[212:215], v[14:17]
	s_barrier
	s_add_i32 s52, s52, 2
	s_addk_i32 s8, 0x100
	s_addk_i32 s9, 0x100
	s_cmp_ge_i32 s52, s21
	s_cbranch_scc0 .LBB0_892
	s_and_b64 vcc, exec, s[48:49]
	s_cbranch_vccz .LBB0_895

.LBB0_1020:
	v_add_u32_e32 v142, 0x10000, v162
	v_add_u32_e32 v150, 0x14000, v162
	ds_read_b128 v[130:133], v142
	ds_read_b128 v[134:137], v142 offset:1024
	ds_read_b128 v[138:141], v142 offset:2048
	ds_read_b128 v[142:145], v142 offset:3072
	ds_read_b128 v[154:157], v150
	ds_read_b128 v[164:167], v150 offset:1024
	ds_read_b128 v[168:171], v150 offset:2048
	ds_read_b128 v[172:175], v150 offset:3072
	s_add_i32 s90, s6, 0x100
	s_add_i32 s7, s88, s6
	s_cmp_eq_u32 s81, s89
	s_cselect_b32 s91, 0, s90
	s_cselect_b32 s93, s87, s7
	s_add_i32 s91, s91, s70
	s_or_b32 s92, s91, 0x80
	s_add_i32 s6, s3, s6
	s_mov_b32 m0, s82
	s_add_i32 s7, s6, 0x20080
	ds_read_b128 v[176:179], v163
	ds_read_b128 v[180:183], v163 offset:1024
	ds_read_b128 v[184:187], v163 offset:2048
	ds_read_b128 v[188:191], v163 offset:3072
	ds_read_b128 v[192:195], v163 offset:4096
	ds_read_b128 v[196:199], v163 offset:5120
	ds_read_b128 v[200:203], v163 offset:6144
	ds_read_b128 v[204:207], v163 offset:7168
	buffer_load_dwordx4 v161, s[12:15], s7 offen lds
	s_add_i32 s6, s6, 0x30080
	s_mov_b32 m0, s83
	s_nop 0
	buffer_load_dwordx4 v161, s[12:15], s6 offen lds
	s_waitcnt vmcnt(8)
	s_waitcnt lgkmcnt(0)
	v_mfma_f32_16x16x32_bf16 v[126:129], v[130:133], v[176:179], v[126:129]
	s_barrier
	v_mfma_f32_16x16x32_bf16 v[126:129], v[134:137], v[180:183], v[126:129]
	v_mfma_f32_16x16x32_bf16 v[122:125], v[138:141], v[176:179], v[122:125]
	v_mfma_f32_16x16x32_bf16 v[122:125], v[142:145], v[180:183], v[122:125]
	v_mfma_f32_16x16x32_bf16 v[118:121], v[154:157], v[176:179], v[118:121]
	v_mfma_f32_16x16x32_bf16 v[118:121], v[164:167], v[180:183], v[118:121]
	v_mfma_f32_16x16x32_bf16 v[114:117], v[168:171], v[176:179], v[114:117]
	v_mfma_f32_16x16x32_bf16 v[114:117], v[172:175], v[180:183], v[114:117]
	v_mfma_f32_16x16x32_bf16 v[98:101], v[168:171], v[184:187], v[98:101]
	v_mfma_f32_16x16x32_bf16 v[98:101], v[172:175], v[188:191], v[98:101]
	v_mfma_f32_16x16x32_bf16 v[102:105], v[154:157], v[184:187], v[102:105]
	v_mfma_f32_16x16x32_bf16 v[102:105], v[164:167], v[188:191], v[102:105]
	v_mfma_f32_16x16x32_bf16 v[106:109], v[138:141], v[184:187], v[106:109]
	v_mfma_f32_16x16x32_bf16 v[106:109], v[142:145], v[188:191], v[106:109]
	v_mfma_f32_16x16x32_bf16 v[110:113], v[130:133], v[184:187], v[110:113]
	v_mfma_f32_16x16x32_bf16 v[110:113], v[134:137], v[188:191], v[110:113]
	v_mfma_f32_16x16x32_bf16 v[94:97], v[130:133], v[192:195], v[94:97]
	v_mfma_f32_16x16x32_bf16 v[94:97], v[134:137], v[196:199], v[94:97]
	v_mfma_f32_16x16x32_bf16 v[90:93], v[138:141], v[192:195], v[90:93]
	v_mfma_f32_16x16x32_bf16 v[90:93], v[142:145], v[196:199], v[90:93]
	v_mfma_f32_16x16x32_bf16 v[86:89], v[154:157], v[192:195], v[86:89]
	v_mfma_f32_16x16x32_bf16 v[86:89], v[164:167], v[196:199], v[86:89]
	v_mfma_f32_16x16x32_bf16 v[82:85], v[168:171], v[192:195], v[82:85]
	v_mfma_f32_16x16x32_bf16 v[82:85], v[172:175], v[196:199], v[82:85]
	v_mfma_f32_16x16x32_bf16 v[66:69], v[168:171], v[200:203], v[66:69]
	v_mfma_f32_16x16x32_bf16 v[66:69], v[172:175], v[204:207], v[66:69]
	v_mfma_f32_16x16x32_bf16 v[70:73], v[154:157], v[200:203], v[70:73]
	v_mfma_f32_16x16x32_bf16 v[70:73], v[164:167], v[204:207], v[70:73]
	v_mfma_f32_16x16x32_bf16 v[74:77], v[138:141], v[200:203], v[74:77]
	v_mfma_f32_16x16x32_bf16 v[74:77], v[142:145], v[204:207], v[74:77]
	v_mfma_f32_16x16x32_bf16 v[78:81], v[130:133], v[200:203], v[78:81]
	v_mfma_f32_16x16x32_bf16 v[78:81], v[134:137], v[204:207], v[78:81]
	s_barrier
	s_mov_b32 m0, s66
	s_mov_b32 s6, s14
	s_mov_b32 s7, s15
	ds_read_b128 v[176:179], v163 offset:16384
	ds_read_b128 v[180:183], v163 offset:17408
	ds_read_b128 v[184:187], v163 offset:18432
	ds_read_b128 v[188:191], v163 offset:19456
	ds_read_b128 v[192:195], v163 offset:20480
	ds_read_b128 v[196:199], v163 offset:21504
	ds_read_b128 v[200:203], v163 offset:22528
	ds_read_b128 v[204:207], v163 offset:23552
	buffer_load_dwordx4 v160, s[4:7], s93 offen lds
	s_add_i32 s94, s93, 0x10000
	s_mov_b32 m0, s67
	s_nop 0
	buffer_load_dwordx4 v160, s[4:7], s94 offen lds
	s_add_i32 s94, s93, 0x20000
	s_mov_b32 m0, s68
	s_nop 0
	buffer_load_dwordx4 v160, s[4:7], s94 offen lds
	s_add_i32 s94, s93, 0x30000
	s_mov_b32 m0, s69
	s_nop 0
	buffer_load_dwordx4 v160, s[4:7], s94 offen lds
	s_mov_b32 m0, s65
	s_add_i32 s94, s91, 0x10000
	buffer_load_dwordx4 v161, s[12:15], s91 offen lds
	s_mov_b32 m0, s71
	s_nop 0
	buffer_load_dwordx4 v161, s[12:15], s94 offen lds
	s_waitcnt vmcnt(8)
	s_waitcnt lgkmcnt(0)
	v_mfma_f32_16x16x32_bf16 v[62:65], v[130:133], v[176:179], v[62:65]
	s_barrier
	v_mfma_f32_16x16x32_bf16 v[62:65], v[134:137], v[180:183], v[62:65]
	v_mfma_f32_16x16x32_bf16 v[58:61], v[138:141], v[176:179], v[58:61]
	v_mfma_f32_16x16x32_bf16 v[58:61], v[142:145], v[180:183], v[58:61]
	v_mfma_f32_16x16x32_bf16 v[54:57], v[154:157], v[176:179], v[54:57]
	v_mfma_f32_16x16x32_bf16 v[54:57], v[164:167], v[180:183], v[54:57]
	v_mfma_f32_16x16x32_bf16 v[50:53], v[168:171], v[176:179], v[50:53]
	v_mfma_f32_16x16x32_bf16 v[50:53], v[172:175], v[180:183], v[50:53]
	v_mfma_f32_16x16x32_bf16 v[34:37], v[168:171], v[184:187], v[34:37]
	v_mfma_f32_16x16x32_bf16 v[34:37], v[172:175], v[188:191], v[34:37]
	v_mfma_f32_16x16x32_bf16 v[38:41], v[154:157], v[184:187], v[38:41]
	v_mfma_f32_16x16x32_bf16 v[38:41], v[164:167], v[188:191], v[38:41]
	v_mfma_f32_16x16x32_bf16 v[42:45], v[138:141], v[184:187], v[42:45]
	v_mfma_f32_16x16x32_bf16 v[42:45], v[142:145], v[188:191], v[42:45]
	v_mfma_f32_16x16x32_bf16 v[46:49], v[130:133], v[184:187], v[46:49]
	v_mfma_f32_16x16x32_bf16 v[46:49], v[134:137], v[188:191], v[46:49]
	v_mfma_f32_16x16x32_bf16 v[30:33], v[130:133], v[192:195], v[30:33]
	v_mfma_f32_16x16x32_bf16 v[30:33], v[134:137], v[196:199], v[30:33]
	v_mfma_f32_16x16x32_bf16 v[26:29], v[138:141], v[192:195], v[26:29]
	v_mfma_f32_16x16x32_bf16 v[26:29], v[142:145], v[196:199], v[26:29]
	v_mfma_f32_16x16x32_bf16 v[22:25], v[154:157], v[192:195], v[22:25]
	v_mfma_f32_16x16x32_bf16 v[22:25], v[164:167], v[196:199], v[22:25]
	v_mfma_f32_16x16x32_bf16 v[18:21], v[168:171], v[192:195], v[18:21]
	v_mfma_f32_16x16x32_bf16 v[18:21], v[172:175], v[196:199], v[18:21]
	v_mfma_f32_16x16x32_bf16 v[2:5], v[168:171], v[200:203], v[2:5]
	v_mfma_f32_16x16x32_bf16 v[2:5], v[172:175], v[204:207], v[2:5]
	v_mfma_f32_16x16x32_bf16 v[6:9], v[154:157], v[200:203], v[6:9]
	v_mfma_f32_16x16x32_bf16 v[6:9], v[164:167], v[204:207], v[6:9]
	v_mfma_f32_16x16x32_bf16 v[10:13], v[138:141], v[200:203], v[10:13]
	v_mfma_f32_16x16x32_bf16 v[10:13], v[142:145], v[204:207], v[10:13]
	v_mfma_f32_16x16x32_bf16 v[14:17], v[130:133], v[200:203], v[14:17]
	v_mfma_f32_16x16x32_bf16 v[14:17], v[134:137], v[204:207], v[14:17]
	s_barrier
	v_add_u32_e32 v142, 0x18000, v162
	v_add_u32_e32 v150, 0x1c000, v162
	ds_read_b128 v[130:133], v142
	ds_read_b128 v[134:137], v142 offset:1024
	ds_read_b128 v[138:141], v142 offset:2048
	ds_read_b128 v[142:145], v142 offset:3072
	ds_read_b128 v[154:157], v150
	ds_read_b128 v[164:167], v150 offset:1024
	ds_read_b128 v[168:171], v150 offset:2048
	ds_read_b128 v[172:175], v150 offset:3072
	s_mov_b32 m0, s72
	s_add_i32 s94, s91, 0x20000
	ds_read_b128 v[176:179], v163 offset:32768
	ds_read_b128 v[180:183], v163 offset:33792
	ds_read_b128 v[184:187], v163 offset:34816
	ds_read_b128 v[188:191], v163 offset:35840
	ds_read_b128 v[192:195], v163 offset:36864
	ds_read_b128 v[196:199], v163 offset:37888
	ds_read_b128 v[200:203], v163 offset:38912
	ds_read_b128 v[204:207], v163 offset:39936
	buffer_load_dwordx4 v161, s[12:15], s94 offen lds
	s_add_i32 s94, s91, 0x30000
	s_mov_b32 m0, s73
	s_nop 0
	buffer_load_dwordx4 v161, s[12:15], s94 offen lds
	s_waitcnt vmcnt(8)
	s_waitcnt lgkmcnt(0)
	v_mfma_f32_16x16x32_bf16 v[126:129], v[130:133], v[176:179], v[126:129]
	s_barrier
	v_mfma_f32_16x16x32_bf16 v[126:129], v[134:137], v[180:183], v[126:129]
	v_mfma_f32_16x16x32_bf16 v[122:125], v[138:141], v[176:179], v[122:125]
	v_mfma_f32_16x16x32_bf16 v[122:125], v[142:145], v[180:183], v[122:125]
	v_mfma_f32_16x16x32_bf16 v[118:121], v[154:157], v[176:179], v[118:121]
	v_mfma_f32_16x16x32_bf16 v[118:121], v[164:167], v[180:183], v[118:121]
	v_mfma_f32_16x16x32_bf16 v[114:117], v[168:171], v[176:179], v[114:117]
	v_mfma_f32_16x16x32_bf16 v[114:117], v[172:175], v[180:183], v[114:117]
	v_mfma_f32_16x16x32_bf16 v[98:101], v[168:171], v[184:187], v[98:101]
	v_mfma_f32_16x16x32_bf16 v[98:101], v[172:175], v[188:191], v[98:101]
	v_mfma_f32_16x16x32_bf16 v[102:105], v[154:157], v[184:187], v[102:105]
	v_mfma_f32_16x16x32_bf16 v[102:105], v[164:167], v[188:191], v[102:105]
	v_mfma_f32_16x16x32_bf16 v[106:109], v[138:141], v[184:187], v[106:109]
	v_mfma_f32_16x16x32_bf16 v[106:109], v[142:145], v[188:191], v[106:109]
	v_mfma_f32_16x16x32_bf16 v[110:113], v[130:133], v[184:187], v[110:113]
	v_mfma_f32_16x16x32_bf16 v[110:113], v[134:137], v[188:191], v[110:113]
	v_mfma_f32_16x16x32_bf16 v[94:97], v[130:133], v[192:195], v[94:97]
	v_mfma_f32_16x16x32_bf16 v[94:97], v[134:137], v[196:199], v[94:97]
	v_mfma_f32_16x16x32_bf16 v[90:93], v[138:141], v[192:195], v[90:93]
	v_mfma_f32_16x16x32_bf16 v[90:93], v[142:145], v[196:199], v[90:93]
	v_mfma_f32_16x16x32_bf16 v[86:89], v[154:157], v[192:195], v[86:89]
	v_mfma_f32_16x16x32_bf16 v[86:89], v[164:167], v[196:199], v[86:89]
	v_mfma_f32_16x16x32_bf16 v[82:85], v[168:171], v[192:195], v[82:85]
	v_mfma_f32_16x16x32_bf16 v[82:85], v[172:175], v[196:199], v[82:85]
	v_mfma_f32_16x16x32_bf16 v[66:69], v[168:171], v[200:203], v[66:69]
	v_mfma_f32_16x16x32_bf16 v[66:69], v[172:175], v[204:207], v[66:69]
	v_mfma_f32_16x16x32_bf16 v[70:73], v[154:157], v[200:203], v[70:73]
	v_mfma_f32_16x16x32_bf16 v[70:73], v[164:167], v[204:207], v[70:73]
	v_mfma_f32_16x16x32_bf16 v[74:77], v[138:141], v[200:203], v[74:77]
	v_mfma_f32_16x16x32_bf16 v[74:77], v[142:145], v[204:207], v[74:77]
	v_mfma_f32_16x16x32_bf16 v[78:81], v[130:133], v[200:203], v[78:81]
	v_mfma_f32_16x16x32_bf16 v[78:81], v[134:137], v[204:207], v[78:81]
	s_barrier
	s_mov_b32 m0, s74
	s_or_b32 s94, s93, 0x80
	ds_read_b128 v[176:179], v163 offset:49152
	ds_read_b128 v[180:183], v163 offset:50176
	ds_read_b128 v[184:187], v163 offset:51200
	ds_read_b128 v[188:191], v163 offset:52224
	ds_read_b128 v[192:195], v163 offset:53248
	ds_read_b128 v[196:199], v163 offset:54272
	ds_read_b128 v[200:203], v163 offset:55296
	ds_read_b128 v[204:207], v163 offset:56320
	buffer_load_dwordx4 v160, s[4:7], s94 offen lds
	s_add_i32 s94, s93, 0x10080
	s_mov_b32 m0, s75
	s_add_i32 s91, s91, 0x10080
	buffer_load_dwordx4 v160, s[4:7], s94 offen lds
	s_add_i32 s94, s93, 0x20080
	s_mov_b32 m0, s78
	s_add_i32 s93, s93, 0x30080
	buffer_load_dwordx4 v160, s[4:7], s94 offen lds
	s_mov_b32 m0, s79
	s_nop 0
	buffer_load_dwordx4 v160, s[4:7], s93 offen lds
	s_mov_b32 m0, s76
	s_nop 0
	buffer_load_dwordx4 v161, s[12:15], s92 offen lds
	s_mov_b32 m0, s77
	s_nop 0
	buffer_load_dwordx4 v161, s[12:15], s91 offen lds
	s_waitcnt vmcnt(8)
	s_waitcnt lgkmcnt(0)
	v_mfma_f32_16x16x32_bf16 v[62:65], v[130:133], v[176:179], v[62:65]
	s_barrier
	v_mfma_f32_16x16x32_bf16 v[62:65], v[134:137], v[180:183], v[62:65]
	v_mfma_f32_16x16x32_bf16 v[58:61], v[138:141], v[176:179], v[58:61]
	v_mfma_f32_16x16x32_bf16 v[58:61], v[142:145], v[180:183], v[58:61]
	v_mfma_f32_16x16x32_bf16 v[54:57], v[154:157], v[176:179], v[54:57]
	v_mfma_f32_16x16x32_bf16 v[54:57], v[164:167], v[180:183], v[54:57]
	v_mfma_f32_16x16x32_bf16 v[50:53], v[168:171], v[176:179], v[50:53]
	v_mfma_f32_16x16x32_bf16 v[50:53], v[172:175], v[180:183], v[50:53]
	v_mfma_f32_16x16x32_bf16 v[34:37], v[168:171], v[184:187], v[34:37]
	v_mfma_f32_16x16x32_bf16 v[34:37], v[172:175], v[188:191], v[34:37]
	v_mfma_f32_16x16x32_bf16 v[38:41], v[154:157], v[184:187], v[38:41]
	v_mfma_f32_16x16x32_bf16 v[38:41], v[164:167], v[188:191], v[38:41]
	v_mfma_f32_16x16x32_bf16 v[42:45], v[138:141], v[184:187], v[42:45]
	v_mfma_f32_16x16x32_bf16 v[42:45], v[142:145], v[188:191], v[42:45]
	v_mfma_f32_16x16x32_bf16 v[46:49], v[130:133], v[184:187], v[46:49]
	v_mfma_f32_16x16x32_bf16 v[46:49], v[134:137], v[188:191], v[46:49]
	v_mfma_f32_16x16x32_bf16 v[30:33], v[130:133], v[192:195], v[30:33]
	v_mfma_f32_16x16x32_bf16 v[30:33], v[134:137], v[196:199], v[30:33]
	v_mfma_f32_16x16x32_bf16 v[26:29], v[138:141], v[192:195], v[26:29]
	v_mfma_f32_16x16x32_bf16 v[26:29], v[142:145], v[196:199], v[26:29]
	v_mfma_f32_16x16x32_bf16 v[22:25], v[154:157], v[192:195], v[22:25]
	v_mfma_f32_16x16x32_bf16 v[22:25], v[164:167], v[196:199], v[22:25]
	v_mfma_f32_16x16x32_bf16 v[18:21], v[168:171], v[192:195], v[18:21]
	v_mfma_f32_16x16x32_bf16 v[18:21], v[172:175], v[196:199], v[18:21]
	v_mfma_f32_16x16x32_bf16 v[2:5], v[168:171], v[200:203], v[2:5]
	v_mfma_f32_16x16x32_bf16 v[2:5], v[172:175], v[204:207], v[2:5]
	v_mfma_f32_16x16x32_bf16 v[6:9], v[154:157], v[200:203], v[6:9]
	v_mfma_f32_16x16x32_bf16 v[6:9], v[164:167], v[204:207], v[6:9]
	v_mfma_f32_16x16x32_bf16 v[10:13], v[138:141], v[200:203], v[10:13]
	v_mfma_f32_16x16x32_bf16 v[10:13], v[142:145], v[204:207], v[10:13]
	v_mfma_f32_16x16x32_bf16 v[14:17], v[130:133], v[200:203], v[14:17]
	v_mfma_f32_16x16x32_bf16 v[14:17], v[134:137], v[204:207], v[14:17]
	s_barrier
	s_add_i32 s89, s89, 2
	s_cmp_ge_i32 s89, s63
	s_mov_b32 s6, s90
	s_cbranch_scc0 .LBB0_1020
	s_and_b64 vcc, exec, s[54:55]
	s_cbranch_vccz .LBB0_1023

.LBB0_1035:
	ds_read_b128 v[140:143], v134
	ds_read_b128 v[148:151], v134 offset:1024
	ds_read_b128 v[152:155], v134 offset:2048
	ds_read_b128 v[156:159], v134 offset:3072
	ds_read_b128 v[160:163], v135
	ds_read_b128 v[164:167], v135 offset:1024
	ds_read_b128 v[168:171], v135 offset:2048
	ds_read_b128 v[172:175], v135 offset:3072
	s_add_i32 s73, s70, 0xfffb8080
	s_cmp_eq_u32 s53, s72
	s_cselect_b32 s73, s68, s73
	s_cselect_b32 s75, s69, s71
	s_add_i32 s74, s73, 0x80
	s_add_i32 s76, s70, 0xfffe8000
	s_mov_b32 m0, s54
	ds_read_b128 v[176:179], v136
	ds_read_b128 v[180:183], v136 offset:1024
	ds_read_b128 v[184:187], v136 offset:2048
	ds_read_b128 v[188:191], v136 offset:3072
	ds_read_b128 v[192:195], v136 offset:4096
	ds_read_b128 v[196:199], v136 offset:5120
	ds_read_b128 v[200:203], v136 offset:6144
	ds_read_b128 v[204:207], v136 offset:7168
	buffer_load_dwordx4 v132, s[12:15], s76 offen lds
	s_mov_b32 m0, s55
	s_nop 0
	buffer_load_dwordx4 v132, s[12:15], s70 offen lds
	s_waitcnt vmcnt(8)
	s_waitcnt lgkmcnt(0)
	v_mfma_f32_16x16x32_bf16 v[126:129], v[140:143], v[176:179], v[126:129]
	s_barrier
	v_mfma_f32_16x16x32_bf16 v[126:129], v[148:151], v[180:183], v[126:129]
	v_mfma_f32_16x16x32_bf16 v[122:125], v[152:155], v[176:179], v[122:125]
	v_mfma_f32_16x16x32_bf16 v[122:125], v[156:159], v[180:183], v[122:125]
	v_mfma_f32_16x16x32_bf16 v[118:121], v[160:163], v[176:179], v[118:121]
	v_mfma_f32_16x16x32_bf16 v[118:121], v[164:167], v[180:183], v[118:121]
	v_mfma_f32_16x16x32_bf16 v[114:117], v[168:171], v[176:179], v[114:117]
	v_mfma_f32_16x16x32_bf16 v[114:117], v[172:175], v[180:183], v[114:117]
	v_mfma_f32_16x16x32_bf16 v[98:101], v[168:171], v[184:187], v[98:101]
	v_mfma_f32_16x16x32_bf16 v[98:101], v[172:175], v[188:191], v[98:101]
	v_mfma_f32_16x16x32_bf16 v[102:105], v[160:163], v[184:187], v[102:105]
	v_mfma_f32_16x16x32_bf16 v[102:105], v[164:167], v[188:191], v[102:105]
	v_mfma_f32_16x16x32_bf16 v[106:109], v[152:155], v[184:187], v[106:109]
	v_mfma_f32_16x16x32_bf16 v[106:109], v[156:159], v[188:191], v[106:109]
	v_mfma_f32_16x16x32_bf16 v[110:113], v[140:143], v[184:187], v[110:113]
	v_mfma_f32_16x16x32_bf16 v[110:113], v[148:151], v[188:191], v[110:113]
	v_mfma_f32_16x16x32_bf16 v[94:97], v[140:143], v[192:195], v[94:97]
	v_mfma_f32_16x16x32_bf16 v[94:97], v[148:151], v[196:199], v[94:97]
	v_mfma_f32_16x16x32_bf16 v[90:93], v[152:155], v[192:195], v[90:93]
	v_mfma_f32_16x16x32_bf16 v[90:93], v[156:159], v[196:199], v[90:93]
	v_mfma_f32_16x16x32_bf16 v[86:89], v[160:163], v[192:195], v[86:89]
	v_mfma_f32_16x16x32_bf16 v[86:89], v[164:167], v[196:199], v[86:89]
	v_mfma_f32_16x16x32_bf16 v[82:85], v[168:171], v[192:195], v[82:85]
	v_mfma_f32_16x16x32_bf16 v[82:85], v[172:175], v[196:199], v[82:85]
	v_mfma_f32_16x16x32_bf16 v[66:69], v[168:171], v[200:203], v[66:69]
	v_mfma_f32_16x16x32_bf16 v[66:69], v[172:175], v[204:207], v[66:69]
	v_mfma_f32_16x16x32_bf16 v[70:73], v[160:163], v[200:203], v[70:73]
	v_mfma_f32_16x16x32_bf16 v[70:73], v[164:167], v[204:207], v[70:73]
	v_mfma_f32_16x16x32_bf16 v[74:77], v[152:155], v[200:203], v[74:77]
	v_mfma_f32_16x16x32_bf16 v[74:77], v[156:159], v[204:207], v[74:77]
	v_mfma_f32_16x16x32_bf16 v[78:81], v[140:143], v[200:203], v[78:81]
	v_mfma_f32_16x16x32_bf16 v[78:81], v[148:151], v[204:207], v[78:81]
	s_barrier
	s_mov_b32 m0, s30
	ds_read_b128 v[176:179], v136 offset:16384
	ds_read_b128 v[180:183], v136 offset:17408
	ds_read_b128 v[184:187], v136 offset:18432
	ds_read_b128 v[188:191], v136 offset:19456
	ds_read_b128 v[192:195], v136 offset:20480
	ds_read_b128 v[196:199], v136 offset:21504
	ds_read_b128 v[200:203], v136 offset:22528
	ds_read_b128 v[204:207], v136 offset:23552
	buffer_load_dwordx4 v133, s[16:19], s75 offen lds
	s_add_i32 s76, s75, 0x200000
	s_mov_b32 m0, s31
	s_nop 0
	buffer_load_dwordx4 v133, s[16:19], s76 offen lds
	s_add_i32 s76, s75, 0x400000
	s_mov_b32 m0, s35
	s_nop 0
	buffer_load_dwordx4 v133, s[16:19], s76 offen lds
	s_add_i32 s76, s75, 0x600000
	s_mov_b32 m0, s42
	s_nop 0
	buffer_load_dwordx4 v133, s[16:19], s76 offen lds
	s_mov_b32 m0, s27
	s_add_i32 s76, s73, 0x18000
	buffer_load_dwordx4 v132, s[12:15], s73 offen lds
	s_mov_b32 m0, s43
	s_nop 0
	buffer_load_dwordx4 v132, s[12:15], s76 offen lds
	s_waitcnt vmcnt(8)
	s_waitcnt lgkmcnt(0)
	v_mfma_f32_16x16x32_bf16 v[62:65], v[140:143], v[176:179], v[62:65]
	s_barrier
	v_mfma_f32_16x16x32_bf16 v[62:65], v[148:151], v[180:183], v[62:65]
	v_mfma_f32_16x16x32_bf16 v[58:61], v[152:155], v[176:179], v[58:61]
	v_mfma_f32_16x16x32_bf16 v[58:61], v[156:159], v[180:183], v[58:61]
	v_mfma_f32_16x16x32_bf16 v[54:57], v[160:163], v[176:179], v[54:57]
	v_mfma_f32_16x16x32_bf16 v[54:57], v[164:167], v[180:183], v[54:57]
	v_mfma_f32_16x16x32_bf16 v[50:53], v[168:171], v[176:179], v[50:53]
	v_mfma_f32_16x16x32_bf16 v[50:53], v[172:175], v[180:183], v[50:53]
	v_mfma_f32_16x16x32_bf16 v[34:37], v[168:171], v[184:187], v[34:37]
	v_mfma_f32_16x16x32_bf16 v[34:37], v[172:175], v[188:191], v[34:37]
	v_mfma_f32_16x16x32_bf16 v[38:41], v[160:163], v[184:187], v[38:41]
	v_mfma_f32_16x16x32_bf16 v[38:41], v[164:167], v[188:191], v[38:41]
	v_mfma_f32_16x16x32_bf16 v[42:45], v[152:155], v[184:187], v[42:45]
	v_mfma_f32_16x16x32_bf16 v[42:45], v[156:159], v[188:191], v[42:45]
	v_mfma_f32_16x16x32_bf16 v[46:49], v[140:143], v[184:187], v[46:49]
	v_mfma_f32_16x16x32_bf16 v[46:49], v[148:151], v[188:191], v[46:49]
	v_mfma_f32_16x16x32_bf16 v[30:33], v[140:143], v[192:195], v[30:33]
	v_mfma_f32_16x16x32_bf16 v[30:33], v[148:151], v[196:199], v[30:33]
	v_mfma_f32_16x16x32_bf16 v[26:29], v[152:155], v[192:195], v[26:29]
	v_mfma_f32_16x16x32_bf16 v[26:29], v[156:159], v[196:199], v[26:29]
	v_mfma_f32_16x16x32_bf16 v[22:25], v[160:163], v[192:195], v[22:25]
	v_mfma_f32_16x16x32_bf16 v[22:25], v[164:167], v[196:199], v[22:25]
	v_mfma_f32_16x16x32_bf16 v[18:21], v[168:171], v[192:195], v[18:21]
	v_mfma_f32_16x16x32_bf16 v[18:21], v[172:175], v[196:199], v[18:21]
	v_mfma_f32_16x16x32_bf16 v[2:5], v[168:171], v[200:203], v[2:5]
	v_mfma_f32_16x16x32_bf16 v[2:5], v[172:175], v[204:207], v[2:5]
	v_mfma_f32_16x16x32_bf16 v[6:9], v[160:163], v[200:203], v[6:9]
	v_mfma_f32_16x16x32_bf16 v[6:9], v[164:167], v[204:207], v[6:9]
	v_mfma_f32_16x16x32_bf16 v[10:13], v[152:155], v[200:203], v[10:13]
	v_mfma_f32_16x16x32_bf16 v[10:13], v[156:159], v[204:207], v[10:13]
	v_mfma_f32_16x16x32_bf16 v[14:17], v[140:143], v[200:203], v[14:17]
	v_mfma_f32_16x16x32_bf16 v[14:17], v[148:151], v[204:207], v[14:17]
	s_barrier
	ds_read_b128 v[140:143], v137
	ds_read_b128 v[148:151], v137 offset:1024
	ds_read_b128 v[152:155], v137 offset:2048
	ds_read_b128 v[156:159], v137 offset:3072
	ds_read_b128 v[160:163], v138
	ds_read_b128 v[164:167], v138 offset:1024
	ds_read_b128 v[168:171], v138 offset:2048
	ds_read_b128 v[172:175], v138 offset:3072
	s_mov_b32 m0, s44
	s_add_i32 s76, s73, 0x30000
	ds_read_b128 v[176:179], v136 offset:32768
	ds_read_b128 v[180:183], v136 offset:33792
	ds_read_b128 v[184:187], v136 offset:34816
	ds_read_b128 v[188:191], v136 offset:35840
	ds_read_b128 v[192:195], v136 offset:36864
	ds_read_b128 v[196:199], v136 offset:37888
	ds_read_b128 v[200:203], v136 offset:38912
	ds_read_b128 v[204:207], v136 offset:39936
	buffer_load_dwordx4 v132, s[12:15], s76 offen lds
	s_add_i32 s76, s73, 0x48000
	s_mov_b32 m0, s45
	s_nop 0
	buffer_load_dwordx4 v132, s[12:15], s76 offen lds
	s_waitcnt vmcnt(8)
	s_waitcnt lgkmcnt(0)
	v_mfma_f32_16x16x32_bf16 v[126:129], v[140:143], v[176:179], v[126:129]
	s_barrier
	v_mfma_f32_16x16x32_bf16 v[126:129], v[148:151], v[180:183], v[126:129]
	v_mfma_f32_16x16x32_bf16 v[122:125], v[152:155], v[176:179], v[122:125]
	v_mfma_f32_16x16x32_bf16 v[122:125], v[156:159], v[180:183], v[122:125]
	v_mfma_f32_16x16x32_bf16 v[118:121], v[160:163], v[176:179], v[118:121]
	v_mfma_f32_16x16x32_bf16 v[118:121], v[164:167], v[180:183], v[118:121]
	v_mfma_f32_16x16x32_bf16 v[114:117], v[168:171], v[176:179], v[114:117]
	v_mfma_f32_16x16x32_bf16 v[114:117], v[172:175], v[180:183], v[114:117]
	v_mfma_f32_16x16x32_bf16 v[98:101], v[168:171], v[184:187], v[98:101]
	v_mfma_f32_16x16x32_bf16 v[98:101], v[172:175], v[188:191], v[98:101]
	v_mfma_f32_16x16x32_bf16 v[102:105], v[160:163], v[184:187], v[102:105]
	v_mfma_f32_16x16x32_bf16 v[102:105], v[164:167], v[188:191], v[102:105]
	v_mfma_f32_16x16x32_bf16 v[106:109], v[152:155], v[184:187], v[106:109]
	v_mfma_f32_16x16x32_bf16 v[106:109], v[156:159], v[188:191], v[106:109]
	v_mfma_f32_16x16x32_bf16 v[110:113], v[140:143], v[184:187], v[110:113]
	v_mfma_f32_16x16x32_bf16 v[110:113], v[148:151], v[188:191], v[110:113]
	v_mfma_f32_16x16x32_bf16 v[94:97], v[140:143], v[192:195], v[94:97]
	v_mfma_f32_16x16x32_bf16 v[94:97], v[148:151], v[196:199], v[94:97]
	v_mfma_f32_16x16x32_bf16 v[90:93], v[152:155], v[192:195], v[90:93]
	v_mfma_f32_16x16x32_bf16 v[90:93], v[156:159], v[196:199], v[90:93]
	v_mfma_f32_16x16x32_bf16 v[86:89], v[160:163], v[192:195], v[86:89]
	v_mfma_f32_16x16x32_bf16 v[86:89], v[164:167], v[196:199], v[86:89]
	v_mfma_f32_16x16x32_bf16 v[82:85], v[168:171], v[192:195], v[82:85]
	v_mfma_f32_16x16x32_bf16 v[82:85], v[172:175], v[196:199], v[82:85]
	v_mfma_f32_16x16x32_bf16 v[66:69], v[168:171], v[200:203], v[66:69]
	v_mfma_f32_16x16x32_bf16 v[66:69], v[172:175], v[204:207], v[66:69]
	v_mfma_f32_16x16x32_bf16 v[70:73], v[160:163], v[200:203], v[70:73]
	v_mfma_f32_16x16x32_bf16 v[70:73], v[164:167], v[204:207], v[70:73]
	v_mfma_f32_16x16x32_bf16 v[74:77], v[152:155], v[200:203], v[74:77]
	v_mfma_f32_16x16x32_bf16 v[74:77], v[156:159], v[204:207], v[74:77]
	v_mfma_f32_16x16x32_bf16 v[78:81], v[140:143], v[200:203], v[78:81]
	v_mfma_f32_16x16x32_bf16 v[78:81], v[148:151], v[204:207], v[78:81]
	s_barrier
	s_mov_b32 m0, s46
	s_add_i32 s76, s75, 0x80
	ds_read_b128 v[176:179], v136 offset:49152
	ds_read_b128 v[180:183], v136 offset:50176
	ds_read_b128 v[184:187], v136 offset:51200
	ds_read_b128 v[188:191], v136 offset:52224
	ds_read_b128 v[192:195], v136 offset:53248
	ds_read_b128 v[196:199], v136 offset:54272
	ds_read_b128 v[200:203], v136 offset:55296
	ds_read_b128 v[204:207], v136 offset:56320
	buffer_load_dwordx4 v133, s[16:19], s76 offen lds
	s_add_i32 s76, s75, 0x200080
	s_mov_b32 m0, s47
	s_add_i32 s73, s73, 0x18080
	buffer_load_dwordx4 v133, s[16:19], s76 offen lds
	s_add_i32 s76, s75, 0x400080
	s_mov_b32 m0, s50
	s_add_i32 s75, s75, 0x600080
	buffer_load_dwordx4 v133, s[16:19], s76 offen lds
	s_mov_b32 m0, s51
	s_nop 0
	buffer_load_dwordx4 v133, s[16:19], s75 offen lds
	s_mov_b32 m0, s48
	s_nop 0
	buffer_load_dwordx4 v132, s[12:15], s74 offen lds
	s_mov_b32 m0, s49
	s_nop 0
	buffer_load_dwordx4 v132, s[12:15], s73 offen lds
	s_waitcnt vmcnt(8)
	s_waitcnt lgkmcnt(0)
	v_mfma_f32_16x16x32_bf16 v[62:65], v[140:143], v[176:179], v[62:65]
	s_barrier
	v_mfma_f32_16x16x32_bf16 v[62:65], v[148:151], v[180:183], v[62:65]
	v_mfma_f32_16x16x32_bf16 v[58:61], v[152:155], v[176:179], v[58:61]
	v_mfma_f32_16x16x32_bf16 v[58:61], v[156:159], v[180:183], v[58:61]
	v_mfma_f32_16x16x32_bf16 v[54:57], v[160:163], v[176:179], v[54:57]
	v_mfma_f32_16x16x32_bf16 v[54:57], v[164:167], v[180:183], v[54:57]
	v_mfma_f32_16x16x32_bf16 v[50:53], v[168:171], v[176:179], v[50:53]
	v_mfma_f32_16x16x32_bf16 v[50:53], v[172:175], v[180:183], v[50:53]
	v_mfma_f32_16x16x32_bf16 v[34:37], v[168:171], v[184:187], v[34:37]
	v_mfma_f32_16x16x32_bf16 v[34:37], v[172:175], v[188:191], v[34:37]
	v_mfma_f32_16x16x32_bf16 v[38:41], v[160:163], v[184:187], v[38:41]
	v_mfma_f32_16x16x32_bf16 v[38:41], v[164:167], v[188:191], v[38:41]
	v_mfma_f32_16x16x32_bf16 v[42:45], v[152:155], v[184:187], v[42:45]
	v_mfma_f32_16x16x32_bf16 v[42:45], v[156:159], v[188:191], v[42:45]
	v_mfma_f32_16x16x32_bf16 v[46:49], v[140:143], v[184:187], v[46:49]
	v_mfma_f32_16x16x32_bf16 v[46:49], v[148:151], v[188:191], v[46:49]
	v_mfma_f32_16x16x32_bf16 v[30:33], v[140:143], v[192:195], v[30:33]
	v_mfma_f32_16x16x32_bf16 v[30:33], v[148:151], v[196:199], v[30:33]
	v_mfma_f32_16x16x32_bf16 v[26:29], v[152:155], v[192:195], v[26:29]
	v_mfma_f32_16x16x32_bf16 v[26:29], v[156:159], v[196:199], v[26:29]
	v_mfma_f32_16x16x32_bf16 v[22:25], v[160:163], v[192:195], v[22:25]
	v_mfma_f32_16x16x32_bf16 v[22:25], v[164:167], v[196:199], v[22:25]
	v_mfma_f32_16x16x32_bf16 v[18:21], v[168:171], v[192:195], v[18:21]
	v_mfma_f32_16x16x32_bf16 v[18:21], v[172:175], v[196:199], v[18:21]
	v_mfma_f32_16x16x32_bf16 v[2:5], v[168:171], v[200:203], v[2:5]
	v_mfma_f32_16x16x32_bf16 v[2:5], v[172:175], v[204:207], v[2:5]
	v_mfma_f32_16x16x32_bf16 v[6:9], v[160:163], v[200:203], v[6:9]
	v_mfma_f32_16x16x32_bf16 v[6:9], v[164:167], v[204:207], v[6:9]
	v_mfma_f32_16x16x32_bf16 v[10:13], v[152:155], v[200:203], v[10:13]
	v_mfma_f32_16x16x32_bf16 v[10:13], v[156:159], v[204:207], v[10:13]
	v_mfma_f32_16x16x32_bf16 v[14:17], v[140:143], v[200:203], v[14:17]
	v_mfma_f32_16x16x32_bf16 v[14:17], v[148:151], v[204:207], v[14:17]
	s_barrier
	s_add_i32 s72, s72, 2
	s_addk_i32 s70, 0x100
	s_addk_i32 s71, 0x100
	s_cmp_ge_i32 s72, s21
	s_cbranch_scc0 .LBB0_1035

.LBB0_1050:
	ds_read_b128 v[132:135], v142
	ds_read_b128 v[136:139], v142 offset:1024
	ds_read_b128 v[148:151], v142 offset:2048
	ds_read_b128 v[152:155], v142 offset:3072
	ds_read_b128 v[156:159], v143
	ds_read_b128 v[160:163], v143 offset:1024
	ds_read_b128 v[164:167], v143 offset:2048
	ds_read_b128 v[168:171], v143 offset:3072
	s_add_i32 s18, s61, 0xfff40080
	s_cmp_eq_u32 s54, s62
	s_cselect_b32 s64, s35, s18
	s_add_i32 s63, s64, 0x80
	s_add_i32 s18, s61, 0xfffc0000
	s_mov_b32 m0, s55
	ds_read_b128 v[172:175], v144
	ds_read_b128 v[176:179], v144 offset:1024
	ds_read_b128 v[180:183], v144 offset:2048
	ds_read_b128 v[184:187], v144 offset:3072
	ds_read_b128 v[188:191], v144 offset:4096
	ds_read_b128 v[192:195], v144 offset:5120
	ds_read_b128 v[196:199], v144 offset:6144
	ds_read_b128 v[200:203], v144 offset:7168
	buffer_load_dwordx4 v140, s[12:15], s18 offen lds
	s_mov_b32 m0, s56
	s_nop 0
	buffer_load_dwordx4 v140, s[12:15], s61 offen lds
	s_waitcnt vmcnt(8)
	s_waitcnt lgkmcnt(0)
	v_mfma_f32_16x16x32_bf16 v[126:129], v[132:135], v[172:175], v[126:129]
	s_barrier
	v_mfma_f32_16x16x32_bf16 v[126:129], v[136:139], v[176:179], v[126:129]
	v_mfma_f32_16x16x32_bf16 v[122:125], v[148:151], v[172:175], v[122:125]
	v_mfma_f32_16x16x32_bf16 v[122:125], v[152:155], v[176:179], v[122:125]
	v_mfma_f32_16x16x32_bf16 v[118:121], v[156:159], v[172:175], v[118:121]
	v_mfma_f32_16x16x32_bf16 v[118:121], v[160:163], v[176:179], v[118:121]
	v_mfma_f32_16x16x32_bf16 v[114:117], v[164:167], v[172:175], v[114:117]
	v_mfma_f32_16x16x32_bf16 v[114:117], v[168:171], v[176:179], v[114:117]
	v_mfma_f32_16x16x32_bf16 v[98:101], v[164:167], v[180:183], v[98:101]
	v_mfma_f32_16x16x32_bf16 v[98:101], v[168:171], v[184:187], v[98:101]
	v_mfma_f32_16x16x32_bf16 v[102:105], v[156:159], v[180:183], v[102:105]
	v_mfma_f32_16x16x32_bf16 v[102:105], v[160:163], v[184:187], v[102:105]
	v_mfma_f32_16x16x32_bf16 v[106:109], v[148:151], v[180:183], v[106:109]
	v_mfma_f32_16x16x32_bf16 v[106:109], v[152:155], v[184:187], v[106:109]
	v_mfma_f32_16x16x32_bf16 v[110:113], v[132:135], v[180:183], v[110:113]
	v_mfma_f32_16x16x32_bf16 v[110:113], v[136:139], v[184:187], v[110:113]
	v_mfma_f32_16x16x32_bf16 v[94:97], v[132:135], v[188:191], v[94:97]
	v_mfma_f32_16x16x32_bf16 v[94:97], v[136:139], v[192:195], v[94:97]
	v_mfma_f32_16x16x32_bf16 v[90:93], v[148:151], v[188:191], v[90:93]
	v_mfma_f32_16x16x32_bf16 v[90:93], v[152:155], v[192:195], v[90:93]
	v_mfma_f32_16x16x32_bf16 v[86:89], v[156:159], v[188:191], v[86:89]
	v_mfma_f32_16x16x32_bf16 v[86:89], v[160:163], v[192:195], v[86:89]
	v_mfma_f32_16x16x32_bf16 v[82:85], v[164:167], v[188:191], v[82:85]
	v_mfma_f32_16x16x32_bf16 v[82:85], v[168:171], v[192:195], v[82:85]
	v_mfma_f32_16x16x32_bf16 v[66:69], v[164:167], v[196:199], v[66:69]
	v_mfma_f32_16x16x32_bf16 v[66:69], v[168:171], v[200:203], v[66:69]
	v_mfma_f32_16x16x32_bf16 v[70:73], v[156:159], v[196:199], v[70:73]
	v_mfma_f32_16x16x32_bf16 v[70:73], v[160:163], v[200:203], v[70:73]
	v_mfma_f32_16x16x32_bf16 v[74:77], v[148:151], v[196:199], v[74:77]
	v_mfma_f32_16x16x32_bf16 v[74:77], v[152:155], v[200:203], v[74:77]
	v_mfma_f32_16x16x32_bf16 v[78:81], v[132:135], v[196:199], v[78:81]
	v_mfma_f32_16x16x32_bf16 v[78:81], v[136:139], v[200:203], v[78:81]
	s_barrier
	s_mov_b32 m0, s25
	s_mov_b32 s18, s14
	s_mov_b32 s19, s15
	ds_read_b128 v[172:175], v144 offset:16384
	ds_read_b128 v[176:179], v144 offset:17408
	ds_read_b128 v[180:183], v144 offset:18432
	ds_read_b128 v[184:187], v144 offset:19456
	ds_read_b128 v[188:191], v144 offset:20480
	ds_read_b128 v[192:195], v144 offset:21504
	ds_read_b128 v[196:199], v144 offset:22528
	ds_read_b128 v[200:203], v144 offset:23552
	buffer_load_dwordx4 v141, s[16:19], s64 offen lds
	s_add_i32 s65, s64, 0x40000
	s_mov_b32 m0, s27
	s_add_i32 s66, s64, 0x80000
	buffer_load_dwordx4 v141, s[16:19], s65 offen lds
	s_mov_b32 m0, s30
	s_add_i32 s67, s64, 0xc0000
	buffer_load_dwordx4 v141, s[16:19], s66 offen lds
	s_mov_b32 m0, s31
	s_nop 0
	buffer_load_dwordx4 v141, s[16:19], s67 offen lds
	s_mov_b32 m0, s21
	s_nop 0
	buffer_load_dwordx4 v140, s[12:15], s64 offen lds
	s_mov_b32 m0, s38
	s_nop 0
	buffer_load_dwordx4 v140, s[12:15], s65 offen lds
	s_waitcnt vmcnt(8)
	s_waitcnt lgkmcnt(0)
	v_mfma_f32_16x16x32_bf16 v[62:65], v[132:135], v[172:175], v[62:65]
	s_barrier
	v_mfma_f32_16x16x32_bf16 v[62:65], v[136:139], v[176:179], v[62:65]
	v_mfma_f32_16x16x32_bf16 v[58:61], v[148:151], v[172:175], v[58:61]
	v_mfma_f32_16x16x32_bf16 v[58:61], v[152:155], v[176:179], v[58:61]
	v_mfma_f32_16x16x32_bf16 v[54:57], v[156:159], v[172:175], v[54:57]
	v_mfma_f32_16x16x32_bf16 v[54:57], v[160:163], v[176:179], v[54:57]
	v_mfma_f32_16x16x32_bf16 v[50:53], v[164:167], v[172:175], v[50:53]
	v_mfma_f32_16x16x32_bf16 v[50:53], v[168:171], v[176:179], v[50:53]
	v_mfma_f32_16x16x32_bf16 v[34:37], v[164:167], v[180:183], v[34:37]
	v_mfma_f32_16x16x32_bf16 v[34:37], v[168:171], v[184:187], v[34:37]
	v_mfma_f32_16x16x32_bf16 v[38:41], v[156:159], v[180:183], v[38:41]
	v_mfma_f32_16x16x32_bf16 v[38:41], v[160:163], v[184:187], v[38:41]
	v_mfma_f32_16x16x32_bf16 v[42:45], v[148:151], v[180:183], v[42:45]
	v_mfma_f32_16x16x32_bf16 v[42:45], v[152:155], v[184:187], v[42:45]
	v_mfma_f32_16x16x32_bf16 v[46:49], v[132:135], v[180:183], v[46:49]
	v_mfma_f32_16x16x32_bf16 v[46:49], v[136:139], v[184:187], v[46:49]
	v_mfma_f32_16x16x32_bf16 v[30:33], v[132:135], v[188:191], v[30:33]
	v_mfma_f32_16x16x32_bf16 v[30:33], v[136:139], v[192:195], v[30:33]
	v_mfma_f32_16x16x32_bf16 v[26:29], v[148:151], v[188:191], v[26:29]
	v_mfma_f32_16x16x32_bf16 v[26:29], v[152:155], v[192:195], v[26:29]
	v_mfma_f32_16x16x32_bf16 v[22:25], v[156:159], v[188:191], v[22:25]
	v_mfma_f32_16x16x32_bf16 v[22:25], v[160:163], v[192:195], v[22:25]
	v_mfma_f32_16x16x32_bf16 v[18:21], v[164:167], v[188:191], v[18:21]
	v_mfma_f32_16x16x32_bf16 v[18:21], v[168:171], v[192:195], v[18:21]
	v_mfma_f32_16x16x32_bf16 v[2:5], v[164:167], v[196:199], v[2:5]
	v_mfma_f32_16x16x32_bf16 v[2:5], v[168:171], v[200:203], v[2:5]
	v_mfma_f32_16x16x32_bf16 v[6:9], v[156:159], v[196:199], v[6:9]
	v_mfma_f32_16x16x32_bf16 v[6:9], v[160:163], v[200:203], v[6:9]
	v_mfma_f32_16x16x32_bf16 v[10:13], v[148:151], v[196:199], v[10:13]
	v_mfma_f32_16x16x32_bf16 v[10:13], v[152:155], v[200:203], v[10:13]
	v_mfma_f32_16x16x32_bf16 v[14:17], v[132:135], v[196:199], v[14:17]
	v_mfma_f32_16x16x32_bf16 v[14:17], v[136:139], v[200:203], v[14:17]
	s_barrier
	ds_read_b128 v[132:135], v145
	ds_read_b128 v[136:139], v145 offset:1024
	ds_read_b128 v[148:151], v145 offset:2048
	ds_read_b128 v[152:155], v145 offset:3072
	ds_read_b128 v[156:159], v147
	ds_read_b128 v[160:163], v147 offset:1024
	ds_read_b128 v[164:167], v147 offset:2048
	ds_read_b128 v[168:171], v147 offset:3072
	s_mov_b32 m0, s39
	ds_read_b128 v[172:175], v144 offset:32768
	ds_read_b128 v[176:179], v144 offset:33792
	ds_read_b128 v[180:183], v144 offset:34816
	ds_read_b128 v[184:187], v144 offset:35840
	ds_read_b128 v[188:191], v144 offset:36864
	ds_read_b128 v[192:195], v144 offset:37888
	ds_read_b128 v[196:199], v144 offset:38912
	ds_read_b128 v[200:203], v144 offset:39936
	buffer_load_dwordx4 v140, s[12:15], s66 offen lds
	s_mov_b32 m0, s40
	s_nop 0
	buffer_load_dwordx4 v140, s[12:15], s67 offen lds
	s_waitcnt vmcnt(8)
	s_waitcnt lgkmcnt(0)
	v_mfma_f32_16x16x32_bf16 v[126:129], v[132:135], v[172:175], v[126:129]
	s_barrier
	v_mfma_f32_16x16x32_bf16 v[126:129], v[136:139], v[176:179], v[126:129]
	v_mfma_f32_16x16x32_bf16 v[122:125], v[148:151], v[172:175], v[122:125]
	v_mfma_f32_16x16x32_bf16 v[122:125], v[152:155], v[176:179], v[122:125]
	v_mfma_f32_16x16x32_bf16 v[118:121], v[156:159], v[172:175], v[118:121]
	v_mfma_f32_16x16x32_bf16 v[118:121], v[160:163], v[176:179], v[118:121]
	v_mfma_f32_16x16x32_bf16 v[114:117], v[164:167], v[172:175], v[114:117]
	v_mfma_f32_16x16x32_bf16 v[114:117], v[168:171], v[176:179], v[114:117]
	v_mfma_f32_16x16x32_bf16 v[98:101], v[164:167], v[180:183], v[98:101]
	v_mfma_f32_16x16x32_bf16 v[98:101], v[168:171], v[184:187], v[98:101]
	v_mfma_f32_16x16x32_bf16 v[102:105], v[156:159], v[180:183], v[102:105]
	v_mfma_f32_16x16x32_bf16 v[102:105], v[160:163], v[184:187], v[102:105]
	v_mfma_f32_16x16x32_bf16 v[106:109], v[148:151], v[180:183], v[106:109]
	v_mfma_f32_16x16x32_bf16 v[106:109], v[152:155], v[184:187], v[106:109]
	v_mfma_f32_16x16x32_bf16 v[110:113], v[132:135], v[180:183], v[110:113]
	v_mfma_f32_16x16x32_bf16 v[110:113], v[136:139], v[184:187], v[110:113]
	v_mfma_f32_16x16x32_bf16 v[94:97], v[132:135], v[188:191], v[94:97]
	v_mfma_f32_16x16x32_bf16 v[94:97], v[136:139], v[192:195], v[94:97]
	v_mfma_f32_16x16x32_bf16 v[90:93], v[148:151], v[188:191], v[90:93]
	v_mfma_f32_16x16x32_bf16 v[90:93], v[152:155], v[192:195], v[90:93]
	v_mfma_f32_16x16x32_bf16 v[86:89], v[156:159], v[188:191], v[86:89]
	v_mfma_f32_16x16x32_bf16 v[86:89], v[160:163], v[192:195], v[86:89]
	v_mfma_f32_16x16x32_bf16 v[82:85], v[164:167], v[188:191], v[82:85]
	v_mfma_f32_16x16x32_bf16 v[82:85], v[168:171], v[192:195], v[82:85]
	v_mfma_f32_16x16x32_bf16 v[66:69], v[164:167], v[196:199], v[66:69]
	v_mfma_f32_16x16x32_bf16 v[66:69], v[168:171], v[200:203], v[66:69]
	v_mfma_f32_16x16x32_bf16 v[70:73], v[156:159], v[196:199], v[70:73]
	v_mfma_f32_16x16x32_bf16 v[70:73], v[160:163], v[200:203], v[70:73]
	v_mfma_f32_16x16x32_bf16 v[74:77], v[148:151], v[196:199], v[74:77]
	v_mfma_f32_16x16x32_bf16 v[74:77], v[152:155], v[200:203], v[74:77]
	v_mfma_f32_16x16x32_bf16 v[78:81], v[132:135], v[196:199], v[78:81]
	v_mfma_f32_16x16x32_bf16 v[78:81], v[136:139], v[200:203], v[78:81]
	s_barrier
	s_mov_b32 m0, s48
	ds_read_b128 v[172:175], v144 offset:49152
	ds_read_b128 v[176:179], v144 offset:50176
	ds_read_b128 v[180:183], v144 offset:51200
	ds_read_b128 v[184:187], v144 offset:52224
	ds_read_b128 v[188:191], v144 offset:53248
	ds_read_b128 v[192:195], v144 offset:54272
	ds_read_b128 v[196:199], v144 offset:55296
	ds_read_b128 v[200:203], v144 offset:56320
	buffer_load_dwordx4 v141, s[16:19], s63 offen lds
	s_add_i32 s65, s64, 0x40080
	s_mov_b32 m0, s49
	s_add_i32 s66, s64, 0x80080
	buffer_load_dwordx4 v141, s[16:19], s65 offen lds
	s_mov_b32 m0, s52
	s_add_i32 s64, s64, 0xc0080
	buffer_load_dwordx4 v141, s[16:19], s66 offen lds
	s_mov_b32 m0, s53
	s_nop 0
	buffer_load_dwordx4 v141, s[16:19], s64 offen lds
	s_mov_b32 m0, s50
	s_nop 0
	buffer_load_dwordx4 v140, s[12:15], s63 offen lds
	s_mov_b32 m0, s51
	s_nop 0
	buffer_load_dwordx4 v140, s[12:15], s65 offen lds
	s_waitcnt vmcnt(8)
	s_waitcnt lgkmcnt(0)
	v_mfma_f32_16x16x32_bf16 v[62:65], v[132:135], v[172:175], v[62:65]
	s_barrier
	v_mfma_f32_16x16x32_bf16 v[62:65], v[136:139], v[176:179], v[62:65]
	v_mfma_f32_16x16x32_bf16 v[58:61], v[148:151], v[172:175], v[58:61]
	v_mfma_f32_16x16x32_bf16 v[58:61], v[152:155], v[176:179], v[58:61]
	v_mfma_f32_16x16x32_bf16 v[54:57], v[156:159], v[172:175], v[54:57]
	v_mfma_f32_16x16x32_bf16 v[54:57], v[160:163], v[176:179], v[54:57]
	v_mfma_f32_16x16x32_bf16 v[50:53], v[164:167], v[172:175], v[50:53]
	v_mfma_f32_16x16x32_bf16 v[50:53], v[168:171], v[176:179], v[50:53]
	v_mfma_f32_16x16x32_bf16 v[34:37], v[164:167], v[180:183], v[34:37]
	v_mfma_f32_16x16x32_bf16 v[34:37], v[168:171], v[184:187], v[34:37]
	v_mfma_f32_16x16x32_bf16 v[38:41], v[156:159], v[180:183], v[38:41]
	v_mfma_f32_16x16x32_bf16 v[38:41], v[160:163], v[184:187], v[38:41]
	v_mfma_f32_16x16x32_bf16 v[42:45], v[148:151], v[180:183], v[42:45]
	v_mfma_f32_16x16x32_bf16 v[42:45], v[152:155], v[184:187], v[42:45]
	v_mfma_f32_16x16x32_bf16 v[46:49], v[132:135], v[180:183], v[46:49]
	v_mfma_f32_16x16x32_bf16 v[46:49], v[136:139], v[184:187], v[46:49]
	v_mfma_f32_16x16x32_bf16 v[30:33], v[132:135], v[188:191], v[30:33]
	v_mfma_f32_16x16x32_bf16 v[30:33], v[136:139], v[192:195], v[30:33]
	v_mfma_f32_16x16x32_bf16 v[26:29], v[148:151], v[188:191], v[26:29]
	v_mfma_f32_16x16x32_bf16 v[26:29], v[152:155], v[192:195], v[26:29]
	v_mfma_f32_16x16x32_bf16 v[22:25], v[156:159], v[188:191], v[22:25]
	v_mfma_f32_16x16x32_bf16 v[22:25], v[160:163], v[192:195], v[22:25]
	v_mfma_f32_16x16x32_bf16 v[18:21], v[164:167], v[188:191], v[18:21]
	v_mfma_f32_16x16x32_bf16 v[18:21], v[168:171], v[192:195], v[18:21]
	v_mfma_f32_16x16x32_bf16 v[2:5], v[164:167], v[196:199], v[2:5]
	v_mfma_f32_16x16x32_bf16 v[2:5], v[168:171], v[200:203], v[2:5]
	v_mfma_f32_16x16x32_bf16 v[6:9], v[156:159], v[196:199], v[6:9]
	v_mfma_f32_16x16x32_bf16 v[6:9], v[160:163], v[200:203], v[6:9]
	v_mfma_f32_16x16x32_bf16 v[10:13], v[148:151], v[196:199], v[10:13]
	v_mfma_f32_16x16x32_bf16 v[10:13], v[152:155], v[200:203], v[10:13]
	v_mfma_f32_16x16x32_bf16 v[14:17], v[132:135], v[196:199], v[14:17]
	v_mfma_f32_16x16x32_bf16 v[14:17], v[136:139], v[200:203], v[14:17]
	s_barrier
	s_add_i32 s62, s62, 2
	s_addk_i32 s61, 0x100
	s_cmp_ge_i32 s62, s3
	s_cbranch_scc0 .LBB0_1050

.LBB0_1181:
	v_add_u32_e32 v2, 0x10000, v232
	ds_read_b128 v[134:137], v2
	ds_read_b128 v[138:141], v2 offset:1024
	ds_read_b128 v[142:145], v2 offset:2048
	ds_read_b128 v[146:149], v2 offset:3072
	v_add_u32_e32 v2, 0x14000, v232
	ds_read_b128 v[150:153], v2
	ds_read_b128 v[154:157], v2 offset:1024
	ds_read_b128 v[158:161], v2 offset:2048
	ds_read_b128 v[162:165], v2 offset:3072
	s_add_i32 s50, s47, s90
	s_and_b64 s[18:19], exec, s[18:19]
	s_cselect_b32 s51, s88, s50
	s_add_i32 s50, s92, 0x80
	s_or_b32 s52, s51, 0x80
	s_add_i32 s18, s89, s93
	s_add_i32 s94, s94, 0x1bfffc80
	s_cmp_lt_u32 s91, 8
	s_cselect_b32 s18, s18, s94
	s_mov_b32 m0, s74
	s_add_i32 s19, s18, 0x80000
	ds_read_b128 v[166:169], v233
	ds_read_b128 v[170:173], v233 offset:1024
	ds_read_b128 v[174:177], v233 offset:2048
	ds_read_b128 v[178:181], v233 offset:3072
	ds_read_b128 v[182:185], v233 offset:4096
	ds_read_b128 v[186:189], v233 offset:5120
	ds_read_b128 v[190:193], v233 offset:6144
	ds_read_b128 v[194:197], v233 offset:7168
	buffer_load_dwordx4 v230, s[12:15], s19 offen lds
	s_add_i32 s18, s18, 0xc0000
	s_mov_b32 m0, s75
	s_nop 0
	buffer_load_dwordx4 v230, s[12:15], s18 offen lds
	s_waitcnt vmcnt(8)
	s_waitcnt lgkmcnt(0)
	v_mfma_f32_16x16x32_bf16 v[130:133], v[134:137], v[166:169], v[130:133]
	s_barrier
	v_mfma_f32_16x16x32_bf16 v[130:133], v[138:141], v[170:173], v[130:133]
	v_mfma_f32_16x16x32_bf16 v[126:129], v[142:145], v[166:169], v[126:129]
	v_mfma_f32_16x16x32_bf16 v[126:129], v[146:149], v[170:173], v[126:129]
	v_mfma_f32_16x16x32_bf16 v[122:125], v[150:153], v[166:169], v[122:125]
	v_mfma_f32_16x16x32_bf16 v[122:125], v[154:157], v[170:173], v[122:125]
	v_mfma_f32_16x16x32_bf16 v[118:121], v[158:161], v[166:169], v[118:121]
	v_mfma_f32_16x16x32_bf16 v[118:121], v[162:165], v[170:173], v[118:121]
	v_mfma_f32_16x16x32_bf16 v[102:105], v[158:161], v[174:177], v[102:105]
	v_mfma_f32_16x16x32_bf16 v[102:105], v[162:165], v[178:181], v[102:105]
	v_mfma_f32_16x16x32_bf16 v[106:109], v[150:153], v[174:177], v[106:109]
	v_mfma_f32_16x16x32_bf16 v[106:109], v[154:157], v[178:181], v[106:109]
	v_mfma_f32_16x16x32_bf16 v[110:113], v[142:145], v[174:177], v[110:113]
	v_mfma_f32_16x16x32_bf16 v[110:113], v[146:149], v[178:181], v[110:113]
	v_mfma_f32_16x16x32_bf16 v[114:117], v[134:137], v[174:177], v[114:117]
	v_mfma_f32_16x16x32_bf16 v[114:117], v[138:141], v[178:181], v[114:117]
	v_mfma_f32_16x16x32_bf16 v[98:101], v[134:137], v[182:185], v[98:101]
	v_mfma_f32_16x16x32_bf16 v[98:101], v[138:141], v[186:189], v[98:101]
	v_mfma_f32_16x16x32_bf16 v[94:97], v[142:145], v[182:185], v[94:97]
	v_mfma_f32_16x16x32_bf16 v[94:97], v[146:149], v[186:189], v[94:97]
	v_mfma_f32_16x16x32_bf16 v[90:93], v[150:153], v[182:185], v[90:93]
	v_mfma_f32_16x16x32_bf16 v[90:93], v[154:157], v[186:189], v[90:93]
	v_mfma_f32_16x16x32_bf16 v[86:89], v[158:161], v[182:185], v[86:89]
	v_mfma_f32_16x16x32_bf16 v[86:89], v[162:165], v[186:189], v[86:89]
	v_mfma_f32_16x16x32_bf16 v[70:73], v[158:161], v[190:193], v[70:73]
	v_mfma_f32_16x16x32_bf16 v[70:73], v[162:165], v[194:197], v[70:73]
	v_mfma_f32_16x16x32_bf16 v[74:77], v[150:153], v[190:193], v[74:77]
	v_mfma_f32_16x16x32_bf16 v[74:77], v[154:157], v[194:197], v[74:77]
	v_mfma_f32_16x16x32_bf16 v[78:81], v[142:145], v[190:193], v[78:81]
	v_mfma_f32_16x16x32_bf16 v[78:81], v[146:149], v[194:197], v[78:81]
	v_mfma_f32_16x16x32_bf16 v[82:85], v[134:137], v[190:193], v[82:85]
	v_mfma_f32_16x16x32_bf16 v[82:85], v[138:141], v[194:197], v[82:85]
	s_barrier
	s_mov_b32 m0, s27
	s_mov_b32 s18, s14
	s_mov_b32 s19, s15
	ds_read_b128 v[166:169], v233 offset:16384
	ds_read_b128 v[170:173], v233 offset:17408
	ds_read_b128 v[174:177], v233 offset:18432
	ds_read_b128 v[178:181], v233 offset:19456
	ds_read_b128 v[182:185], v233 offset:20480
	ds_read_b128 v[186:189], v233 offset:21504
	ds_read_b128 v[190:193], v233 offset:22528
	ds_read_b128 v[194:197], v233 offset:23552
	buffer_load_dwordx4 v231, s[16:19], s51 offen lds
	s_add_i32 s53, s51, 0x18000
	s_mov_b32 m0, s30
	s_nop 0
	buffer_load_dwordx4 v231, s[16:19], s53 offen lds
	s_add_i32 s53, s51, 0x30000
	s_mov_b32 m0, s31
	s_nop 0
	buffer_load_dwordx4 v231, s[16:19], s53 offen lds
	s_add_i32 s53, s51, 0x48000
	s_mov_b32 m0, s54
	s_nop 0
	buffer_load_dwordx4 v231, s[16:19], s53 offen lds
	s_mov_b32 m0, s25
	s_add_i32 s53, s92, 0x40000
	buffer_load_dwordx4 v230, s[12:15], s92 offen lds
	s_mov_b32 m0, s55
	s_nop 0
	buffer_load_dwordx4 v230, s[12:15], s53 offen lds
	s_waitcnt vmcnt(8)
	s_waitcnt lgkmcnt(0)
	v_mfma_f32_16x16x32_bf16 v[66:69], v[134:137], v[166:169], v[66:69]
	s_barrier
	v_mfma_f32_16x16x32_bf16 v[62:65], v[142:145], v[166:169], v[62:65]
	v_mfma_f32_16x16x32_bf16 v[50:53], v[134:137], v[174:177], v[50:53]
	v_mfma_f32_16x16x32_bf16 v[46:49], v[142:145], v[174:177], v[46:49]
	v_mfma_f32_16x16x32_bf16 v[34:37], v[134:137], v[182:185], v[34:37]
	v_mfma_f32_16x16x32_bf16 v[30:33], v[142:145], v[182:185], v[30:33]
	v_mfma_f32_16x16x32_bf16 v[18:21], v[134:137], v[190:193], v[18:21]
	v_mfma_f32_16x16x32_bf16 v[14:17], v[142:145], v[190:193], v[14:17]
	v_mfma_f32_16x16x32_bf16 v[58:61], v[150:153], v[166:169], v[58:61]
	v_mfma_f32_16x16x32_bf16 v[54:57], v[158:161], v[166:169], v[54:57]
	v_mfma_f32_16x16x32_bf16 v[42:45], v[150:153], v[174:177], v[42:45]
	v_mfma_f32_16x16x32_bf16 v[38:41], v[158:161], v[174:177], v[38:41]
	v_mfma_f32_16x16x32_bf16 v[26:29], v[150:153], v[182:185], v[26:29]
	v_mfma_f32_16x16x32_bf16 v[22:25], v[158:161], v[182:185], v[22:25]
	v_mfma_f32_16x16x32_bf16 v[10:13], v[150:153], v[190:193], v[10:13]
	v_mfma_f32_16x16x32_bf16 v[4:7], v[158:161], v[190:193], v[6:9]
	v_mfma_f32_16x16x32_bf16 v[66:69], v[138:141], v[170:173], v[66:69]
	v_mfma_f32_16x16x32_bf16 v[62:65], v[146:149], v[170:173], v[62:65]
	v_mfma_f32_16x16x32_bf16 v[50:53], v[138:141], v[178:181], v[50:53]
	v_mfma_f32_16x16x32_bf16 v[46:49], v[146:149], v[178:181], v[46:49]
	v_mfma_f32_16x16x32_bf16 v[34:37], v[138:141], v[186:189], v[34:37]
	v_mfma_f32_16x16x32_bf16 v[30:33], v[146:149], v[186:189], v[30:33]
	v_mfma_f32_16x16x32_bf16 v[18:21], v[138:141], v[194:197], v[18:21]
	v_mfma_f32_16x16x32_bf16 v[14:17], v[146:149], v[194:197], v[14:17]
	v_mfma_f32_16x16x32_bf16 v[58:61], v[154:157], v[170:173], v[58:61]
	v_mfma_f32_16x16x32_bf16 v[54:57], v[162:165], v[170:173], v[54:57]
	v_mfma_f32_16x16x32_bf16 v[42:45], v[154:157], v[178:181], v[42:45]
	v_mfma_f32_16x16x32_bf16 v[38:41], v[162:165], v[178:181], v[38:41]
	v_mfma_f32_16x16x32_bf16 v[26:29], v[154:157], v[186:189], v[26:29]
	v_mfma_f32_16x16x32_bf16 v[22:25], v[162:165], v[186:189], v[22:25]
	v_mfma_f32_16x16x32_bf16 v[10:13], v[154:157], v[194:197], v[10:13]
	v_mfma_f32_16x16x32_bf16 v[4:7], v[162:165], v[194:197], v[4:7]
	s_barrier
	v_add_u32_e32 v2, 0x18000, v232
	ds_read_b128 v[134:137], v2
	ds_read_b128 v[138:141], v2 offset:1024
	ds_read_b128 v[142:145], v2 offset:2048
	ds_read_b128 v[146:149], v2 offset:3072
	v_add_u32_e32 v2, 0x1c000, v232
	ds_read_b128 v[150:153], v2
	ds_read_b128 v[154:157], v2 offset:1024
	ds_read_b128 v[158:161], v2 offset:2048
	ds_read_b128 v[162:165], v2 offset:3072
	s_mov_b32 m0, s56
	s_add_i32 s53, s92, 0x80000
	ds_read_b128 v[166:169], v233 offset:32768
	ds_read_b128 v[170:173], v233 offset:33792
	ds_read_b128 v[174:177], v233 offset:34816
	ds_read_b128 v[178:181], v233 offset:35840
	ds_read_b128 v[182:185], v233 offset:36864
	ds_read_b128 v[186:189], v233 offset:37888
	ds_read_b128 v[190:193], v233 offset:38912
	ds_read_b128 v[194:197], v233 offset:39936
	buffer_load_dwordx4 v230, s[12:15], s53 offen lds
	s_add_i32 s53, s92, 0xc0000
	s_mov_b32 m0, s57
	s_nop 0
	buffer_load_dwordx4 v230, s[12:15], s53 offen lds
	s_waitcnt vmcnt(8)
	s_waitcnt lgkmcnt(0)
	v_mfma_f32_16x16x32_bf16 v[130:133], v[134:137], v[166:169], v[130:133]
	s_barrier
	v_mfma_f32_16x16x32_bf16 v[130:133], v[138:141], v[170:173], v[130:133]
	v_mfma_f32_16x16x32_bf16 v[126:129], v[142:145], v[166:169], v[126:129]
	v_mfma_f32_16x16x32_bf16 v[126:129], v[146:149], v[170:173], v[126:129]
	v_mfma_f32_16x16x32_bf16 v[122:125], v[150:153], v[166:169], v[122:125]
	v_mfma_f32_16x16x32_bf16 v[122:125], v[154:157], v[170:173], v[122:125]
	v_mfma_f32_16x16x32_bf16 v[118:121], v[158:161], v[166:169], v[118:121]
	v_mfma_f32_16x16x32_bf16 v[118:121], v[162:165], v[170:173], v[118:121]
	v_mfma_f32_16x16x32_bf16 v[102:105], v[158:161], v[174:177], v[102:105]
	v_mfma_f32_16x16x32_bf16 v[102:105], v[162:165], v[178:181], v[102:105]
	v_mfma_f32_16x16x32_bf16 v[106:109], v[150:153], v[174:177], v[106:109]
	v_mfma_f32_16x16x32_bf16 v[106:109], v[154:157], v[178:181], v[106:109]
	v_mfma_f32_16x16x32_bf16 v[110:113], v[142:145], v[174:177], v[110:113]
	v_mfma_f32_16x16x32_bf16 v[110:113], v[146:149], v[178:181], v[110:113]
	v_mfma_f32_16x16x32_bf16 v[114:117], v[134:137], v[174:177], v[114:117]
	v_mfma_f32_16x16x32_bf16 v[114:117], v[138:141], v[178:181], v[114:117]
	v_mfma_f32_16x16x32_bf16 v[98:101], v[134:137], v[182:185], v[98:101]
	v_mfma_f32_16x16x32_bf16 v[98:101], v[138:141], v[186:189], v[98:101]
	v_mfma_f32_16x16x32_bf16 v[94:97], v[142:145], v[182:185], v[94:97]
	v_mfma_f32_16x16x32_bf16 v[94:97], v[146:149], v[186:189], v[94:97]
	v_mfma_f32_16x16x32_bf16 v[90:93], v[150:153], v[182:185], v[90:93]
	v_mfma_f32_16x16x32_bf16 v[90:93], v[154:157], v[186:189], v[90:93]
	v_mfma_f32_16x16x32_bf16 v[86:89], v[158:161], v[182:185], v[86:89]
	v_mfma_f32_16x16x32_bf16 v[86:89], v[162:165], v[186:189], v[86:89]
	v_mfma_f32_16x16x32_bf16 v[70:73], v[158:161], v[190:193], v[70:73]
	v_mfma_f32_16x16x32_bf16 v[70:73], v[162:165], v[194:197], v[70:73]
	v_mfma_f32_16x16x32_bf16 v[74:77], v[150:153], v[190:193], v[74:77]
	v_mfma_f32_16x16x32_bf16 v[74:77], v[154:157], v[194:197], v[74:77]
	v_mfma_f32_16x16x32_bf16 v[78:81], v[142:145], v[190:193], v[78:81]
	v_mfma_f32_16x16x32_bf16 v[78:81], v[146:149], v[194:197], v[78:81]
	v_mfma_f32_16x16x32_bf16 v[82:85], v[134:137], v[190:193], v[82:85]
	v_mfma_f32_16x16x32_bf16 v[82:85], v[138:141], v[194:197], v[82:85]
	s_barrier
	s_mov_b32 m0, s64
	ds_read_b128 v[166:169], v233 offset:49152
	ds_read_b128 v[170:173], v233 offset:50176
	ds_read_b128 v[174:177], v233 offset:51200
	ds_read_b128 v[178:181], v233 offset:52224
	ds_read_b128 v[182:185], v233 offset:53248
	ds_read_b128 v[186:189], v233 offset:54272
	ds_read_b128 v[190:193], v233 offset:55296
	ds_read_b128 v[194:197], v233 offset:56320
	buffer_load_dwordx4 v231, s[16:19], s52 offen lds
	s_add_i32 s52, s51, 0x18080
	s_mov_b32 m0, s65
	s_nop 0
	buffer_load_dwordx4 v231, s[16:19], s52 offen lds
	s_add_i32 s52, s51, 0x30080
	s_mov_b32 m0, s68
	s_add_i32 s51, s51, 0x48080
	buffer_load_dwordx4 v231, s[16:19], s52 offen lds
	s_mov_b32 m0, s69
	s_nop 0
	buffer_load_dwordx4 v231, s[16:19], s51 offen lds
	s_mov_b32 m0, s66
	s_add_i32 s18, s92, 0x40080
	buffer_load_dwordx4 v230, s[12:15], s50 offen lds
	s_mov_b32 m0, s67
	s_nop 0
	buffer_load_dwordx4 v230, s[12:15], s18 offen lds
	s_waitcnt vmcnt(8)
	s_waitcnt lgkmcnt(0)
	v_mfma_f32_16x16x32_bf16 v[66:69], v[134:137], v[166:169], v[66:69]
	s_barrier
	v_mfma_f32_16x16x32_bf16 v[62:65], v[142:145], v[166:169], v[62:65]
	v_mfma_f32_16x16x32_bf16 v[50:53], v[134:137], v[174:177], v[50:53]
	v_mfma_f32_16x16x32_bf16 v[46:49], v[142:145], v[174:177], v[46:49]
	v_mfma_f32_16x16x32_bf16 v[34:37], v[134:137], v[182:185], v[34:37]
	v_mfma_f32_16x16x32_bf16 v[30:33], v[142:145], v[182:185], v[30:33]
	v_mfma_f32_16x16x32_bf16 v[18:21], v[134:137], v[190:193], v[18:21]
	v_mfma_f32_16x16x32_bf16 v[14:17], v[142:145], v[190:193], v[14:17]
	v_mfma_f32_16x16x32_bf16 v[58:61], v[150:153], v[166:169], v[58:61]
	v_mfma_f32_16x16x32_bf16 v[54:57], v[158:161], v[166:169], v[54:57]
	v_mfma_f32_16x16x32_bf16 v[42:45], v[150:153], v[174:177], v[42:45]
	v_mfma_f32_16x16x32_bf16 v[38:41], v[158:161], v[174:177], v[38:41]
	v_mfma_f32_16x16x32_bf16 v[26:29], v[150:153], v[182:185], v[26:29]
	v_mfma_f32_16x16x32_bf16 v[22:25], v[158:161], v[182:185], v[22:25]
	v_mfma_f32_16x16x32_bf16 v[8:11], v[150:153], v[190:193], v[10:13]
	v_mfma_f32_16x16x32_bf16 v[4:7], v[158:161], v[190:193], v[4:7]
	v_mfma_f32_16x16x32_bf16 v[66:69], v[138:141], v[170:173], v[66:69]
	v_mfma_f32_16x16x32_bf16 v[62:65], v[146:149], v[170:173], v[62:65]
	v_mfma_f32_16x16x32_bf16 v[50:53], v[138:141], v[178:181], v[50:53]
	v_mfma_f32_16x16x32_bf16 v[46:49], v[146:149], v[178:181], v[46:49]
	v_mfma_f32_16x16x32_bf16 v[34:37], v[138:141], v[186:189], v[34:37]
	v_mfma_f32_16x16x32_bf16 v[30:33], v[146:149], v[186:189], v[30:33]
	v_mfma_f32_16x16x32_bf16 v[18:21], v[138:141], v[194:197], v[18:21]
	v_mfma_f32_16x16x32_bf16 v[14:17], v[146:149], v[194:197], v[14:17]
	v_mfma_f32_16x16x32_bf16 v[58:61], v[154:157], v[170:173], v[58:61]
	v_mfma_f32_16x16x32_bf16 v[54:57], v[162:165], v[170:173], v[54:57]
	v_mfma_f32_16x16x32_bf16 v[42:45], v[154:157], v[178:181], v[42:45]
	v_mfma_f32_16x16x32_bf16 v[38:41], v[162:165], v[178:181], v[38:41]
	v_mfma_f32_16x16x32_bf16 v[26:29], v[154:157], v[186:189], v[26:29]
	v_mfma_f32_16x16x32_bf16 v[22:25], v[162:165], v[186:189], v[22:25]
	v_mfma_f32_16x16x32_bf16 v[10:13], v[154:157], v[194:197], v[8:11]
	v_mfma_f32_16x16x32_bf16 v[6:9], v[162:165], v[194:197], v[4:7]
	s_barrier
	s_add_i32 s91, s91, 2
	s_addk_i32 s90, 0x100
	s_cmp_ge_i32 s91, s3
	s_cbranch_scc1 .LBB0_1193

.LBB0_1290:
	ds_read_b128 v[106:109], v224
	ds_read_b128 v[118:121], v224 offset:1024
	ds_read_b128 v[130:133], v224 offset:2048
	ds_read_b128 v[138:141], v224 offset:3072
	ds_read_b128 v[146:149], v225
	ds_read_b128 v[150:153], v225 offset:1024
	ds_read_b128 v[154:157], v225 offset:2048
	ds_read_b128 v[158:161], v225 offset:3072
	s_add_i32 s18, s72, 0xffe80080
	s_cmp_eq_u32 s56, s74
	s_cselect_b32 s75, s6, s18
	s_cselect_b32 s77, s7, s73
	s_or_b32 s76, s75, 0x80
	s_add_i32 s18, s72, 0xfff80000
	s_mov_b32 m0, s57
	ds_read_b128 v[162:165], v226
	ds_read_b128 v[166:169], v226 offset:1024
	ds_read_b128 v[170:173], v226 offset:2048
	ds_read_b128 v[174:177], v226 offset:3072
	ds_read_b128 v[178:181], v226 offset:4096
	ds_read_b128 v[182:185], v226 offset:5120
	ds_read_b128 v[190:193], v226 offset:6144
	ds_read_b128 v[194:197], v226 offset:7168
	buffer_load_dwordx4 v222, s[12:15], s18 offen lds
	s_mov_b32 m0, s60
	s_nop 0
	buffer_load_dwordx4 v222, s[12:15], s72 offen lds
	s_waitcnt vmcnt(8)
	s_waitcnt lgkmcnt(0)
	v_mfma_f32_16x16x32_bf16 v[142:145], v[106:109], v[162:165], v[142:145]
	s_barrier
	v_mfma_f32_16x16x32_bf16 v[142:145], v[118:121], v[166:169], v[142:145]
	v_mfma_f32_16x16x32_bf16 v[134:137], v[130:133], v[162:165], v[134:137]
	v_mfma_f32_16x16x32_bf16 v[134:137], v[138:141], v[166:169], v[134:137]
	v_mfma_f32_16x16x32_bf16 v[126:129], v[146:149], v[162:165], v[126:129]
	v_mfma_f32_16x16x32_bf16 v[126:129], v[150:153], v[166:169], v[126:129]
	v_mfma_f32_16x16x32_bf16 v[122:125], v[154:157], v[162:165], v[122:125]
	v_mfma_f32_16x16x32_bf16 v[122:125], v[158:161], v[166:169], v[122:125]
	v_mfma_f32_16x16x32_bf16 v[98:101], v[154:157], v[170:173], v[98:101]
	v_mfma_f32_16x16x32_bf16 v[98:101], v[158:161], v[174:177], v[98:101]
	v_mfma_f32_16x16x32_bf16 v[102:105], v[146:149], v[170:173], v[102:105]
	v_mfma_f32_16x16x32_bf16 v[102:105], v[150:153], v[174:177], v[102:105]
	v_mfma_f32_16x16x32_bf16 v[110:113], v[130:133], v[170:173], v[110:113]
	v_mfma_f32_16x16x32_bf16 v[110:113], v[138:141], v[174:177], v[110:113]
	v_mfma_f32_16x16x32_bf16 v[114:117], v[106:109], v[170:173], v[114:117]
	v_mfma_f32_16x16x32_bf16 v[114:117], v[118:121], v[174:177], v[114:117]
	v_mfma_f32_16x16x32_bf16 v[94:97], v[106:109], v[178:181], v[94:97]
	v_mfma_f32_16x16x32_bf16 v[94:97], v[118:121], v[182:185], v[94:97]
	v_mfma_f32_16x16x32_bf16 v[90:93], v[130:133], v[178:181], v[90:93]
	v_mfma_f32_16x16x32_bf16 v[90:93], v[138:141], v[182:185], v[90:93]
	v_mfma_f32_16x16x32_bf16 v[86:89], v[146:149], v[178:181], v[86:89]
	v_mfma_f32_16x16x32_bf16 v[86:89], v[150:153], v[182:185], v[86:89]
	v_mfma_f32_16x16x32_bf16 v[82:85], v[154:157], v[178:181], v[82:85]
	v_mfma_f32_16x16x32_bf16 v[82:85], v[158:161], v[182:185], v[82:85]
	v_mfma_f32_16x16x32_bf16 v[66:69], v[154:157], v[190:193], v[66:69]
	v_mfma_f32_16x16x32_bf16 v[66:69], v[158:161], v[194:197], v[66:69]
	v_mfma_f32_16x16x32_bf16 v[70:73], v[146:149], v[190:193], v[70:73]
	v_mfma_f32_16x16x32_bf16 v[70:73], v[150:153], v[194:197], v[70:73]
	v_mfma_f32_16x16x32_bf16 v[74:77], v[130:133], v[190:193], v[74:77]
	v_mfma_f32_16x16x32_bf16 v[74:77], v[138:141], v[194:197], v[74:77]
	v_mfma_f32_16x16x32_bf16 v[78:81], v[106:109], v[190:193], v[78:81]
	v_mfma_f32_16x16x32_bf16 v[78:81], v[118:121], v[194:197], v[78:81]
	s_barrier
	s_mov_b32 m0, s27
	s_mov_b32 s18, s14
	s_mov_b32 s19, s15
	ds_read_b128 v[162:165], v226 offset:16384
	ds_read_b128 v[166:169], v226 offset:17408
	ds_read_b128 v[170:173], v226 offset:18432
	ds_read_b128 v[174:177], v226 offset:19456
	ds_read_b128 v[178:181], v226 offset:20480
	ds_read_b128 v[182:185], v226 offset:21504
	ds_read_b128 v[190:193], v226 offset:22528
	ds_read_b128 v[194:197], v226 offset:23552
	buffer_load_dwordx4 v223, s[16:19], s77 offen lds
	s_add_i32 s78, s77, 0x80000
	s_mov_b32 m0, s30
	s_nop 0
	buffer_load_dwordx4 v223, s[16:19], s78 offen lds
	s_add_i32 s78, s77, 0x100000
	s_mov_b32 m0, s31
	s_nop 0
	buffer_load_dwordx4 v223, s[16:19], s78 offen lds
	s_add_i32 s78, s77, 0x180000
	s_mov_b32 m0, s41
	s_nop 0
	buffer_load_dwordx4 v223, s[16:19], s78 offen lds
	s_mov_b32 m0, s25
	s_add_i32 s78, s75, 0x80000
	buffer_load_dwordx4 v222, s[12:15], s75 offen lds
	s_mov_b32 m0, s42
	s_nop 0
	buffer_load_dwordx4 v222, s[12:15], s78 offen lds
	s_waitcnt vmcnt(8)
	s_waitcnt lgkmcnt(0)
	v_mfma_f32_16x16x32_bf16 v[62:65], v[106:109], v[162:165], v[62:65]
	s_barrier
	v_mfma_f32_16x16x32_bf16 v[62:65], v[118:121], v[166:169], v[62:65]
	v_mfma_f32_16x16x32_bf16 v[58:61], v[130:133], v[162:165], v[58:61]
	v_mfma_f32_16x16x32_bf16 v[58:61], v[138:141], v[166:169], v[58:61]
	v_mfma_f32_16x16x32_bf16 v[54:57], v[146:149], v[162:165], v[54:57]
	v_mfma_f32_16x16x32_bf16 v[54:57], v[150:153], v[166:169], v[54:57]
	v_mfma_f32_16x16x32_bf16 v[50:53], v[154:157], v[162:165], v[50:53]
	v_mfma_f32_16x16x32_bf16 v[50:53], v[158:161], v[166:169], v[50:53]
	v_mfma_f32_16x16x32_bf16 v[34:37], v[154:157], v[170:173], v[34:37]
	v_mfma_f32_16x16x32_bf16 v[34:37], v[158:161], v[174:177], v[34:37]
	v_mfma_f32_16x16x32_bf16 v[38:41], v[146:149], v[170:173], v[38:41]
	v_mfma_f32_16x16x32_bf16 v[38:41], v[150:153], v[174:177], v[38:41]
	v_mfma_f32_16x16x32_bf16 v[42:45], v[130:133], v[170:173], v[42:45]
	v_mfma_f32_16x16x32_bf16 v[42:45], v[138:141], v[174:177], v[42:45]
	v_mfma_f32_16x16x32_bf16 v[46:49], v[106:109], v[170:173], v[46:49]
	v_mfma_f32_16x16x32_bf16 v[46:49], v[118:121], v[174:177], v[46:49]
	v_mfma_f32_16x16x32_bf16 v[30:33], v[106:109], v[178:181], v[30:33]
	v_mfma_f32_16x16x32_bf16 v[30:33], v[118:121], v[182:185], v[30:33]
	v_mfma_f32_16x16x32_bf16 v[26:29], v[130:133], v[178:181], v[26:29]
	v_mfma_f32_16x16x32_bf16 v[26:29], v[138:141], v[182:185], v[26:29]
	v_mfma_f32_16x16x32_bf16 v[22:25], v[146:149], v[178:181], v[22:25]
	v_mfma_f32_16x16x32_bf16 v[22:25], v[150:153], v[182:185], v[22:25]
	v_mfma_f32_16x16x32_bf16 v[18:21], v[154:157], v[178:181], v[18:21]
	v_mfma_f32_16x16x32_bf16 v[18:21], v[158:161], v[182:185], v[18:21]
	v_mfma_f32_16x16x32_bf16 v[2:5], v[154:157], v[190:193], v[2:5]
	v_mfma_f32_16x16x32_bf16 v[2:5], v[158:161], v[194:197], v[2:5]
	v_mfma_f32_16x16x32_bf16 v[6:9], v[146:149], v[190:193], v[6:9]
	v_mfma_f32_16x16x32_bf16 v[6:9], v[150:153], v[194:197], v[6:9]
	v_mfma_f32_16x16x32_bf16 v[10:13], v[130:133], v[190:193], v[10:13]
	v_mfma_f32_16x16x32_bf16 v[10:13], v[138:141], v[194:197], v[10:13]
	v_mfma_f32_16x16x32_bf16 v[14:17], v[106:109], v[190:193], v[14:17]
	v_mfma_f32_16x16x32_bf16 v[14:17], v[118:121], v[194:197], v[14:17]
	s_barrier
	ds_read_b128 v[106:109], v227
	ds_read_b128 v[118:121], v227 offset:1024
	ds_read_b128 v[130:133], v227 offset:2048
	ds_read_b128 v[138:141], v227 offset:3072
	ds_read_b128 v[146:149], v228
	ds_read_b128 v[150:153], v228 offset:1024
	ds_read_b128 v[154:157], v228 offset:2048
	ds_read_b128 v[158:161], v228 offset:3072
	s_mov_b32 m0, s43
	s_add_i32 s78, s75, 0x100000
	ds_read_b128 v[162:165], v226 offset:32768
	ds_read_b128 v[166:169], v226 offset:33792
	ds_read_b128 v[170:173], v226 offset:34816
	ds_read_b128 v[174:177], v226 offset:35840
	ds_read_b128 v[178:181], v226 offset:36864
	ds_read_b128 v[182:185], v226 offset:37888
	ds_read_b128 v[190:193], v226 offset:38912
	ds_read_b128 v[194:197], v226 offset:39936
	buffer_load_dwordx4 v222, s[12:15], s78 offen lds
	s_add_i32 s78, s75, 0x180000
	s_mov_b32 m0, s44
	s_nop 0
	buffer_load_dwordx4 v222, s[12:15], s78 offen lds
	s_waitcnt vmcnt(8)
	s_waitcnt lgkmcnt(0)
	v_mfma_f32_16x16x32_bf16 v[142:145], v[106:109], v[162:165], v[142:145]
	s_barrier
	v_mfma_f32_16x16x32_bf16 v[142:145], v[118:121], v[166:169], v[142:145]
	v_mfma_f32_16x16x32_bf16 v[134:137], v[130:133], v[162:165], v[134:137]
	v_mfma_f32_16x16x32_bf16 v[134:137], v[138:141], v[166:169], v[134:137]
	v_mfma_f32_16x16x32_bf16 v[126:129], v[146:149], v[162:165], v[126:129]
	v_mfma_f32_16x16x32_bf16 v[126:129], v[150:153], v[166:169], v[126:129]
	v_mfma_f32_16x16x32_bf16 v[122:125], v[154:157], v[162:165], v[122:125]
	v_mfma_f32_16x16x32_bf16 v[122:125], v[158:161], v[166:169], v[122:125]
	v_mfma_f32_16x16x32_bf16 v[98:101], v[154:157], v[170:173], v[98:101]
	v_mfma_f32_16x16x32_bf16 v[98:101], v[158:161], v[174:177], v[98:101]
	v_mfma_f32_16x16x32_bf16 v[102:105], v[146:149], v[170:173], v[102:105]
	v_mfma_f32_16x16x32_bf16 v[102:105], v[150:153], v[174:177], v[102:105]
	v_mfma_f32_16x16x32_bf16 v[110:113], v[130:133], v[170:173], v[110:113]
	v_mfma_f32_16x16x32_bf16 v[110:113], v[138:141], v[174:177], v[110:113]
	v_mfma_f32_16x16x32_bf16 v[114:117], v[106:109], v[170:173], v[114:117]
	v_mfma_f32_16x16x32_bf16 v[114:117], v[118:121], v[174:177], v[114:117]
	v_mfma_f32_16x16x32_bf16 v[94:97], v[106:109], v[178:181], v[94:97]
	v_mfma_f32_16x16x32_bf16 v[94:97], v[118:121], v[182:185], v[94:97]
	v_mfma_f32_16x16x32_bf16 v[90:93], v[130:133], v[178:181], v[90:93]
	v_mfma_f32_16x16x32_bf16 v[90:93], v[138:141], v[182:185], v[90:93]
	v_mfma_f32_16x16x32_bf16 v[86:89], v[146:149], v[178:181], v[86:89]
	v_mfma_f32_16x16x32_bf16 v[86:89], v[150:153], v[182:185], v[86:89]
	v_mfma_f32_16x16x32_bf16 v[82:85], v[154:157], v[178:181], v[82:85]
	v_mfma_f32_16x16x32_bf16 v[82:85], v[158:161], v[182:185], v[82:85]
	v_mfma_f32_16x16x32_bf16 v[66:69], v[154:157], v[190:193], v[66:69]
	v_mfma_f32_16x16x32_bf16 v[66:69], v[158:161], v[194:197], v[66:69]
	v_mfma_f32_16x16x32_bf16 v[70:73], v[146:149], v[190:193], v[70:73]
	v_mfma_f32_16x16x32_bf16 v[70:73], v[150:153], v[194:197], v[70:73]
	v_mfma_f32_16x16x32_bf16 v[74:77], v[130:133], v[190:193], v[74:77]
	v_mfma_f32_16x16x32_bf16 v[74:77], v[138:141], v[194:197], v[74:77]
	v_mfma_f32_16x16x32_bf16 v[78:81], v[106:109], v[190:193], v[78:81]
	v_mfma_f32_16x16x32_bf16 v[78:81], v[118:121], v[194:197], v[78:81]
	s_barrier
	s_mov_b32 m0, s48
	s_or_b32 s78, s77, 0x80
	ds_read_b128 v[162:165], v226 offset:49152
	ds_read_b128 v[166:169], v226 offset:50176
	ds_read_b128 v[170:173], v226 offset:51200
	ds_read_b128 v[174:177], v226 offset:52224
	ds_read_b128 v[178:181], v226 offset:53248
	ds_read_b128 v[182:185], v226 offset:54272
	ds_read_b128 v[190:193], v226 offset:55296
	ds_read_b128 v[194:197], v226 offset:56320
	buffer_load_dwordx4 v223, s[16:19], s78 offen lds
	s_add_i32 s78, s77, 0x80080
	s_mov_b32 m0, s49
	s_add_i32 s75, s75, 0x80080
	buffer_load_dwordx4 v223, s[16:19], s78 offen lds
	s_add_i32 s78, s77, 0x100080
	s_mov_b32 m0, s52
	s_add_i32 s77, s77, 0x180080
	buffer_load_dwordx4 v223, s[16:19], s78 offen lds
	s_mov_b32 m0, s53
	s_nop 0
	buffer_load_dwordx4 v223, s[16:19], s77 offen lds
	s_mov_b32 m0, s50
	s_nop 0
	buffer_load_dwordx4 v222, s[12:15], s76 offen lds
	s_mov_b32 m0, s51
	s_nop 0
	buffer_load_dwordx4 v222, s[12:15], s75 offen lds
	s_waitcnt vmcnt(8)
	s_waitcnt lgkmcnt(0)
	v_mfma_f32_16x16x32_bf16 v[62:65], v[106:109], v[162:165], v[62:65]
	s_barrier
	v_mfma_f32_16x16x32_bf16 v[62:65], v[118:121], v[166:169], v[62:65]
	v_mfma_f32_16x16x32_bf16 v[58:61], v[130:133], v[162:165], v[58:61]
	v_mfma_f32_16x16x32_bf16 v[58:61], v[138:141], v[166:169], v[58:61]
	v_mfma_f32_16x16x32_bf16 v[54:57], v[146:149], v[162:165], v[54:57]
	v_mfma_f32_16x16x32_bf16 v[54:57], v[150:153], v[166:169], v[54:57]
	v_mfma_f32_16x16x32_bf16 v[50:53], v[154:157], v[162:165], v[50:53]
	v_mfma_f32_16x16x32_bf16 v[50:53], v[158:161], v[166:169], v[50:53]
	v_mfma_f32_16x16x32_bf16 v[34:37], v[154:157], v[170:173], v[34:37]
	v_mfma_f32_16x16x32_bf16 v[34:37], v[158:161], v[174:177], v[34:37]
	v_mfma_f32_16x16x32_bf16 v[38:41], v[146:149], v[170:173], v[38:41]
	v_mfma_f32_16x16x32_bf16 v[38:41], v[150:153], v[174:177], v[38:41]
	v_mfma_f32_16x16x32_bf16 v[42:45], v[130:133], v[170:173], v[42:45]
	v_mfma_f32_16x16x32_bf16 v[42:45], v[138:141], v[174:177], v[42:45]
	v_mfma_f32_16x16x32_bf16 v[46:49], v[106:109], v[170:173], v[46:49]
	v_mfma_f32_16x16x32_bf16 v[46:49], v[118:121], v[174:177], v[46:49]
	v_mfma_f32_16x16x32_bf16 v[30:33], v[106:109], v[178:181], v[30:33]
	v_mfma_f32_16x16x32_bf16 v[30:33], v[118:121], v[182:185], v[30:33]
	v_mfma_f32_16x16x32_bf16 v[26:29], v[130:133], v[178:181], v[26:29]
	v_mfma_f32_16x16x32_bf16 v[26:29], v[138:141], v[182:185], v[26:29]
	v_mfma_f32_16x16x32_bf16 v[22:25], v[146:149], v[178:181], v[22:25]
	v_mfma_f32_16x16x32_bf16 v[22:25], v[150:153], v[182:185], v[22:25]
	v_mfma_f32_16x16x32_bf16 v[18:21], v[154:157], v[178:181], v[18:21]
	v_mfma_f32_16x16x32_bf16 v[18:21], v[158:161], v[182:185], v[18:21]
	v_mfma_f32_16x16x32_bf16 v[2:5], v[154:157], v[190:193], v[2:5]
	v_mfma_f32_16x16x32_bf16 v[2:5], v[158:161], v[194:197], v[2:5]
	v_mfma_f32_16x16x32_bf16 v[6:9], v[146:149], v[190:193], v[6:9]
	v_mfma_f32_16x16x32_bf16 v[6:9], v[150:153], v[194:197], v[6:9]
	v_mfma_f32_16x16x32_bf16 v[10:13], v[130:133], v[190:193], v[10:13]
	v_mfma_f32_16x16x32_bf16 v[10:13], v[138:141], v[194:197], v[10:13]
	v_mfma_f32_16x16x32_bf16 v[14:17], v[106:109], v[190:193], v[14:17]
	v_mfma_f32_16x16x32_bf16 v[14:17], v[118:121], v[194:197], v[14:17]
	s_barrier
	s_add_i32 s74, s74, 2
	s_addk_i32 s72, 0x100
	s_addk_i32 s73, 0x100
	s_cmp_ge_i32 s74, s3
	s_cbranch_scc0 .LBB0_1290
	s_and_b64 vcc, exec, s[38:39]
	s_cbranch_vccz .LBB0_1293

.LBB0_1382:
	ds_read_b128 v[144:147], v138
	ds_read_b128 v[148:151], v138 offset:1024
	ds_read_b128 v[152:155], v138 offset:2048
	ds_read_b128 v[156:159], v138 offset:3072
	ds_read_b128 v[160:163], v139
	ds_read_b128 v[164:167], v139 offset:1024
	ds_read_b128 v[168:171], v139 offset:2048
	ds_read_b128 v[172:175], v139 offset:3072
	s_add_i32 s14, s74, 0xffe80080
	s_cmp_eq_u32 s61, s76
	s_cselect_b32 s77, s72, s14
	s_cselect_b32 s79, s73, s75
	s_or_b32 s78, s77, 0x80
	s_add_i32 s14, s74, 0xfff80000
	s_mov_b32 m0, s62
	ds_read_b128 v[176:179], v140
	ds_read_b128 v[180:183], v140 offset:1024
	ds_read_b128 v[184:187], v140 offset:2048
	ds_read_b128 v[188:191], v140 offset:3072
	ds_read_b128 v[192:195], v140 offset:4096
	ds_read_b128 v[196:199], v140 offset:5120
	ds_read_b128 v[200:203], v140 offset:6144
	ds_read_b128 v[204:207], v140 offset:7168
	buffer_load_dwordx4 v136, s[16:19], s14 offen lds
	s_mov_b32 m0, s63
	s_nop 0
	buffer_load_dwordx4 v136, s[16:19], s74 offen lds
	s_waitcnt vmcnt(8)
	s_waitcnt lgkmcnt(0)
	v_mfma_f32_16x16x32_bf16 v[118:121], v[144:147], v[176:179], v[118:121]
	s_barrier
	v_mfma_f32_16x16x32_bf16 v[118:121], v[148:151], v[180:183], v[118:121]
	v_mfma_f32_16x16x32_bf16 v[114:117], v[152:155], v[176:179], v[114:117]
	v_mfma_f32_16x16x32_bf16 v[114:117], v[156:159], v[180:183], v[114:117]
	v_mfma_f32_16x16x32_bf16 v[126:129], v[160:163], v[176:179], v[126:129]
	v_mfma_f32_16x16x32_bf16 v[126:129], v[164:167], v[180:183], v[126:129]
	v_mfma_f32_16x16x32_bf16 v[122:125], v[168:171], v[176:179], v[122:125]
	v_mfma_f32_16x16x32_bf16 v[122:125], v[172:175], v[180:183], v[122:125]
	v_mfma_f32_16x16x32_bf16 v[98:101], v[168:171], v[184:187], v[98:101]
	v_mfma_f32_16x16x32_bf16 v[98:101], v[172:175], v[188:191], v[98:101]
	v_mfma_f32_16x16x32_bf16 v[106:109], v[160:163], v[184:187], v[106:109]
	v_mfma_f32_16x16x32_bf16 v[106:109], v[164:167], v[188:191], v[106:109]
	v_mfma_f32_16x16x32_bf16 v[102:105], v[152:155], v[184:187], v[102:105]
	v_mfma_f32_16x16x32_bf16 v[102:105], v[156:159], v[188:191], v[102:105]
	v_mfma_f32_16x16x32_bf16 v[110:113], v[144:147], v[184:187], v[110:113]
	v_mfma_f32_16x16x32_bf16 v[110:113], v[148:151], v[188:191], v[110:113]
	v_mfma_f32_16x16x32_bf16 v[94:97], v[144:147], v[192:195], v[94:97]
	v_mfma_f32_16x16x32_bf16 v[94:97], v[148:151], v[196:199], v[94:97]
	v_mfma_f32_16x16x32_bf16 v[86:89], v[152:155], v[192:195], v[86:89]
	v_mfma_f32_16x16x32_bf16 v[86:89], v[156:159], v[196:199], v[86:89]
	v_mfma_f32_16x16x32_bf16 v[90:93], v[160:163], v[192:195], v[90:93]
	v_mfma_f32_16x16x32_bf16 v[90:93], v[164:167], v[196:199], v[90:93]
	v_mfma_f32_16x16x32_bf16 v[82:85], v[168:171], v[192:195], v[82:85]
	v_mfma_f32_16x16x32_bf16 v[82:85], v[172:175], v[196:199], v[82:85]
	v_mfma_f32_16x16x32_bf16 v[70:73], v[168:171], v[200:203], v[70:73]
	v_mfma_f32_16x16x32_bf16 v[70:73], v[172:175], v[204:207], v[70:73]
	v_mfma_f32_16x16x32_bf16 v[74:77], v[160:163], v[200:203], v[74:77]
	v_mfma_f32_16x16x32_bf16 v[74:77], v[164:167], v[204:207], v[74:77]
	v_mfma_f32_16x16x32_bf16 v[66:69], v[152:155], v[200:203], v[66:69]
	v_mfma_f32_16x16x32_bf16 v[66:69], v[156:159], v[204:207], v[66:69]
	v_mfma_f32_16x16x32_bf16 v[78:81], v[144:147], v[200:203], v[78:81]
	v_mfma_f32_16x16x32_bf16 v[78:81], v[148:151], v[204:207], v[78:81]
	s_barrier
	s_mov_b32 m0, s45
	s_mov_b32 s14, s18
	s_mov_b32 s15, s19
	ds_read_b128 v[176:179], v140 offset:16384
	ds_read_b128 v[180:183], v140 offset:17408
	ds_read_b128 v[184:187], v140 offset:18432
	ds_read_b128 v[188:191], v140 offset:19456
	ds_read_b128 v[192:195], v140 offset:20480
	ds_read_b128 v[196:199], v140 offset:21504
	ds_read_b128 v[200:203], v140 offset:22528
	ds_read_b128 v[204:207], v140 offset:23552
	buffer_load_dwordx4 v137, s[12:15], s79 offen lds
	s_add_i32 s80, s79, 0x80000
	s_mov_b32 m0, s46
	s_nop 0
	buffer_load_dwordx4 v137, s[12:15], s80 offen lds
	s_add_i32 s80, s79, 0x100000
	s_mov_b32 m0, s47
	s_nop 0
	buffer_load_dwordx4 v137, s[12:15], s80 offen lds
	s_add_i32 s80, s79, 0x180000
	s_mov_b32 m0, s48
	s_nop 0
	buffer_load_dwordx4 v137, s[12:15], s80 offen lds
	s_mov_b32 m0, s44
	s_add_i32 s80, s77, 0x80000
	buffer_load_dwordx4 v136, s[16:19], s77 offen lds
	s_mov_b32 m0, s49
	s_nop 0
	buffer_load_dwordx4 v136, s[16:19], s80 offen lds
	s_waitcnt vmcnt(8)
	s_waitcnt lgkmcnt(0)
	v_mfma_f32_16x16x32_bf16 v[62:65], v[144:147], v[176:179], v[62:65]
	s_barrier
	v_mfma_f32_16x16x32_bf16 v[62:65], v[148:151], v[180:183], v[62:65]
	v_mfma_f32_16x16x32_bf16 v[54:57], v[152:155], v[176:179], v[54:57]
	v_mfma_f32_16x16x32_bf16 v[54:57], v[156:159], v[180:183], v[54:57]
	v_mfma_f32_16x16x32_bf16 v[58:61], v[160:163], v[176:179], v[58:61]
	v_mfma_f32_16x16x32_bf16 v[58:61], v[164:167], v[180:183], v[58:61]
	v_mfma_f32_16x16x32_bf16 v[50:53], v[168:171], v[176:179], v[50:53]
	v_mfma_f32_16x16x32_bf16 v[50:53], v[172:175], v[180:183], v[50:53]
	v_mfma_f32_16x16x32_bf16 v[34:37], v[168:171], v[184:187], v[34:37]
	v_mfma_f32_16x16x32_bf16 v[34:37], v[172:175], v[188:191], v[34:37]
	v_mfma_f32_16x16x32_bf16 v[42:45], v[160:163], v[184:187], v[42:45]
	v_mfma_f32_16x16x32_bf16 v[42:45], v[164:167], v[188:191], v[42:45]
	v_mfma_f32_16x16x32_bf16 v[38:41], v[152:155], v[184:187], v[38:41]
	v_mfma_f32_16x16x32_bf16 v[38:41], v[156:159], v[188:191], v[38:41]
	v_mfma_f32_16x16x32_bf16 v[46:49], v[144:147], v[184:187], v[46:49]
	v_mfma_f32_16x16x32_bf16 v[46:49], v[148:151], v[188:191], v[46:49]
	v_mfma_f32_16x16x32_bf16 v[30:33], v[144:147], v[192:195], v[30:33]
	v_mfma_f32_16x16x32_bf16 v[30:33], v[148:151], v[196:199], v[30:33]
	v_mfma_f32_16x16x32_bf16 v[22:25], v[152:155], v[192:195], v[22:25]
	v_mfma_f32_16x16x32_bf16 v[22:25], v[156:159], v[196:199], v[22:25]
	v_mfma_f32_16x16x32_bf16 v[26:29], v[160:163], v[192:195], v[26:29]
	v_mfma_f32_16x16x32_bf16 v[26:29], v[164:167], v[196:199], v[26:29]
	v_mfma_f32_16x16x32_bf16 v[18:21], v[168:171], v[192:195], v[18:21]
	v_mfma_f32_16x16x32_bf16 v[18:21], v[172:175], v[196:199], v[18:21]
	v_mfma_f32_16x16x32_bf16 v[2:5], v[168:171], v[200:203], v[2:5]
	v_mfma_f32_16x16x32_bf16 v[2:5], v[172:175], v[204:207], v[2:5]
	v_mfma_f32_16x16x32_bf16 v[10:13], v[160:163], v[200:203], v[10:13]
	v_mfma_f32_16x16x32_bf16 v[10:13], v[164:167], v[204:207], v[10:13]
	v_mfma_f32_16x16x32_bf16 v[6:9], v[152:155], v[200:203], v[6:9]
	v_mfma_f32_16x16x32_bf16 v[6:9], v[156:159], v[204:207], v[6:9]
	v_mfma_f32_16x16x32_bf16 v[14:17], v[144:147], v[200:203], v[14:17]
	v_mfma_f32_16x16x32_bf16 v[14:17], v[148:151], v[204:207], v[14:17]
	s_barrier
	ds_read_b128 v[144:147], v141
	ds_read_b128 v[148:151], v141 offset:1024
	ds_read_b128 v[152:155], v141 offset:2048
	ds_read_b128 v[156:159], v141 offset:3072
	ds_read_b128 v[160:163], v142
	ds_read_b128 v[164:167], v142 offset:1024
	ds_read_b128 v[168:171], v142 offset:2048
	ds_read_b128 v[172:175], v142 offset:3072
	s_mov_b32 m0, s50
	s_add_i32 s80, s77, 0x100000
	ds_read_b128 v[176:179], v140 offset:32768
	ds_read_b128 v[180:183], v140 offset:33792
	ds_read_b128 v[184:187], v140 offset:34816
	ds_read_b128 v[188:191], v140 offset:35840
	ds_read_b128 v[192:195], v140 offset:36864
	ds_read_b128 v[196:199], v140 offset:37888
	ds_read_b128 v[200:203], v140 offset:38912
	ds_read_b128 v[204:207], v140 offset:39936
	buffer_load_dwordx4 v136, s[16:19], s80 offen lds
	s_add_i32 s80, s77, 0x180000
	s_mov_b32 m0, s51
	s_nop 0
	buffer_load_dwordx4 v136, s[16:19], s80 offen lds
	s_waitcnt vmcnt(8)
	s_waitcnt lgkmcnt(0)
	v_mfma_f32_16x16x32_bf16 v[118:121], v[144:147], v[176:179], v[118:121]
	s_barrier
	v_mfma_f32_16x16x32_bf16 v[118:121], v[148:151], v[180:183], v[118:121]
	v_mfma_f32_16x16x32_bf16 v[114:117], v[152:155], v[176:179], v[114:117]
	v_mfma_f32_16x16x32_bf16 v[114:117], v[156:159], v[180:183], v[114:117]
	v_mfma_f32_16x16x32_bf16 v[126:129], v[160:163], v[176:179], v[126:129]
	v_mfma_f32_16x16x32_bf16 v[126:129], v[164:167], v[180:183], v[126:129]
	v_mfma_f32_16x16x32_bf16 v[122:125], v[168:171], v[176:179], v[122:125]
	v_mfma_f32_16x16x32_bf16 v[122:125], v[172:175], v[180:183], v[122:125]
	v_mfma_f32_16x16x32_bf16 v[98:101], v[168:171], v[184:187], v[98:101]
	v_mfma_f32_16x16x32_bf16 v[98:101], v[172:175], v[188:191], v[98:101]
	v_mfma_f32_16x16x32_bf16 v[106:109], v[160:163], v[184:187], v[106:109]
	v_mfma_f32_16x16x32_bf16 v[106:109], v[164:167], v[188:191], v[106:109]
	v_mfma_f32_16x16x32_bf16 v[102:105], v[152:155], v[184:187], v[102:105]
	v_mfma_f32_16x16x32_bf16 v[102:105], v[156:159], v[188:191], v[102:105]
	v_mfma_f32_16x16x32_bf16 v[110:113], v[144:147], v[184:187], v[110:113]
	v_mfma_f32_16x16x32_bf16 v[110:113], v[148:151], v[188:191], v[110:113]
	v_mfma_f32_16x16x32_bf16 v[94:97], v[144:147], v[192:195], v[94:97]
	v_mfma_f32_16x16x32_bf16 v[94:97], v[148:151], v[196:199], v[94:97]
	v_mfma_f32_16x16x32_bf16 v[86:89], v[152:155], v[192:195], v[86:89]
	v_mfma_f32_16x16x32_bf16 v[86:89], v[156:159], v[196:199], v[86:89]
	v_mfma_f32_16x16x32_bf16 v[90:93], v[160:163], v[192:195], v[90:93]
	v_mfma_f32_16x16x32_bf16 v[90:93], v[164:167], v[196:199], v[90:93]
	v_mfma_f32_16x16x32_bf16 v[82:85], v[168:171], v[192:195], v[82:85]
	v_mfma_f32_16x16x32_bf16 v[82:85], v[172:175], v[196:199], v[82:85]
	v_mfma_f32_16x16x32_bf16 v[70:73], v[168:171], v[200:203], v[70:73]
	v_mfma_f32_16x16x32_bf16 v[70:73], v[172:175], v[204:207], v[70:73]
	v_mfma_f32_16x16x32_bf16 v[74:77], v[160:163], v[200:203], v[74:77]
	v_mfma_f32_16x16x32_bf16 v[74:77], v[164:167], v[204:207], v[74:77]
	v_mfma_f32_16x16x32_bf16 v[66:69], v[152:155], v[200:203], v[66:69]
	v_mfma_f32_16x16x32_bf16 v[66:69], v[156:159], v[204:207], v[66:69]
	v_mfma_f32_16x16x32_bf16 v[78:81], v[144:147], v[200:203], v[78:81]
	v_mfma_f32_16x16x32_bf16 v[78:81], v[148:151], v[204:207], v[78:81]
	s_barrier
	s_mov_b32 m0, s53
	s_or_b32 s80, s79, 0x80
	ds_read_b128 v[176:179], v140 offset:49152
	ds_read_b128 v[180:183], v140 offset:50176
	ds_read_b128 v[184:187], v140 offset:51200
	ds_read_b128 v[188:191], v140 offset:52224
	ds_read_b128 v[192:195], v140 offset:53248
	ds_read_b128 v[196:199], v140 offset:54272
	ds_read_b128 v[200:203], v140 offset:55296
	ds_read_b128 v[204:207], v140 offset:56320
	buffer_load_dwordx4 v137, s[12:15], s80 offen lds
	s_add_i32 s80, s79, 0x80080
	s_mov_b32 m0, s54
	s_add_i32 s77, s77, 0x80080
	buffer_load_dwordx4 v137, s[12:15], s80 offen lds
	s_add_i32 s80, s79, 0x100080
	s_mov_b32 m0, s57
	s_add_i32 s79, s79, 0x180080
	buffer_load_dwordx4 v137, s[12:15], s80 offen lds
	s_mov_b32 m0, s58
	s_nop 0
	buffer_load_dwordx4 v137, s[12:15], s79 offen lds
	s_mov_b32 m0, s55
	s_nop 0
	buffer_load_dwordx4 v136, s[16:19], s78 offen lds
	s_mov_b32 m0, s56
	s_nop 0
	buffer_load_dwordx4 v136, s[16:19], s77 offen lds
	s_waitcnt vmcnt(8)
	s_waitcnt lgkmcnt(0)
	v_mfma_f32_16x16x32_bf16 v[62:65], v[144:147], v[176:179], v[62:65]
	s_barrier
	v_mfma_f32_16x16x32_bf16 v[62:65], v[148:151], v[180:183], v[62:65]
	v_mfma_f32_16x16x32_bf16 v[54:57], v[152:155], v[176:179], v[54:57]
	v_mfma_f32_16x16x32_bf16 v[54:57], v[156:159], v[180:183], v[54:57]
	v_mfma_f32_16x16x32_bf16 v[58:61], v[160:163], v[176:179], v[58:61]
	v_mfma_f32_16x16x32_bf16 v[58:61], v[164:167], v[180:183], v[58:61]
	v_mfma_f32_16x16x32_bf16 v[50:53], v[168:171], v[176:179], v[50:53]
	v_mfma_f32_16x16x32_bf16 v[50:53], v[172:175], v[180:183], v[50:53]
	v_mfma_f32_16x16x32_bf16 v[34:37], v[168:171], v[184:187], v[34:37]
	v_mfma_f32_16x16x32_bf16 v[34:37], v[172:175], v[188:191], v[34:37]
	v_mfma_f32_16x16x32_bf16 v[42:45], v[160:163], v[184:187], v[42:45]
	v_mfma_f32_16x16x32_bf16 v[42:45], v[164:167], v[188:191], v[42:45]
	v_mfma_f32_16x16x32_bf16 v[38:41], v[152:155], v[184:187], v[38:41]
	v_mfma_f32_16x16x32_bf16 v[38:41], v[156:159], v[188:191], v[38:41]
	v_mfma_f32_16x16x32_bf16 v[46:49], v[144:147], v[184:187], v[46:49]
	v_mfma_f32_16x16x32_bf16 v[46:49], v[148:151], v[188:191], v[46:49]
	v_mfma_f32_16x16x32_bf16 v[30:33], v[144:147], v[192:195], v[30:33]
	v_mfma_f32_16x16x32_bf16 v[30:33], v[148:151], v[196:199], v[30:33]
	v_mfma_f32_16x16x32_bf16 v[22:25], v[152:155], v[192:195], v[22:25]
	v_mfma_f32_16x16x32_bf16 v[22:25], v[156:159], v[196:199], v[22:25]
	v_mfma_f32_16x16x32_bf16 v[26:29], v[160:163], v[192:195], v[26:29]
	v_mfma_f32_16x16x32_bf16 v[26:29], v[164:167], v[196:199], v[26:29]
	v_mfma_f32_16x16x32_bf16 v[18:21], v[168:171], v[192:195], v[18:21]
	v_mfma_f32_16x16x32_bf16 v[18:21], v[172:175], v[196:199], v[18:21]
	v_mfma_f32_16x16x32_bf16 v[2:5], v[168:171], v[200:203], v[2:5]
	v_mfma_f32_16x16x32_bf16 v[2:5], v[172:175], v[204:207], v[2:5]
	v_mfma_f32_16x16x32_bf16 v[10:13], v[160:163], v[200:203], v[10:13]
	v_mfma_f32_16x16x32_bf16 v[10:13], v[164:167], v[204:207], v[10:13]
	v_mfma_f32_16x16x32_bf16 v[6:9], v[152:155], v[200:203], v[6:9]
	v_mfma_f32_16x16x32_bf16 v[6:9], v[156:159], v[204:207], v[6:9]
	v_mfma_f32_16x16x32_bf16 v[14:17], v[144:147], v[200:203], v[14:17]
	v_mfma_f32_16x16x32_bf16 v[14:17], v[148:151], v[204:207], v[14:17]
	s_barrier
	s_add_i32 s76, s76, 2
	s_addk_i32 s74, 0x100
	s_addk_i32 s75, 0x100
	s_cmp_ge_i32 s76, s27
	s_cbranch_scc0 .LBB0_1382
	s_and_b64 vcc, exec, s[42:43]
	s_cbranch_vccz .LBB0_1385

.LBB0_1402:
	ds_read_b128 v[146:149], v138
	ds_read_b128 v[150:153], v138 offset:1024
	ds_read_b128 v[154:157], v138 offset:2048
	ds_read_b128 v[158:161], v138 offset:3072
	ds_read_b128 v[162:165], v139
	ds_read_b128 v[166:169], v139 offset:1024
	ds_read_b128 v[170:173], v139 offset:2048
	ds_read_b128 v[174:177], v139 offset:3072
	s_add_i32 s22, s75, 0xffe80080
	s_cmp_eq_u32 s62, s77
	s_cselect_b32 s78, s73, s22
	s_cselect_b32 s80, s74, s76
	s_or_b32 s79, s78, 0x80
	s_add_i32 s22, s75, 0xfff80000
	s_mov_b32 m0, s63
	ds_read_b128 v[178:181], v140
	ds_read_b128 v[182:185], v140 offset:1024
	ds_read_b128 v[186:189], v140 offset:2048
	ds_read_b128 v[190:193], v140 offset:3072
	ds_read_b128 v[194:197], v140 offset:4096
	ds_read_b128 v[198:201], v140 offset:5120
	ds_read_b128 v[202:205], v140 offset:6144
	ds_read_b128 v[206:209], v140 offset:7168
	buffer_load_dwordx4 v136, s[16:19], s22 offen lds
	s_mov_b32 m0, s64
	s_nop 0
	buffer_load_dwordx4 v136, s[16:19], s75 offen lds
	s_waitcnt vmcnt(8)
	s_waitcnt lgkmcnt(0)
	v_mfma_f32_16x16x32_bf16 v[118:121], v[146:149], v[178:181], v[118:121]
	s_barrier
	v_mfma_f32_16x16x32_bf16 v[118:121], v[150:153], v[182:185], v[118:121]
	v_mfma_f32_16x16x32_bf16 v[114:117], v[154:157], v[178:181], v[114:117]
	v_mfma_f32_16x16x32_bf16 v[114:117], v[158:161], v[182:185], v[114:117]
	v_mfma_f32_16x16x32_bf16 v[126:129], v[162:165], v[178:181], v[126:129]
	v_mfma_f32_16x16x32_bf16 v[126:129], v[166:169], v[182:185], v[126:129]
	v_mfma_f32_16x16x32_bf16 v[122:125], v[170:173], v[178:181], v[122:125]
	v_mfma_f32_16x16x32_bf16 v[122:125], v[174:177], v[182:185], v[122:125]
	v_mfma_f32_16x16x32_bf16 v[98:101], v[170:173], v[186:189], v[98:101]
	v_mfma_f32_16x16x32_bf16 v[98:101], v[174:177], v[190:193], v[98:101]
	v_mfma_f32_16x16x32_bf16 v[106:109], v[162:165], v[186:189], v[106:109]
	v_mfma_f32_16x16x32_bf16 v[106:109], v[166:169], v[190:193], v[106:109]
	v_mfma_f32_16x16x32_bf16 v[102:105], v[154:157], v[186:189], v[102:105]
	v_mfma_f32_16x16x32_bf16 v[102:105], v[158:161], v[190:193], v[102:105]
	v_mfma_f32_16x16x32_bf16 v[110:113], v[146:149], v[186:189], v[110:113]
	v_mfma_f32_16x16x32_bf16 v[110:113], v[150:153], v[190:193], v[110:113]
	v_mfma_f32_16x16x32_bf16 v[94:97], v[146:149], v[194:197], v[94:97]
	v_mfma_f32_16x16x32_bf16 v[94:97], v[150:153], v[198:201], v[94:97]
	v_mfma_f32_16x16x32_bf16 v[86:89], v[154:157], v[194:197], v[86:89]
	v_mfma_f32_16x16x32_bf16 v[86:89], v[158:161], v[198:201], v[86:89]
	v_mfma_f32_16x16x32_bf16 v[90:93], v[162:165], v[194:197], v[90:93]
	v_mfma_f32_16x16x32_bf16 v[90:93], v[166:169], v[198:201], v[90:93]
	v_mfma_f32_16x16x32_bf16 v[82:85], v[170:173], v[194:197], v[82:85]
	v_mfma_f32_16x16x32_bf16 v[82:85], v[174:177], v[198:201], v[82:85]
	v_mfma_f32_16x16x32_bf16 v[70:73], v[170:173], v[202:205], v[70:73]
	v_mfma_f32_16x16x32_bf16 v[70:73], v[174:177], v[206:209], v[70:73]
	v_mfma_f32_16x16x32_bf16 v[74:77], v[162:165], v[202:205], v[74:77]
	v_mfma_f32_16x16x32_bf16 v[74:77], v[166:169], v[206:209], v[74:77]
	v_mfma_f32_16x16x32_bf16 v[66:69], v[154:157], v[202:205], v[66:69]
	v_mfma_f32_16x16x32_bf16 v[66:69], v[158:161], v[206:209], v[66:69]
	v_mfma_f32_16x16x32_bf16 v[78:81], v[146:149], v[202:205], v[78:81]
	v_mfma_f32_16x16x32_bf16 v[78:81], v[150:153], v[206:209], v[78:81]
	s_barrier
	s_mov_b32 m0, s31
	s_mov_b32 s22, s18
	s_mov_b32 s23, s19
	ds_read_b128 v[178:181], v140 offset:16384
	ds_read_b128 v[182:185], v140 offset:17408
	ds_read_b128 v[186:189], v140 offset:18432
	ds_read_b128 v[190:193], v140 offset:19456
	ds_read_b128 v[194:197], v140 offset:20480
	ds_read_b128 v[198:201], v140 offset:21504
	ds_read_b128 v[202:205], v140 offset:22528
	ds_read_b128 v[206:209], v140 offset:23552
	buffer_load_dwordx4 v137, s[20:23], s80 offen lds
	s_add_i32 s81, s80, 0x80000
	s_mov_b32 m0, s48
	s_nop 0
	buffer_load_dwordx4 v137, s[20:23], s81 offen lds
	s_add_i32 s81, s80, 0x100000
	s_mov_b32 m0, s49
	s_nop 0
	buffer_load_dwordx4 v137, s[20:23], s81 offen lds
	s_add_i32 s81, s80, 0x180000
	s_mov_b32 m0, s50
	s_nop 0
	buffer_load_dwordx4 v137, s[20:23], s81 offen lds
	s_mov_b32 m0, s30
	s_add_i32 s81, s78, 0x80000
	buffer_load_dwordx4 v136, s[16:19], s78 offen lds
	s_mov_b32 m0, s51
	s_nop 0
	buffer_load_dwordx4 v136, s[16:19], s81 offen lds
	s_waitcnt vmcnt(8)
	s_waitcnt lgkmcnt(0)
	v_mfma_f32_16x16x32_bf16 v[62:65], v[146:149], v[178:181], v[62:65]
	s_barrier
	v_mfma_f32_16x16x32_bf16 v[62:65], v[150:153], v[182:185], v[62:65]
	v_mfma_f32_16x16x32_bf16 v[54:57], v[154:157], v[178:181], v[54:57]
	v_mfma_f32_16x16x32_bf16 v[54:57], v[158:161], v[182:185], v[54:57]
	v_mfma_f32_16x16x32_bf16 v[58:61], v[162:165], v[178:181], v[58:61]
	v_mfma_f32_16x16x32_bf16 v[58:61], v[166:169], v[182:185], v[58:61]
	v_mfma_f32_16x16x32_bf16 v[50:53], v[170:173], v[178:181], v[50:53]
	v_mfma_f32_16x16x32_bf16 v[50:53], v[174:177], v[182:185], v[50:53]
	v_mfma_f32_16x16x32_bf16 v[34:37], v[170:173], v[186:189], v[34:37]
	v_mfma_f32_16x16x32_bf16 v[34:37], v[174:177], v[190:193], v[34:37]
	v_mfma_f32_16x16x32_bf16 v[42:45], v[162:165], v[186:189], v[42:45]
	v_mfma_f32_16x16x32_bf16 v[42:45], v[166:169], v[190:193], v[42:45]
	v_mfma_f32_16x16x32_bf16 v[38:41], v[154:157], v[186:189], v[38:41]
	v_mfma_f32_16x16x32_bf16 v[38:41], v[158:161], v[190:193], v[38:41]
	v_mfma_f32_16x16x32_bf16 v[46:49], v[146:149], v[186:189], v[46:49]
	v_mfma_f32_16x16x32_bf16 v[46:49], v[150:153], v[190:193], v[46:49]
	v_mfma_f32_16x16x32_bf16 v[30:33], v[146:149], v[194:197], v[30:33]
	v_mfma_f32_16x16x32_bf16 v[30:33], v[150:153], v[198:201], v[30:33]
	v_mfma_f32_16x16x32_bf16 v[22:25], v[154:157], v[194:197], v[22:25]
	v_mfma_f32_16x16x32_bf16 v[22:25], v[158:161], v[198:201], v[22:25]
	v_mfma_f32_16x16x32_bf16 v[26:29], v[162:165], v[194:197], v[26:29]
	v_mfma_f32_16x16x32_bf16 v[26:29], v[166:169], v[198:201], v[26:29]
	v_mfma_f32_16x16x32_bf16 v[18:21], v[170:173], v[194:197], v[18:21]
	v_mfma_f32_16x16x32_bf16 v[18:21], v[174:177], v[198:201], v[18:21]
	v_mfma_f32_16x16x32_bf16 v[2:5], v[170:173], v[202:205], v[2:5]
	v_mfma_f32_16x16x32_bf16 v[2:5], v[174:177], v[206:209], v[2:5]
	v_mfma_f32_16x16x32_bf16 v[10:13], v[162:165], v[202:205], v[10:13]
	v_mfma_f32_16x16x32_bf16 v[10:13], v[166:169], v[206:209], v[10:13]
	v_mfma_f32_16x16x32_bf16 v[6:9], v[154:157], v[202:205], v[6:9]
	v_mfma_f32_16x16x32_bf16 v[6:9], v[158:161], v[206:209], v[6:9]
	v_mfma_f32_16x16x32_bf16 v[14:17], v[146:149], v[202:205], v[14:17]
	v_mfma_f32_16x16x32_bf16 v[14:17], v[150:153], v[206:209], v[14:17]
	s_barrier
	ds_read_b128 v[146:149], v141
	ds_read_b128 v[150:153], v141 offset:1024
	ds_read_b128 v[154:157], v141 offset:2048
	ds_read_b128 v[158:161], v141 offset:3072
	ds_read_b128 v[162:165], v142
	ds_read_b128 v[166:169], v142 offset:1024
	ds_read_b128 v[170:173], v142 offset:2048
	ds_read_b128 v[174:177], v142 offset:3072
	s_mov_b32 m0, s52
	s_add_i32 s81, s78, 0x100000
	ds_read_b128 v[178:181], v140 offset:32768
	ds_read_b128 v[182:185], v140 offset:33792
	ds_read_b128 v[186:189], v140 offset:34816
	ds_read_b128 v[190:193], v140 offset:35840
	ds_read_b128 v[194:197], v140 offset:36864
	ds_read_b128 v[198:201], v140 offset:37888
	ds_read_b128 v[202:205], v140 offset:38912
	ds_read_b128 v[206:209], v140 offset:39936
	buffer_load_dwordx4 v136, s[16:19], s81 offen lds
	s_add_i32 s81, s78, 0x180000
	s_mov_b32 m0, s53
	s_nop 0
	buffer_load_dwordx4 v136, s[16:19], s81 offen lds
	s_waitcnt vmcnt(8)
	s_waitcnt lgkmcnt(0)
	v_mfma_f32_16x16x32_bf16 v[118:121], v[146:149], v[178:181], v[118:121]
	s_barrier
	v_mfma_f32_16x16x32_bf16 v[118:121], v[150:153], v[182:185], v[118:121]
	v_mfma_f32_16x16x32_bf16 v[114:117], v[154:157], v[178:181], v[114:117]
	v_mfma_f32_16x16x32_bf16 v[114:117], v[158:161], v[182:185], v[114:117]
	v_mfma_f32_16x16x32_bf16 v[126:129], v[162:165], v[178:181], v[126:129]
	v_mfma_f32_16x16x32_bf16 v[126:129], v[166:169], v[182:185], v[126:129]
	v_mfma_f32_16x16x32_bf16 v[122:125], v[170:173], v[178:181], v[122:125]
	v_mfma_f32_16x16x32_bf16 v[122:125], v[174:177], v[182:185], v[122:125]
	v_mfma_f32_16x16x32_bf16 v[98:101], v[170:173], v[186:189], v[98:101]
	v_mfma_f32_16x16x32_bf16 v[98:101], v[174:177], v[190:193], v[98:101]
	v_mfma_f32_16x16x32_bf16 v[106:109], v[162:165], v[186:189], v[106:109]
	v_mfma_f32_16x16x32_bf16 v[106:109], v[166:169], v[190:193], v[106:109]
	v_mfma_f32_16x16x32_bf16 v[102:105], v[154:157], v[186:189], v[102:105]
	v_mfma_f32_16x16x32_bf16 v[102:105], v[158:161], v[190:193], v[102:105]
	v_mfma_f32_16x16x32_bf16 v[110:113], v[146:149], v[186:189], v[110:113]
	v_mfma_f32_16x16x32_bf16 v[110:113], v[150:153], v[190:193], v[110:113]
	v_mfma_f32_16x16x32_bf16 v[94:97], v[146:149], v[194:197], v[94:97]
	v_mfma_f32_16x16x32_bf16 v[94:97], v[150:153], v[198:201], v[94:97]
	v_mfma_f32_16x16x32_bf16 v[86:89], v[154:157], v[194:197], v[86:89]
	v_mfma_f32_16x16x32_bf16 v[86:89], v[158:161], v[198:201], v[86:89]
	v_mfma_f32_16x16x32_bf16 v[90:93], v[162:165], v[194:197], v[90:93]
	v_mfma_f32_16x16x32_bf16 v[90:93], v[166:169], v[198:201], v[90:93]
	v_mfma_f32_16x16x32_bf16 v[82:85], v[170:173], v[194:197], v[82:85]
	v_mfma_f32_16x16x32_bf16 v[82:85], v[174:177], v[198:201], v[82:85]
	v_mfma_f32_16x16x32_bf16 v[70:73], v[170:173], v[202:205], v[70:73]
	v_mfma_f32_16x16x32_bf16 v[70:73], v[174:177], v[206:209], v[70:73]
	v_mfma_f32_16x16x32_bf16 v[74:77], v[162:165], v[202:205], v[74:77]
	v_mfma_f32_16x16x32_bf16 v[74:77], v[166:169], v[206:209], v[74:77]
	v_mfma_f32_16x16x32_bf16 v[66:69], v[154:157], v[202:205], v[66:69]
	v_mfma_f32_16x16x32_bf16 v[66:69], v[158:161], v[206:209], v[66:69]
	v_mfma_f32_16x16x32_bf16 v[78:81], v[146:149], v[202:205], v[78:81]
	v_mfma_f32_16x16x32_bf16 v[78:81], v[150:153], v[206:209], v[78:81]
	s_barrier
	s_mov_b32 m0, s54
	s_or_b32 s81, s80, 0x80
	ds_read_b128 v[178:181], v140 offset:49152
	ds_read_b128 v[182:185], v140 offset:50176
	ds_read_b128 v[186:189], v140 offset:51200
	ds_read_b128 v[190:193], v140 offset:52224
	ds_read_b128 v[194:197], v140 offset:53248
	ds_read_b128 v[198:201], v140 offset:54272
	ds_read_b128 v[202:205], v140 offset:55296
	ds_read_b128 v[206:209], v140 offset:56320
	buffer_load_dwordx4 v137, s[20:23], s81 offen lds
	s_add_i32 s81, s80, 0x80080
	s_mov_b32 m0, s55
	s_add_i32 s78, s78, 0x80080
	buffer_load_dwordx4 v137, s[20:23], s81 offen lds
	s_add_i32 s81, s80, 0x100080
	s_mov_b32 m0, s58
	s_add_i32 s80, s80, 0x180080
	buffer_load_dwordx4 v137, s[20:23], s81 offen lds
	s_mov_b32 m0, s59
	s_nop 0
	buffer_load_dwordx4 v137, s[20:23], s80 offen lds
	s_mov_b32 m0, s56
	s_nop 0
	buffer_load_dwordx4 v136, s[16:19], s79 offen lds
	s_mov_b32 m0, s57
	s_nop 0
	buffer_load_dwordx4 v136, s[16:19], s78 offen lds
	s_waitcnt vmcnt(8)
	s_waitcnt lgkmcnt(0)
	v_mfma_f32_16x16x32_bf16 v[62:65], v[146:149], v[178:181], v[62:65]
	s_barrier
	v_mfma_f32_16x16x32_bf16 v[62:65], v[150:153], v[182:185], v[62:65]
	v_mfma_f32_16x16x32_bf16 v[54:57], v[154:157], v[178:181], v[54:57]
	v_mfma_f32_16x16x32_bf16 v[54:57], v[158:161], v[182:185], v[54:57]
	v_mfma_f32_16x16x32_bf16 v[58:61], v[162:165], v[178:181], v[58:61]
	v_mfma_f32_16x16x32_bf16 v[58:61], v[166:169], v[182:185], v[58:61]
	v_mfma_f32_16x16x32_bf16 v[50:53], v[170:173], v[178:181], v[50:53]
	v_mfma_f32_16x16x32_bf16 v[50:53], v[174:177], v[182:185], v[50:53]
	v_mfma_f32_16x16x32_bf16 v[34:37], v[170:173], v[186:189], v[34:37]
	v_mfma_f32_16x16x32_bf16 v[34:37], v[174:177], v[190:193], v[34:37]
	v_mfma_f32_16x16x32_bf16 v[42:45], v[162:165], v[186:189], v[42:45]
	v_mfma_f32_16x16x32_bf16 v[42:45], v[166:169], v[190:193], v[42:45]
	v_mfma_f32_16x16x32_bf16 v[38:41], v[154:157], v[186:189], v[38:41]
	v_mfma_f32_16x16x32_bf16 v[38:41], v[158:161], v[190:193], v[38:41]
	v_mfma_f32_16x16x32_bf16 v[46:49], v[146:149], v[186:189], v[46:49]
	v_mfma_f32_16x16x32_bf16 v[46:49], v[150:153], v[190:193], v[46:49]
	v_mfma_f32_16x16x32_bf16 v[30:33], v[146:149], v[194:197], v[30:33]
	v_mfma_f32_16x16x32_bf16 v[30:33], v[150:153], v[198:201], v[30:33]
	v_mfma_f32_16x16x32_bf16 v[22:25], v[154:157], v[194:197], v[22:25]
	v_mfma_f32_16x16x32_bf16 v[22:25], v[158:161], v[198:201], v[22:25]
	v_mfma_f32_16x16x32_bf16 v[26:29], v[162:165], v[194:197], v[26:29]
	v_mfma_f32_16x16x32_bf16 v[26:29], v[166:169], v[198:201], v[26:29]
	v_mfma_f32_16x16x32_bf16 v[18:21], v[170:173], v[194:197], v[18:21]
	v_mfma_f32_16x16x32_bf16 v[18:21], v[174:177], v[198:201], v[18:21]
	v_mfma_f32_16x16x32_bf16 v[2:5], v[170:173], v[202:205], v[2:5]
	v_mfma_f32_16x16x32_bf16 v[2:5], v[174:177], v[206:209], v[2:5]
	v_mfma_f32_16x16x32_bf16 v[10:13], v[162:165], v[202:205], v[10:13]
	v_mfma_f32_16x16x32_bf16 v[10:13], v[166:169], v[206:209], v[10:13]
	v_mfma_f32_16x16x32_bf16 v[6:9], v[154:157], v[202:205], v[6:9]
	v_mfma_f32_16x16x32_bf16 v[6:9], v[158:161], v[206:209], v[6:9]
	v_mfma_f32_16x16x32_bf16 v[14:17], v[146:149], v[202:205], v[14:17]
	v_mfma_f32_16x16x32_bf16 v[14:17], v[150:153], v[206:209], v[14:17]
	s_barrier
	s_add_i32 s77, s77, 2
	s_addk_i32 s75, 0x100
	s_addk_i32 s76, 0x100
	s_cmp_ge_i32 s77, s13
	s_cbranch_scc0 .LBB0_1402
	s_and_b64 vcc, exec, s[46:47]
	s_cbranch_vccz .LBB0_1405

.LBB0_1519:
	ds_read_b128 v[134:137], v208
	ds_read_b128 v[138:141], v208 offset:1024
	ds_read_b128 v[142:145], v208 offset:2048
	ds_read_b128 v[146:149], v208 offset:3072
	ds_read_b128 v[150:153], v209
	ds_read_b128 v[154:157], v209 offset:1024
	ds_read_b128 v[158:161], v209 offset:2048
	ds_read_b128 v[162:165], v209 offset:3072
	s_add_i32 s18, s80, 0xffbf8080
	s_cmp_eq_u32 s65, s82
	s_cselect_b32 s83, s6, s18
	s_cselect_b32 s85, s7, s81
	s_or_b32 s84, s83, 0x80
	s_add_i32 s18, s80, 0xffea8000
	s_mov_b32 m0, s66
	ds_read_b128 v[166:169], v210
	ds_read_b128 v[170:173], v210 offset:1024
	ds_read_b128 v[174:177], v210 offset:2048
	ds_read_b128 v[178:181], v210 offset:3072
	ds_read_b128 v[182:185], v210 offset:4096
	ds_read_b128 v[186:189], v210 offset:5120
	ds_read_b128 v[190:193], v210 offset:6144
	ds_read_b128 v[194:197], v210 offset:7168
	buffer_load_dwordx4 v206, s[12:15], s18 offen lds
	s_mov_b32 m0, s69
	s_nop 0
	buffer_load_dwordx4 v206, s[12:15], s80 offen lds
	s_waitcnt vmcnt(8)
	s_waitcnt lgkmcnt(0)
	v_mfma_f32_16x16x32_bf16 v[126:129], v[134:137], v[166:169], v[126:129]
	s_barrier
	v_mfma_f32_16x16x32_bf16 v[126:129], v[138:141], v[170:173], v[126:129]
	v_mfma_f32_16x16x32_bf16 v[122:125], v[142:145], v[166:169], v[122:125]
	v_mfma_f32_16x16x32_bf16 v[122:125], v[146:149], v[170:173], v[122:125]
	v_mfma_f32_16x16x32_bf16 v[110:113], v[150:153], v[166:169], v[110:113]
	v_mfma_f32_16x16x32_bf16 v[110:113], v[154:157], v[170:173], v[110:113]
	v_mfma_f32_16x16x32_bf16 v[102:105], v[158:161], v[166:169], v[102:105]
	v_mfma_f32_16x16x32_bf16 v[102:105], v[162:165], v[170:173], v[102:105]
	v_mfma_f32_16x16x32_bf16 v[86:89], v[158:161], v[174:177], v[86:89]
	v_mfma_f32_16x16x32_bf16 v[86:89], v[162:165], v[178:181], v[86:89]
	v_mfma_f32_16x16x32_bf16 v[94:97], v[150:153], v[174:177], v[94:97]
	v_mfma_f32_16x16x32_bf16 v[94:97], v[154:157], v[178:181], v[94:97]
	v_mfma_f32_16x16x32_bf16 v[114:117], v[142:145], v[174:177], v[114:117]
	v_mfma_f32_16x16x32_bf16 v[114:117], v[146:149], v[178:181], v[114:117]
	v_mfma_f32_16x16x32_bf16 v[118:121], v[134:137], v[174:177], v[118:121]
	v_mfma_f32_16x16x32_bf16 v[118:121], v[138:141], v[178:181], v[118:121]
	v_mfma_f32_16x16x32_bf16 v[106:109], v[134:137], v[182:185], v[106:109]
	v_mfma_f32_16x16x32_bf16 v[106:109], v[138:141], v[186:189], v[106:109]
	v_mfma_f32_16x16x32_bf16 v[98:101], v[142:145], v[182:185], v[98:101]
	v_mfma_f32_16x16x32_bf16 v[98:101], v[146:149], v[186:189], v[98:101]
	v_mfma_f32_16x16x32_bf16 v[78:81], v[150:153], v[182:185], v[78:81]
	v_mfma_f32_16x16x32_bf16 v[78:81], v[154:157], v[186:189], v[78:81]
	v_mfma_f32_16x16x32_bf16 v[74:77], v[158:161], v[182:185], v[74:77]
	v_mfma_f32_16x16x32_bf16 v[74:77], v[162:165], v[186:189], v[74:77]
	v_mfma_f32_16x16x32_bf16 v[66:69], v[158:161], v[190:193], v[66:69]
	v_mfma_f32_16x16x32_bf16 v[66:69], v[162:165], v[194:197], v[66:69]
	v_mfma_f32_16x16x32_bf16 v[70:73], v[150:153], v[190:193], v[70:73]
	v_mfma_f32_16x16x32_bf16 v[70:73], v[154:157], v[194:197], v[70:73]
	v_mfma_f32_16x16x32_bf16 v[82:85], v[142:145], v[190:193], v[82:85]
	v_mfma_f32_16x16x32_bf16 v[82:85], v[146:149], v[194:197], v[82:85]
	v_mfma_f32_16x16x32_bf16 v[90:93], v[134:137], v[190:193], v[90:93]
	v_mfma_f32_16x16x32_bf16 v[90:93], v[138:141], v[194:197], v[90:93]
	s_barrier
	s_mov_b32 m0, s27
	s_mov_b32 s18, s14
	s_mov_b32 s19, s15
	ds_read_b128 v[166:169], v210 offset:16384
	ds_read_b128 v[170:173], v210 offset:17408
	ds_read_b128 v[174:177], v210 offset:18432
	ds_read_b128 v[178:181], v210 offset:19456
	ds_read_b128 v[182:185], v210 offset:20480
	ds_read_b128 v[186:189], v210 offset:21504
	ds_read_b128 v[190:193], v210 offset:22528
	ds_read_b128 v[194:197], v210 offset:23552
	buffer_load_dwordx4 v207, s[16:19], s85 offen lds
	s_add_i32 s86, s85, 0x158000
	s_mov_b32 m0, s30
	s_nop 0
	buffer_load_dwordx4 v207, s[16:19], s86 offen lds
	s_add_i32 s86, s85, 0x2b0000
	s_mov_b32 m0, s31
	s_nop 0
	buffer_load_dwordx4 v207, s[16:19], s86 offen lds
	s_add_i32 s86, s85, 0x408000
	s_mov_b32 m0, s50
	s_nop 0
	buffer_load_dwordx4 v207, s[16:19], s86 offen lds
	s_mov_b32 m0, s25
	s_add_i32 s86, s83, 0x158000
	buffer_load_dwordx4 v206, s[12:15], s83 offen lds
	s_mov_b32 m0, s51
	s_nop 0
	buffer_load_dwordx4 v206, s[12:15], s86 offen lds
	s_waitcnt vmcnt(8)
	s_waitcnt lgkmcnt(0)
	v_mfma_f32_16x16x32_bf16 v[62:65], v[134:137], v[166:169], v[62:65]
	s_barrier
	v_mfma_f32_16x16x32_bf16 v[62:65], v[138:141], v[170:173], v[62:65]
	v_mfma_f32_16x16x32_bf16 v[58:61], v[142:145], v[166:169], v[58:61]
	v_mfma_f32_16x16x32_bf16 v[58:61], v[146:149], v[170:173], v[58:61]
	v_mfma_f32_16x16x32_bf16 v[46:49], v[150:153], v[166:169], v[46:49]
	v_mfma_f32_16x16x32_bf16 v[46:49], v[154:157], v[170:173], v[46:49]
	v_mfma_f32_16x16x32_bf16 v[38:41], v[158:161], v[166:169], v[38:41]
	v_mfma_f32_16x16x32_bf16 v[38:41], v[162:165], v[170:173], v[38:41]
	v_mfma_f32_16x16x32_bf16 v[22:25], v[158:161], v[174:177], v[22:25]
	v_mfma_f32_16x16x32_bf16 v[22:25], v[162:165], v[178:181], v[22:25]
	v_mfma_f32_16x16x32_bf16 v[30:33], v[150:153], v[174:177], v[30:33]
	v_mfma_f32_16x16x32_bf16 v[30:33], v[154:157], v[178:181], v[30:33]
	v_mfma_f32_16x16x32_bf16 v[50:53], v[142:145], v[174:177], v[50:53]
	v_mfma_f32_16x16x32_bf16 v[50:53], v[146:149], v[178:181], v[50:53]
	v_mfma_f32_16x16x32_bf16 v[54:57], v[134:137], v[174:177], v[54:57]
	v_mfma_f32_16x16x32_bf16 v[54:57], v[138:141], v[178:181], v[54:57]
	v_mfma_f32_16x16x32_bf16 v[42:45], v[134:137], v[182:185], v[42:45]
	v_mfma_f32_16x16x32_bf16 v[42:45], v[138:141], v[186:189], v[42:45]
	v_mfma_f32_16x16x32_bf16 v[34:37], v[142:145], v[182:185], v[34:37]
	v_mfma_f32_16x16x32_bf16 v[34:37], v[146:149], v[186:189], v[34:37]
	v_mfma_f32_16x16x32_bf16 v[14:17], v[150:153], v[182:185], v[14:17]
	v_mfma_f32_16x16x32_bf16 v[14:17], v[154:157], v[186:189], v[14:17]
	v_mfma_f32_16x16x32_bf16 v[10:13], v[158:161], v[182:185], v[10:13]
	v_mfma_f32_16x16x32_bf16 v[10:13], v[162:165], v[186:189], v[10:13]
	v_mfma_f32_16x16x32_bf16 v[2:5], v[158:161], v[190:193], v[2:5]
	v_mfma_f32_16x16x32_bf16 v[2:5], v[162:165], v[194:197], v[2:5]
	v_mfma_f32_16x16x32_bf16 v[6:9], v[150:153], v[190:193], v[6:9]
	v_mfma_f32_16x16x32_bf16 v[6:9], v[154:157], v[194:197], v[6:9]
	v_mfma_f32_16x16x32_bf16 v[18:21], v[142:145], v[190:193], v[18:21]
	v_mfma_f32_16x16x32_bf16 v[18:21], v[146:149], v[194:197], v[18:21]
	v_mfma_f32_16x16x32_bf16 v[26:29], v[134:137], v[190:193], v[26:29]
	v_mfma_f32_16x16x32_bf16 v[26:29], v[138:141], v[194:197], v[26:29]
	s_barrier
	ds_read_b128 v[134:137], v211
	ds_read_b128 v[138:141], v211 offset:1024
	ds_read_b128 v[142:145], v211 offset:2048
	ds_read_b128 v[146:149], v211 offset:3072
	ds_read_b128 v[150:153], v212
	ds_read_b128 v[154:157], v212 offset:1024
	ds_read_b128 v[158:161], v212 offset:2048
	ds_read_b128 v[162:165], v212 offset:3072
	s_mov_b32 m0, s52
	s_add_i32 s86, s83, 0x2b0000
	ds_read_b128 v[166:169], v210 offset:32768
	ds_read_b128 v[170:173], v210 offset:33792
	ds_read_b128 v[174:177], v210 offset:34816
	ds_read_b128 v[178:181], v210 offset:35840
	ds_read_b128 v[182:185], v210 offset:36864
	ds_read_b128 v[186:189], v210 offset:37888
	ds_read_b128 v[190:193], v210 offset:38912
	ds_read_b128 v[194:197], v210 offset:39936
	buffer_load_dwordx4 v206, s[12:15], s86 offen lds
	s_add_i32 s86, s83, 0x408000
	s_mov_b32 m0, s53
	s_nop 0
	buffer_load_dwordx4 v206, s[12:15], s86 offen lds
	s_waitcnt vmcnt(8)
	s_waitcnt lgkmcnt(0)
	v_mfma_f32_16x16x32_bf16 v[126:129], v[134:137], v[166:169], v[126:129]
	s_barrier
	v_mfma_f32_16x16x32_bf16 v[126:129], v[138:141], v[170:173], v[126:129]
	v_mfma_f32_16x16x32_bf16 v[122:125], v[142:145], v[166:169], v[122:125]
	v_mfma_f32_16x16x32_bf16 v[122:125], v[146:149], v[170:173], v[122:125]
	v_mfma_f32_16x16x32_bf16 v[110:113], v[150:153], v[166:169], v[110:113]
	v_mfma_f32_16x16x32_bf16 v[110:113], v[154:157], v[170:173], v[110:113]
	v_mfma_f32_16x16x32_bf16 v[102:105], v[158:161], v[166:169], v[102:105]
	v_mfma_f32_16x16x32_bf16 v[102:105], v[162:165], v[170:173], v[102:105]
	v_mfma_f32_16x16x32_bf16 v[86:89], v[158:161], v[174:177], v[86:89]
	v_mfma_f32_16x16x32_bf16 v[86:89], v[162:165], v[178:181], v[86:89]
	v_mfma_f32_16x16x32_bf16 v[94:97], v[150:153], v[174:177], v[94:97]
	v_mfma_f32_16x16x32_bf16 v[94:97], v[154:157], v[178:181], v[94:97]
	v_mfma_f32_16x16x32_bf16 v[114:117], v[142:145], v[174:177], v[114:117]
	v_mfma_f32_16x16x32_bf16 v[114:117], v[146:149], v[178:181], v[114:117]
	v_mfma_f32_16x16x32_bf16 v[118:121], v[134:137], v[174:177], v[118:121]
	v_mfma_f32_16x16x32_bf16 v[118:121], v[138:141], v[178:181], v[118:121]
	v_mfma_f32_16x16x32_bf16 v[106:109], v[134:137], v[182:185], v[106:109]
	v_mfma_f32_16x16x32_bf16 v[106:109], v[138:141], v[186:189], v[106:109]
	v_mfma_f32_16x16x32_bf16 v[98:101], v[142:145], v[182:185], v[98:101]
	v_mfma_f32_16x16x32_bf16 v[98:101], v[146:149], v[186:189], v[98:101]
	v_mfma_f32_16x16x32_bf16 v[78:81], v[150:153], v[182:185], v[78:81]
	v_mfma_f32_16x16x32_bf16 v[78:81], v[154:157], v[186:189], v[78:81]
	v_mfma_f32_16x16x32_bf16 v[74:77], v[158:161], v[182:185], v[74:77]
	v_mfma_f32_16x16x32_bf16 v[74:77], v[162:165], v[186:189], v[74:77]
	v_mfma_f32_16x16x32_bf16 v[66:69], v[158:161], v[190:193], v[66:69]
	v_mfma_f32_16x16x32_bf16 v[66:69], v[162:165], v[194:197], v[66:69]
	v_mfma_f32_16x16x32_bf16 v[70:73], v[150:153], v[190:193], v[70:73]
	v_mfma_f32_16x16x32_bf16 v[70:73], v[154:157], v[194:197], v[70:73]
	v_mfma_f32_16x16x32_bf16 v[82:85], v[142:145], v[190:193], v[82:85]
	v_mfma_f32_16x16x32_bf16 v[82:85], v[146:149], v[194:197], v[82:85]
	v_mfma_f32_16x16x32_bf16 v[90:93], v[134:137], v[190:193], v[90:93]
	v_mfma_f32_16x16x32_bf16 v[90:93], v[138:141], v[194:197], v[90:93]
	s_barrier
	s_mov_b32 m0, s57
	s_or_b32 s86, s85, 0x80
	ds_read_b128 v[166:169], v210 offset:49152
	ds_read_b128 v[170:173], v210 offset:50176
	ds_read_b128 v[174:177], v210 offset:51200
	ds_read_b128 v[178:181], v210 offset:52224
	ds_read_b128 v[182:185], v210 offset:53248
	ds_read_b128 v[186:189], v210 offset:54272
	ds_read_b128 v[190:193], v210 offset:55296
	ds_read_b128 v[194:197], v210 offset:56320
	buffer_load_dwordx4 v207, s[16:19], s86 offen lds
	s_add_i32 s86, s85, 0x158080
	s_mov_b32 m0, s58
	s_add_i32 s83, s83, 0x158080
	buffer_load_dwordx4 v207, s[16:19], s86 offen lds
	s_add_i32 s86, s85, 0x2b0080
	s_mov_b32 m0, s61
	s_add_i32 s85, s85, 0x408080
	buffer_load_dwordx4 v207, s[16:19], s86 offen lds
	s_mov_b32 m0, s62
	s_nop 0
	buffer_load_dwordx4 v207, s[16:19], s85 offen lds
	s_mov_b32 m0, s59
	s_nop 0
	buffer_load_dwordx4 v206, s[12:15], s84 offen lds
	s_mov_b32 m0, s60
	s_nop 0
	buffer_load_dwordx4 v206, s[12:15], s83 offen lds
	s_waitcnt vmcnt(8)
	s_waitcnt lgkmcnt(0)
	v_mfma_f32_16x16x32_bf16 v[62:65], v[134:137], v[166:169], v[62:65]
	s_barrier
	v_mfma_f32_16x16x32_bf16 v[62:65], v[138:141], v[170:173], v[62:65]
	v_mfma_f32_16x16x32_bf16 v[58:61], v[142:145], v[166:169], v[58:61]
	v_mfma_f32_16x16x32_bf16 v[58:61], v[146:149], v[170:173], v[58:61]
	v_mfma_f32_16x16x32_bf16 v[46:49], v[150:153], v[166:169], v[46:49]
	v_mfma_f32_16x16x32_bf16 v[46:49], v[154:157], v[170:173], v[46:49]
	v_mfma_f32_16x16x32_bf16 v[38:41], v[158:161], v[166:169], v[38:41]
	v_mfma_f32_16x16x32_bf16 v[38:41], v[162:165], v[170:173], v[38:41]
	v_mfma_f32_16x16x32_bf16 v[22:25], v[158:161], v[174:177], v[22:25]
	v_mfma_f32_16x16x32_bf16 v[22:25], v[162:165], v[178:181], v[22:25]
	v_mfma_f32_16x16x32_bf16 v[30:33], v[150:153], v[174:177], v[30:33]
	v_mfma_f32_16x16x32_bf16 v[30:33], v[154:157], v[178:181], v[30:33]
	v_mfma_f32_16x16x32_bf16 v[50:53], v[142:145], v[174:177], v[50:53]
	v_mfma_f32_16x16x32_bf16 v[50:53], v[146:149], v[178:181], v[50:53]
	v_mfma_f32_16x16x32_bf16 v[54:57], v[134:137], v[174:177], v[54:57]
	v_mfma_f32_16x16x32_bf16 v[54:57], v[138:141], v[178:181], v[54:57]
	v_mfma_f32_16x16x32_bf16 v[42:45], v[134:137], v[182:185], v[42:45]
	v_mfma_f32_16x16x32_bf16 v[42:45], v[138:141], v[186:189], v[42:45]
	v_mfma_f32_16x16x32_bf16 v[34:37], v[142:145], v[182:185], v[34:37]
	v_mfma_f32_16x16x32_bf16 v[34:37], v[146:149], v[186:189], v[34:37]
	v_mfma_f32_16x16x32_bf16 v[14:17], v[150:153], v[182:185], v[14:17]
	v_mfma_f32_16x16x32_bf16 v[14:17], v[154:157], v[186:189], v[14:17]
	v_mfma_f32_16x16x32_bf16 v[10:13], v[158:161], v[182:185], v[10:13]
	v_mfma_f32_16x16x32_bf16 v[10:13], v[162:165], v[186:189], v[10:13]
	v_mfma_f32_16x16x32_bf16 v[2:5], v[158:161], v[190:193], v[2:5]
	v_mfma_f32_16x16x32_bf16 v[2:5], v[162:165], v[194:197], v[2:5]
	v_mfma_f32_16x16x32_bf16 v[6:9], v[150:153], v[190:193], v[6:9]
	v_mfma_f32_16x16x32_bf16 v[6:9], v[154:157], v[194:197], v[6:9]
	v_mfma_f32_16x16x32_bf16 v[18:21], v[142:145], v[190:193], v[18:21]
	v_mfma_f32_16x16x32_bf16 v[18:21], v[146:149], v[194:197], v[18:21]
	v_mfma_f32_16x16x32_bf16 v[26:29], v[134:137], v[190:193], v[26:29]
	v_mfma_f32_16x16x32_bf16 v[26:29], v[138:141], v[194:197], v[26:29]
	s_barrier
	s_add_i32 s82, s82, 2
	s_addk_i32 s80, 0x100
	s_addk_i32 s81, 0x100
	s_cmp_ge_i32 s82, s3
	s_cbranch_scc0 .LBB0_1519
	v_pk_mul_f32 v[182:183], v[128:129], 0.5 op_sel_hi:[1,0]
	v_pk_mul_f32 v[184:185], v[126:127], 0.5 op_sel_hi:[1,0]
	v_pk_mul_f32 v[186:187], v[124:125], 0.5 op_sel_hi:[1,0]
	v_pk_mul_f32 v[188:189], v[122:123], 0.5 op_sel_hi:[1,0]
	v_pk_mul_f32 v[196:197], v[112:113], 0.5 op_sel_hi:[1,0]
	v_pk_mul_f32 v[194:195], v[110:111], 0.5 op_sel_hi:[1,0]
	v_pk_mul_f32 v[192:193], v[104:105], 0.5 op_sel_hi:[1,0]
	v_pk_mul_f32 v[190:191], v[102:103], 0.5 op_sel_hi:[1,0]
	v_pk_mul_f32 v[180:181], v[120:121], 0.5 op_sel_hi:[1,0]
	v_pk_mul_f32 v[178:179], v[118:119], 0.5 op_sel_hi:[1,0]
	v_pk_mul_f32 v[176:177], v[116:117], 0.5 op_sel_hi:[1,0]
	v_pk_mul_f32 v[174:175], v[114:115], 0.5 op_sel_hi:[1,0]
	v_pk_mul_f32 v[170:171], v[96:97], 0.5 op_sel_hi:[1,0]
	v_pk_mul_f32 v[168:169], v[94:95], 0.5 op_sel_hi:[1,0]
	v_pk_mul_f32 v[166:167], v[88:89], 0.5 op_sel_hi:[1,0]
	v_pk_mul_f32 v[164:165], v[86:87], 0.5 op_sel_hi:[1,0]
	v_pk_mul_f32 v[162:163], v[108:109], 0.5 op_sel_hi:[1,0]
	v_pk_mul_f32 v[160:161], v[106:107], 0.5 op_sel_hi:[1,0]
	v_pk_mul_f32 v[158:159], v[100:101], 0.5 op_sel_hi:[1,0]
	v_pk_mul_f32 v[156:157], v[98:99], 0.5 op_sel_hi:[1,0]
	v_pk_mul_f32 v[154:155], v[80:81], 0.5 op_sel_hi:[1,0]
	v_pk_mul_f32 v[152:153], v[78:79], 0.5 op_sel_hi:[1,0]
	v_pk_mul_f32 v[150:151], v[76:77], 0.5 op_sel_hi:[1,0]
	v_pk_mul_f32 v[148:149], v[74:75], 0.5 op_sel_hi:[1,0]
	v_pk_mul_f32 v[144:145], v[92:93], 0.5 op_sel_hi:[1,0]
	v_pk_mul_f32 v[142:143], v[90:91], 0.5 op_sel_hi:[1,0]
	v_pk_mul_f32 v[140:141], v[84:85], 0.5 op_sel_hi:[1,0]
	v_pk_mul_f32 v[138:139], v[82:83], 0.5 op_sel_hi:[1,0]
	v_pk_mul_f32 v[136:137], v[72:73], 0.5 op_sel_hi:[1,0]
	v_pk_mul_f32 v[134:135], v[70:71], 0.5 op_sel_hi:[1,0]
	v_pk_mul_f32 v[128:129], v[68:69], 0.5 op_sel_hi:[1,0]
	v_pk_mul_f32 v[126:127], v[66:67], 0.5 op_sel_hi:[1,0]
	v_pk_mul_f32 v[122:123], v[64:65], 0.5 op_sel_hi:[1,0]
	v_pk_mul_f32 v[120:121], v[62:63], 0.5 op_sel_hi:[1,0]
	v_pk_mul_f32 v[118:119], v[60:61], 0.5 op_sel_hi:[1,0]
	v_pk_mul_f32 v[116:117], v[58:59], 0.5 op_sel_hi:[1,0]
	v_pk_mul_f32 v[112:113], v[48:49], 0.5 op_sel_hi:[1,0]
	v_pk_mul_f32 v[110:111], v[46:47], 0.5 op_sel_hi:[1,0]
	v_pk_mul_f32 v[108:109], v[40:41], 0.5 op_sel_hi:[1,0]
	v_pk_mul_f32 v[106:107], v[38:39], 0.5 op_sel_hi:[1,0]
	v_pk_mul_f32 v[104:105], v[56:57], 0.5 op_sel_hi:[1,0]
	v_pk_mul_f32 v[102:103], v[54:55], 0.5 op_sel_hi:[1,0]
	v_pk_mul_f32 v[100:101], v[52:53], 0.5 op_sel_hi:[1,0]
	v_pk_mul_f32 v[98:99], v[50:51], 0.5 op_sel_hi:[1,0]
	v_pk_mul_f32 v[96:97], v[32:33], 0.5 op_sel_hi:[1,0]
	v_pk_mul_f32 v[94:95], v[30:31], 0.5 op_sel_hi:[1,0]
	v_pk_mul_f32 v[92:93], v[24:25], 0.5 op_sel_hi:[1,0]
	v_pk_mul_f32 v[90:91], v[22:23], 0.5 op_sel_hi:[1,0]
	v_pk_mul_f32 v[88:89], v[44:45], 0.5 op_sel_hi:[1,0]
	v_pk_mul_f32 v[86:87], v[42:43], 0.5 op_sel_hi:[1,0]
	v_pk_mul_f32 v[84:85], v[36:37], 0.5 op_sel_hi:[1,0]
	v_pk_mul_f32 v[82:83], v[34:35], 0.5 op_sel_hi:[1,0]
	v_pk_mul_f32 v[80:81], v[16:17], 0.5 op_sel_hi:[1,0]
	v_pk_mul_f32 v[78:79], v[14:15], 0.5 op_sel_hi:[1,0]
	v_pk_mul_f32 v[76:77], v[12:13], 0.5 op_sel_hi:[1,0]
	v_pk_mul_f32 v[74:75], v[10:11], 0.5 op_sel_hi:[1,0]
	v_pk_mul_f32 v[72:73], v[28:29], 0.5 op_sel_hi:[1,0]
	v_pk_mul_f32 v[70:71], v[26:27], 0.5 op_sel_hi:[1,0]
	v_pk_mul_f32 v[68:69], v[20:21], 0.5 op_sel_hi:[1,0]
	v_pk_mul_f32 v[66:67], v[18:19], 0.5 op_sel_hi:[1,0]
	v_pk_mul_f32 v[64:65], v[8:9], 0.5 op_sel_hi:[1,0]
	v_pk_mul_f32 v[62:63], v[6:7], 0.5 op_sel_hi:[1,0]
	v_pk_mul_f32 v[60:61], v[4:5], 0.5 op_sel_hi:[1,0]
	v_pk_mul_f32 v[58:59], v[2:3], 0.5 op_sel_hi:[1,0]
	s_and_b64 vcc, exec, s[40:41]
	s_cbranch_vccz .LBB0_1522
